# phases whose only stores are 16-byte stores (w_in GEMM, xq GEMM, up GEMM, weight conversion) now use agent-scope write-through stores, and the grid barrier after them skips the L2 write-back
# speedup vs baseline: 1.0036x; 1.0036x over previous
; __device__ __forceinline__ unsigned pk2(float lo, float hi) { const hf32x2 v = {lo, hi}; return __builtin_bit_cast(unsigned, __builtin_convertvector(v, hbf16x2)); }
; __device__ __forceinline__ void tconv_tile_w(const float* src, int N, int kb, int nb, bf16_t* dst, int ldd, float* tile, const float* kscale = nullptr) {
;     ...
;     for (int p = 0; p < 8; ++p) { const int idx = tid + 512 * p, r = idx >> 6, c4 = idx & 63;
;         float* t = tile + r * 257 + c4 * 4; t[0] = v[p][0]; t[1] = v[p][1]; t[2] = v[p][2]; t[3] = v[p][3]; }
;     __syncthreads();
; #pragma unroll
;     for (int q = 0; q < 4; ++q) { const int id = tid + 512 * q, n = id >> 3, k8 = id & 7;
;         const float* s = tile + (k8 * 8) * 257 + n;
;         u32x4 o; o.x = pk2(s[0], s[257]); o.y = pk2(s[2 * 257], s[3 * 257]); o.z = pk2(s[4 * 257], s[5 * 257]); o.w = pk2(s[6 * 257], s[7 * 257]);
;         *(u32x4*)(dst + (size_t)(nb * 256 + n) * ldd + kb * 64 + k8 * 8) = o; }
;     __syncthreads();
.Ltc_pnosc_77:
	v_cvt_pk_bf16_f32 v64, v0, v4
	v_cvt_pk_bf16_f32 v65, v1, v5
	v_cvt_pk_bf16_f32 v66, v2, v6
	v_cvt_pk_bf16_f32 v67, v3, v7
	v_cvt_pk_bf16_f32 v68, v8, v12
	v_cvt_pk_bf16_f32 v69, v9, v13
	v_cvt_pk_bf16_f32 v70, v10, v14
	v_cvt_pk_bf16_f32 v71, v11, v15
	v_cvt_pk_bf16_f32 v72, v16, v20
	v_cvt_pk_bf16_f32 v73, v17, v21
	v_cvt_pk_bf16_f32 v74, v18, v22
	v_cvt_pk_bf16_f32 v75, v19, v23
	v_cvt_pk_bf16_f32 v76, v24, v28
	v_cvt_pk_bf16_f32 v77, v25, v29
	v_cvt_pk_bf16_f32 v78, v26, v30
	v_cvt_pk_bf16_f32 v79, v27, v31
	ds_write2_b32 v114, v64, v65 offset1:1
	ds_write2_b32 v114, v66, v67 offset0:2 offset1:3
	ds_write2_b32 v115, v68, v69 offset1:1
	ds_write2_b32 v115, v70, v71 offset0:2 offset1:3
	ds_write2_b32 v116, v72, v73 offset1:1
	ds_write2_b32 v116, v74, v75 offset0:2 offset1:3
	ds_write2_b32 v117, v76, v77 offset1:1
	ds_write2_b32 v117, v78, v79 offset0:2 offset1:3
	v_add_u32_e32 v113, 0, v108
	v_mad_u32_u24 v109, v113, s52, v107
	v_add_u32_e32 v113, 64, v108
	v_mad_u32_u24 v110, v113, s52, v107
	v_add_u32_e32 v113, 128, v108
	v_mad_u32_u24 v111, v113, s52, v107
	v_add_u32_e32 v113, 192, v108
	v_mad_u32_u24 v112, v113, s52, v107
	s_waitcnt lgkmcnt(0)
	s_barrier
	ds_read_b32 v80, v106 offset:0
	ds_read_b32 v81, v106 offset:1028
	ds_read_b32 v82, v106 offset:2056
	ds_read_b32 v83, v106 offset:3084
	ds_read_b32 v84, v106 offset:256
	ds_read_b32 v85, v106 offset:1284
	ds_read_b32 v86, v106 offset:2312
	ds_read_b32 v87, v106 offset:3340
	ds_read_b32 v88, v106 offset:512
	ds_read_b32 v89, v106 offset:1540
	ds_read_b32 v90, v106 offset:2568
	ds_read_b32 v91, v106 offset:3596
	ds_read_b32 v92, v106 offset:768
	ds_read_b32 v93, v106 offset:1796
	ds_read_b32 v94, v106 offset:2824
	ds_read_b32 v95, v106 offset:3852
	s_waitcnt lgkmcnt(12)
	global_store_dwordx4 v109, v[80:83], s[50:51] sc1
	s_waitcnt lgkmcnt(8)
	global_store_dwordx4 v110, v[84:87], s[50:51] sc1
	s_waitcnt lgkmcnt(4)
	global_store_dwordx4 v111, v[88:91], s[50:51] sc1
	s_waitcnt lgkmcnt(0)
	global_store_dwordx4 v112, v[92:95], s[50:51] sc1
	s_cmp_eq_u32 s43, 0
	s_cbranch_scc1 .Ltc_exit_1
	s_waitcnt lgkmcnt(0)
	s_mov_b64 s[50:51], s[46:47]
	s_mov_b32 s52, s48
	s_mov_b32 s59, s61
	s_mov_b64 s[68:69], s[76:77]
	s_mov_b64 s[70:71], s[78:79]
	s_mov_b64 s[72:73], s[80:81]
	s_mov_b64 s[74:75], s[82:83]
	s_add_u32 s29, s29, s63
	s_mov_b32 s62, 0

; __device__ __forceinline__ unsigned pk2(float lo, float hi) { const hf32x2 v = {lo, hi}; return __builtin_bit_cast(unsigned, __builtin_convertvector(v, hbf16x2)); }
; __device__ __forceinline__ void tconv_tile_w(const float* src, int N, int kb, int nb, bf16_t* dst, int ldd, float* tile, const float* kscale = nullptr) {
;     ...
;     for (int p = 0; p < 8; ++p) { const int idx = tid + 512 * p, r = idx >> 6, c4 = idx & 63;
;         float* t = tile + r * 257 + c4 * 4; t[0] = v[p][0]; t[1] = v[p][1]; t[2] = v[p][2]; t[3] = v[p][3]; }
;     __syncthreads();
; #pragma unroll
;     for (int q = 0; q < 4; ++q) { const int id = tid + 512 * q, n = id >> 3, k8 = id & 7;
;         const float* s = tile + (k8 * 8) * 257 + n;
;         u32x4 o; o.x = pk2(s[0], s[257]); o.y = pk2(s[2 * 257], s[3 * 257]); o.z = pk2(s[4 * 257], s[5 * 257]); o.w = pk2(s[6 * 257], s[7 * 257]);
;         *(u32x4*)(dst + (size_t)(nb * 256 + n) * ldd + kb * 64 + k8 * 8) = o; }
;     __syncthreads();
.Ltc_pnosc_117:
	v_cvt_pk_bf16_f32 v64, v32, v36
	v_cvt_pk_bf16_f32 v65, v33, v37
	v_cvt_pk_bf16_f32 v66, v34, v38
	v_cvt_pk_bf16_f32 v67, v35, v39
	v_cvt_pk_bf16_f32 v68, v40, v44
	v_cvt_pk_bf16_f32 v69, v41, v45
	v_cvt_pk_bf16_f32 v70, v42, v46
	v_cvt_pk_bf16_f32 v71, v43, v47
	v_cvt_pk_bf16_f32 v72, v48, v52
	v_cvt_pk_bf16_f32 v73, v49, v53
	v_cvt_pk_bf16_f32 v74, v50, v54
	v_cvt_pk_bf16_f32 v75, v51, v55
	v_cvt_pk_bf16_f32 v76, v56, v60
	v_cvt_pk_bf16_f32 v77, v57, v61
	v_cvt_pk_bf16_f32 v78, v58, v62
	v_cvt_pk_bf16_f32 v79, v59, v63
	ds_write2_b32 v118, v64, v65 offset1:1
	ds_write2_b32 v118, v66, v67 offset0:2 offset1:3
	ds_write2_b32 v119, v68, v69 offset1:1
	ds_write2_b32 v119, v70, v71 offset0:2 offset1:3
	ds_write2_b32 v120, v72, v73 offset1:1
	ds_write2_b32 v120, v74, v75 offset0:2 offset1:3
	ds_write2_b32 v121, v76, v77 offset1:1
	ds_write2_b32 v121, v78, v79 offset0:2 offset1:3
	v_add_u32_e32 v113, 0, v108
	v_mad_u32_u24 v109, v113, s52, v107
	v_add_u32_e32 v113, 64, v108
	v_mad_u32_u24 v110, v113, s52, v107
	v_add_u32_e32 v113, 128, v108
	v_mad_u32_u24 v111, v113, s52, v107
	v_add_u32_e32 v113, 192, v108
	v_mad_u32_u24 v112, v113, s52, v107
	s_waitcnt lgkmcnt(0)
	s_barrier
	ds_read_b32 v80, v106 offset:33024
	ds_read_b32 v81, v106 offset:34052
	ds_read_b32 v82, v106 offset:35080
	ds_read_b32 v83, v106 offset:36108
	ds_read_b32 v84, v106 offset:33280
	ds_read_b32 v85, v106 offset:34308
	ds_read_b32 v86, v106 offset:35336
	ds_read_b32 v87, v106 offset:36364
	ds_read_b32 v88, v106 offset:33536
	ds_read_b32 v89, v106 offset:34564
	ds_read_b32 v90, v106 offset:35592
	ds_read_b32 v91, v106 offset:36620
	ds_read_b32 v92, v106 offset:33792
	ds_read_b32 v93, v106 offset:34820
	ds_read_b32 v94, v106 offset:35848
	ds_read_b32 v95, v106 offset:36876
	s_waitcnt lgkmcnt(12)
	global_store_dwordx4 v109, v[80:83], s[50:51] sc1
	s_waitcnt lgkmcnt(8)
	global_store_dwordx4 v110, v[84:87], s[50:51] sc1
	s_waitcnt lgkmcnt(4)
	global_store_dwordx4 v111, v[88:91], s[50:51] sc1
	s_waitcnt lgkmcnt(0)
	global_store_dwordx4 v112, v[92:95], s[50:51] sc1
	s_cmp_eq_u32 s43, 0
	s_cbranch_scc1 .Ltc_exit_1
	s_waitcnt lgkmcnt(0)
	s_mov_b64 s[50:51], s[46:47]
	s_mov_b32 s52, s48
	s_mov_b32 s59, s61
	s_mov_b64 s[68:69], s[76:77]
	s_mov_b64 s[70:71], s[78:79]
	s_mov_b64 s[72:73], s[80:81]
	s_mov_b64 s[74:75], s[82:83]
	s_branch .Ltc_loop_37

; __device__ __forceinline__ unsigned cvt_pk_bf16(float lo, float hi) { unsigned r; asm volatile("v_cvt_pk_bf16_f32 %0, %1, %2" : "=v"(r) : "v"(lo), "v"(hi)); return r; }
;     __device__ __forceinline__ void operator()(const f32x4 (&acc)[2][2][4][2], const Unit& u, int wr, int wc, int fr, int fq) const {
;     ...
;             for (int m = 0; m < 4; ++m) { const int row = row0 + ai * HALF + m * 16; const float rs = rsv[ai][m];
; #pragma unroll
;                 for (int bj = 0; bj < 2; ++bj) { const f32x4 v0 = acc[ai][bj][m][0] * rs, v1 = acc[ai][bj][m][1] * rs;
;                     u32x4 o; o.x = cvt_pk_bf16(v0[0], v0[1]); o.y = cvt_pk_bf16(v0[2], v0[3]); o.z = cvt_pk_bf16(v1[0], v1[1]); o.w = cvt_pk_bf16(v1[2], v1[3]);
;                     bf16_t* dst;
;                     if (u.pn < 4) { const int colg = u.pn * BM + bj * HALF + wc * 32 + 8 * fq; dst = P + (size_t)(colg >> 9) * ((size_t)T * 512) + (size_t)row * 512 + (colg & 511); }
;                     else if (u.pn < 8) { const int colc = (u.pn - 4) * BM + bj * HALF + wc * 32 + 8 * fq; dst = P + PJ_UC + (size_t)row * 1024 + colc; }
;                     else { const int which = (u.pn - 8) >> 1, hd = ((u.pn - 8) & 1) * 4 + 2 * bj + (wc >> 1), dim = 32 * (wc & 1) + 8 * fq, bb = row >> 11, ll = row & 2047;
;                         dst = P + PJ_QKV + ((size_t)(((which * 4 + bb) * 8 + hd) * SEQ + ll)) * 64 + dim; }
;                     *(u32x4*)dst = o; } }
.LBB0_162:
	v_mov_b32_e32 v163, v162
	global_store_dwordx4 v[128:129], v[122:125], off sc1
	v_cndmask_b32_e64 v0, 0, 1, s[2:3]
	v_cmp_ne_u32_e64 s[40:41], 1, v0
	v_mov_b32_e32 v122, v162
	v_mov_b32_e32 v123, v162
	v_pk_mul_f32 v[120:121], v[120:121], v[122:123]
	v_pk_mul_f32 v[122:123], v[116:117], v[122:123]
	v_pk_mul_f32 v[116:117], v[114:115], v[162:163]
	s_andn2_b64 vcc, exec, s[2:3]
	s_mov_b64 s[2:3], -1
	v_pk_mul_f32 v[118:119], v[118:119], v[162:163]
	s_nop 0
	v_cvt_pk_bf16_f32 v114, v118, v119
	v_cvt_pk_bf16_f32 v115, v120, v121
	v_cvt_pk_bf16_f32 v116, v116, v117
	v_cvt_pk_bf16_f32 v117, v122, v123
	s_cbranch_vccnz .LBB0_168
	s_cmp_lt_u32 s34, 8
	s_cbranch_scc1 .LBB0_165
	s_lshl_b32 s2, s34, 2
	s_lshl_b32 s3, s34, 1
	s_and_b32 s2, s2, 4
	s_and_b32 s3, s3, 0x3fffc
	s_or_b32 s2, s2, s61
	s_add_i32 s3, s20, s3
	s_lshl_b32 s3, s3, 14
	s_lshl_b32 s2, s2, 11
	s_or_b32 s2, s2, s3
	v_or_b32_e32 v0, s2, v194
	v_or_b32_e32 v118, 0x1000, v0
	v_ashrrev_i32_e32 v119, 31, v118
	v_lshlrev_b64 v[118:119], 7, v[118:119]
	v_lshl_add_u64 v[120:121], v[140:141], 0, v[118:119]
	s_mov_b64 s[2:3], 0

; __device__ __forceinline__ unsigned cvt_pk_bf16(float lo, float hi) { unsigned r; asm volatile("v_cvt_pk_bf16_f32 %0, %1, %2" : "=v"(r) : "v"(lo), "v"(hi)); return r; }
;     __device__ __forceinline__ void operator()(const f32x4 (&acc)[2][2][4][2], const Unit& u, int wr, int wc, int fr, int fq) const {
;     ...
;                 for (int m = 0; m < 4; ++m) { float t = ((p0[ai][m][0] + p0[ai][m][1]) + (p0[ai][m][2] + p0[ai][m][3])) + ((p1[ai][m][0] + p1[ai][m][1]) + (p1[ai][m][2] + p1[ai][m][3]));
;                     t += __shfl_xor(t, 16); t += __shfl_xor(t, 32);
;                     rsv[ai][m] = 1.0f / sqrtf(t * (1.0f / D) + EPS); }
;         }
; #pragma unroll
;         for (int ai = 0; ai < 2; ++ai)
; #pragma unroll
;             for (int m = 0; m < 4; ++m) { const int row = row0 + ai * HALF + m * 16; const float rs = rsv[ai][m];
; #pragma unroll
;                 for (int bj = 0; bj < 2; ++bj) { const f32x4 v0 = acc[ai][bj][m][0] * rs, v1 = acc[ai][bj][m][1] * rs;
;                     u32x4 o; o.x = cvt_pk_bf16(v0[0], v0[1]); o.y = cvt_pk_bf16(v0[2], v0[3]); o.z = cvt_pk_bf16(v1[0], v1[1]); o.w = cvt_pk_bf16(v1[2], v1[3]);
;                     bf16_t* dst;
;                     if (u.pn < 4) { const int colg = u.pn * BM + bj * HALF + wc * 32 + 8 * fq; dst = P + (size_t)(colg >> 9) * ((size_t)T * 512) + (size_t)row * 512 + (colg & 511); }
;                     else if (u.pn < 8) { const int colc = (u.pn - 4) * BM + bj * HALF + wc * 32 + 8 * fq; dst = P + PJ_UC + (size_t)row * 1024 + colc; }
;                     else { const int which = (u.pn - 8) >> 1, hd = ((u.pn - 8) & 1) * 4 + 2 * bj + (wc >> 1), dim = 32 * (wc & 1) + 8 * fq, bb = row >> 11, ll = row & 2047;
;                         dst = P + PJ_QKV + ((size_t)(((which * 4 + bb) * 8 + hd) * SEQ + ll)) * 64 + dim; }
;                     *(u32x4*)dst = o; } }
.LBB0_170:
	s_waitcnt lgkmcnt(6)
	v_add_f32_e32 v0, v192, v193
	v_fmamk_f32 v0, v0, 0x3a000000, v223
	v_mul_f32_e32 v118, 0x4f800000, v0
	v_cmp_gt_f32_e32 vcc, s11, v0
	global_store_dwordx4 v[120:121], v[114:117], off sc1
	s_nop 0
	v_cndmask_b32_e32 v0, v0, v118, vcc
	v_sqrt_f32_e32 v118, v0
	v_and_b32_e32 v116, 0x7df, v158
	v_lshlrev_b64 v[114:115], 11, v[158:159]
	v_add_u32_e32 v119, -1, v118
	v_fma_f32 v123, -v119, v118, v0
	v_add_u32_e32 v122, 1, v118
	v_cmp_ge_f32_e64 s[42:43], 0, v123
	s_nop 1
	v_cndmask_b32_e64 v119, v118, v119, s[42:43]
	v_fma_f32 v118, -v122, v118, v0
	v_cmp_lt_f32_e64 s[42:43], 0, v118
	s_nop 1
	v_cndmask_b32_e64 v118, v119, v122, s[42:43]
	v_mul_f32_e32 v119, 0x37800000, v118
	v_cndmask_b32_e32 v118, v118, v119, vcc
	v_cmp_class_f32_e32 vcc, v0, v224
	s_nop 1
	v_cndmask_b32_e32 v0, v118, v0, vcc
	v_div_scale_f32 v118, s[2:3], v0, v0, 1.0
	v_rcp_f32_e32 v119, v118
	s_mov_b64 s[2:3], -1
	v_fma_f32 v122, -v118, v119, 1.0
	v_fmac_f32_e32 v119, v122, v119
	v_div_scale_f32 v122, vcc, 1.0, v0, 1.0
	v_mul_f32_e32 v123, v122, v119
	v_fma_f32 v124, -v118, v123, v122
	v_fmac_f32_e32 v123, v124, v119
	v_fma_f32 v118, -v118, v123, v122
	v_div_fmas_f32 v118, v118, v119, v123
	v_div_fixup_f32 v118, v118, v0, 1.0
	v_pk_mul_f32 v[112:113], v[112:113], v[118:119] op_sel_hi:[1,0]
	v_pk_mul_f32 v[120:121], v[108:109], v[118:119] op_sel_hi:[1,0]
	v_pk_mul_f32 v[108:109], v[106:107], v[118:119] op_sel_hi:[1,0]
	s_and_b64 vcc, exec, s[40:41]
	v_pk_mul_f32 v[110:111], v[110:111], v[118:119] op_sel_hi:[1,0]
	s_nop 0
	v_cvt_pk_bf16_f32 v106, v110, v111
	v_cvt_pk_bf16_f32 v107, v112, v113
	v_cvt_pk_bf16_f32 v108, v108, v109
	v_cvt_pk_bf16_f32 v109, v120, v121
	s_cbranch_vccnz .LBB0_176
	s_cmp_lt_u32 s34, 8
	s_cbranch_scc1 .LBB0_173
	s_lshl_b32 s2, s34, 2
	s_lshl_b32 s3, s34, 1
	s_and_b32 s2, s2, 4
	s_and_b32 s3, s3, 0x3fffc
	s_or_b32 s2, s2, s61
	s_add_i32 s3, s20, s3
	s_lshl_b32 s3, s3, 14
	s_lshl_b32 s2, s2, 11
	s_or_b32 s2, s3, s2
	v_or_b32_e32 v110, s2, v116
	v_ashrrev_i32_e32 v111, 31, v110
	v_lshlrev_b64 v[110:111], 7, v[110:111]
	v_lshl_add_u64 v[112:113], v[140:141], 0, v[110:111]
	s_mov_b64 s[2:3], 0

; __device__ __forceinline__ unsigned cvt_pk_bf16(float lo, float hi) { unsigned r; asm volatile("v_cvt_pk_bf16_f32 %0, %1, %2" : "=v"(r) : "v"(lo), "v"(hi)); return r; }
;     __device__ __forceinline__ void operator()(const f32x4 (&acc)[2][2][4][2], const Unit& u, int wr, int wc, int fr, int fq) const {
;     ...
;             for (int m = 0; m < 4; ++m) { const int row = row0 + ai * HALF + m * 16; const float rs = rsv[ai][m];
; #pragma unroll
;                 for (int bj = 0; bj < 2; ++bj) { const f32x4 v0 = acc[ai][bj][m][0] * rs, v1 = acc[ai][bj][m][1] * rs;
;                     u32x4 o; o.x = cvt_pk_bf16(v0[0], v0[1]); o.y = cvt_pk_bf16(v0[2], v0[3]); o.z = cvt_pk_bf16(v1[0], v1[1]); o.w = cvt_pk_bf16(v1[2], v1[3]);
;                     bf16_t* dst;
;                     if (u.pn < 4) { const int colg = u.pn * BM + bj * HALF + wc * 32 + 8 * fq; dst = P + (size_t)(colg >> 9) * ((size_t)T * 512) + (size_t)row * 512 + (colg & 511); }
;                     else if (u.pn < 8) { const int colc = (u.pn - 4) * BM + bj * HALF + wc * 32 + 8 * fq; dst = P + PJ_UC + (size_t)row * 1024 + colc; }
;                     else { const int which = (u.pn - 8) >> 1, hd = ((u.pn - 8) & 1) * 4 + 2 * bj + (wc >> 1), dim = 32 * (wc & 1) + 8 * fq, bb = row >> 11, ll = row & 2047;
;                         dst = P + PJ_QKV + ((size_t)(((which * 4 + bb) * 8 + hd) * SEQ + ll)) * 64 + dim; }
;                     *(u32x4*)dst = o; } }
.LBB0_178:
	v_mov_b32_e32 v119, v118
	global_store_dwordx4 v[112:113], v[106:109], off sc1
	s_and_b64 vcc, exec, s[40:41]
	s_mov_b64 s[2:3], -1
	v_mov_b32_e32 v106, v118
	v_mov_b32_e32 v107, v118
	v_pk_mul_f32 v[104:105], v[104:105], v[106:107]
	v_pk_mul_f32 v[106:107], v[100:101], v[106:107]
	v_pk_mul_f32 v[100:101], v[98:99], v[118:119]
	v_pk_mul_f32 v[102:103], v[102:103], v[118:119]
	s_nop 0
	v_cvt_pk_bf16_f32 v98, v102, v103
	v_cvt_pk_bf16_f32 v99, v104, v105
	v_cvt_pk_bf16_f32 v100, v100, v101
	v_cvt_pk_bf16_f32 v101, v106, v107
	s_cbranch_vccnz .LBB0_184
	s_cmp_lt_u32 s34, 8
	s_cbranch_scc1 .LBB0_181
	s_lshl_b32 s2, s34, 2
	s_lshl_b32 s3, s34, 1
	s_and_b32 s2, s2, 4
	s_and_b32 s3, s3, 0x3fffc
	s_or_b32 s2, s2, s61
	s_add_i32 s3, s20, s3
	s_lshl_b32 s3, s3, 14
	s_lshl_b32 s2, s2, 11
	s_or_b32 s2, s2, s3
	v_or_b32_e32 v0, s2, v116
	v_or_b32_e32 v102, 0x1000, v0
	v_ashrrev_i32_e32 v103, 31, v102
	v_lshlrev_b64 v[102:103], 7, v[102:103]
	v_lshl_add_u64 v[104:105], v[140:141], 0, v[102:103]
	s_mov_b64 s[2:3], 0

; __device__ __forceinline__ unsigned cvt_pk_bf16(float lo, float hi) { unsigned r; asm volatile("v_cvt_pk_bf16_f32 %0, %1, %2" : "=v"(r) : "v"(lo), "v"(hi)); return r; }
;     __device__ __forceinline__ void operator()(const f32x4 (&acc)[2][2][4][2], const Unit& u, int wr, int wc, int fr, int fq) const {
;     ...
;                 for (int m = 0; m < 4; ++m) { float t = ((p0[ai][m][0] + p0[ai][m][1]) + (p0[ai][m][2] + p0[ai][m][3])) + ((p1[ai][m][0] + p1[ai][m][1]) + (p1[ai][m][2] + p1[ai][m][3]));
;                     t += __shfl_xor(t, 16); t += __shfl_xor(t, 32);
;                     rsv[ai][m] = 1.0f / sqrtf(t * (1.0f / D) + EPS); }
;         }
; #pragma unroll
;         for (int ai = 0; ai < 2; ++ai)
; #pragma unroll
;             for (int m = 0; m < 4; ++m) { const int row = row0 + ai * HALF + m * 16; const float rs = rsv[ai][m];
; #pragma unroll
;                 for (int bj = 0; bj < 2; ++bj) { const f32x4 v0 = acc[ai][bj][m][0] * rs, v1 = acc[ai][bj][m][1] * rs;
;                     u32x4 o; o.x = cvt_pk_bf16(v0[0], v0[1]); o.y = cvt_pk_bf16(v0[2], v0[3]); o.z = cvt_pk_bf16(v1[0], v1[1]); o.w = cvt_pk_bf16(v1[2], v1[3]);
;                     bf16_t* dst;
;                     if (u.pn < 4) { const int colg = u.pn * BM + bj * HALF + wc * 32 + 8 * fq; dst = P + (size_t)(colg >> 9) * ((size_t)T * 512) + (size_t)row * 512 + (colg & 511); }
;                     else if (u.pn < 8) { const int colc = (u.pn - 4) * BM + bj * HALF + wc * 32 + 8 * fq; dst = P + PJ_UC + (size_t)row * 1024 + colc; }
;                     else { const int which = (u.pn - 8) >> 1, hd = ((u.pn - 8) & 1) * 4 + 2 * bj + (wc >> 1), dim = 32 * (wc & 1) + 8 * fq, bb = row >> 11, ll = row & 2047;
;                         dst = P + PJ_QKV + ((size_t)(((which * 4 + bb) * 8 + hd) * SEQ + ll)) * 64 + dim; }
;                     *(u32x4*)dst = o; } }
.LBB0_186:
	s_waitcnt lgkmcnt(5)
	v_add_f32_e32 v0, v190, v191
	v_fmamk_f32 v0, v0, 0x3a000000, v223
	v_mul_f32_e32 v102, 0x4f800000, v0
	v_cmp_gt_f32_e32 vcc, s11, v0
	global_store_dwordx4 v[104:105], v[98:101], off sc1
	s_nop 0
	v_cndmask_b32_e32 v0, v0, v102, vcc
	v_sqrt_f32_e32 v102, v0
	v_and_b32_e32 v100, 0x7ef, v156
	v_lshlrev_b64 v[98:99], 11, v[156:157]
	v_add_u32_e32 v103, -1, v102
	v_fma_f32 v107, -v103, v102, v0
	v_add_u32_e32 v106, 1, v102
	v_cmp_ge_f32_e64 s[42:43], 0, v107
	s_nop 1
	v_cndmask_b32_e64 v103, v102, v103, s[42:43]
	v_fma_f32 v102, -v106, v102, v0
	v_cmp_lt_f32_e64 s[42:43], 0, v102
	s_nop 1
	v_cndmask_b32_e64 v102, v103, v106, s[42:43]
	v_mul_f32_e32 v103, 0x37800000, v102
	v_cndmask_b32_e32 v102, v102, v103, vcc
	v_cmp_class_f32_e32 vcc, v0, v224
	s_nop 1
	v_cndmask_b32_e32 v0, v102, v0, vcc
	v_div_scale_f32 v102, s[2:3], v0, v0, 1.0
	v_rcp_f32_e32 v103, v102
	s_mov_b64 s[2:3], -1
	v_fma_f32 v106, -v102, v103, 1.0
	v_fmac_f32_e32 v103, v106, v103
	v_div_scale_f32 v106, vcc, 1.0, v0, 1.0
	v_mul_f32_e32 v107, v106, v103
	v_fma_f32 v108, -v102, v107, v106
	v_fmac_f32_e32 v107, v108, v103
	v_fma_f32 v102, -v102, v107, v106
	v_div_fmas_f32 v102, v102, v103, v107
	v_div_fixup_f32 v102, v102, v0, 1.0
	v_pk_mul_f32 v[96:97], v[96:97], v[102:103] op_sel_hi:[1,0]
	v_pk_mul_f32 v[104:105], v[92:93], v[102:103] op_sel_hi:[1,0]
	v_pk_mul_f32 v[92:93], v[90:91], v[102:103] op_sel_hi:[1,0]
	s_and_b64 vcc, exec, s[40:41]
	v_pk_mul_f32 v[94:95], v[94:95], v[102:103] op_sel_hi:[1,0]
	s_nop 0
	v_cvt_pk_bf16_f32 v90, v94, v95
	v_cvt_pk_bf16_f32 v91, v96, v97
	v_cvt_pk_bf16_f32 v92, v92, v93
	v_cvt_pk_bf16_f32 v93, v104, v105
	s_cbranch_vccnz .LBB0_192
	s_cmp_lt_u32 s34, 8
	s_cbranch_scc1 .LBB0_189
	s_lshl_b32 s2, s34, 2
	s_lshl_b32 s3, s34, 1
	s_and_b32 s2, s2, 4
	s_and_b32 s3, s3, 0x3fffc
	s_or_b32 s2, s2, s61
	s_add_i32 s3, s20, s3
	s_lshl_b32 s3, s3, 14
	s_lshl_b32 s2, s2, 11
	s_or_b32 s2, s3, s2
	v_or_b32_e32 v94, s2, v100
	v_ashrrev_i32_e32 v95, 31, v94
	v_lshlrev_b64 v[94:95], 7, v[94:95]
	v_lshl_add_u64 v[96:97], v[140:141], 0, v[94:95]
	s_mov_b64 s[2:3], 0

; __device__ __forceinline__ unsigned cvt_pk_bf16(float lo, float hi) { unsigned r; asm volatile("v_cvt_pk_bf16_f32 %0, %1, %2" : "=v"(r) : "v"(lo), "v"(hi)); return r; }
;     __device__ __forceinline__ void operator()(const f32x4 (&acc)[2][2][4][2], const Unit& u, int wr, int wc, int fr, int fq) const {
;     ...
;             for (int m = 0; m < 4; ++m) { const int row = row0 + ai * HALF + m * 16; const float rs = rsv[ai][m];
; #pragma unroll
;                 for (int bj = 0; bj < 2; ++bj) { const f32x4 v0 = acc[ai][bj][m][0] * rs, v1 = acc[ai][bj][m][1] * rs;
;                     u32x4 o; o.x = cvt_pk_bf16(v0[0], v0[1]); o.y = cvt_pk_bf16(v0[2], v0[3]); o.z = cvt_pk_bf16(v1[0], v1[1]); o.w = cvt_pk_bf16(v1[2], v1[3]);
;                     bf16_t* dst;
;                     if (u.pn < 4) { const int colg = u.pn * BM + bj * HALF + wc * 32 + 8 * fq; dst = P + (size_t)(colg >> 9) * ((size_t)T * 512) + (size_t)row * 512 + (colg & 511); }
;                     else if (u.pn < 8) { const int colc = (u.pn - 4) * BM + bj * HALF + wc * 32 + 8 * fq; dst = P + PJ_UC + (size_t)row * 1024 + colc; }
;                     else { const int which = (u.pn - 8) >> 1, hd = ((u.pn - 8) & 1) * 4 + 2 * bj + (wc >> 1), dim = 32 * (wc & 1) + 8 * fq, bb = row >> 11, ll = row & 2047;
;                         dst = P + PJ_QKV + ((size_t)(((which * 4 + bb) * 8 + hd) * SEQ + ll)) * 64 + dim; }
;                     *(u32x4*)dst = o; } }
.LBB0_194:
	v_mov_b32_e32 v103, v102
	global_store_dwordx4 v[96:97], v[90:93], off sc1
	s_and_b64 vcc, exec, s[40:41]
	s_mov_b64 s[2:3], -1
	v_mov_b32_e32 v90, v102
	v_mov_b32_e32 v91, v102
	v_pk_mul_f32 v[88:89], v[88:89], v[90:91]
	v_pk_mul_f32 v[90:91], v[84:85], v[90:91]
	v_pk_mul_f32 v[84:85], v[82:83], v[102:103]
	v_pk_mul_f32 v[86:87], v[86:87], v[102:103]
	s_nop 0
	v_cvt_pk_bf16_f32 v82, v86, v87
	v_cvt_pk_bf16_f32 v83, v88, v89
	v_cvt_pk_bf16_f32 v84, v84, v85
	v_cvt_pk_bf16_f32 v85, v90, v91
	s_cbranch_vccnz .LBB0_200
	s_cmp_lt_u32 s34, 8
	s_cbranch_scc1 .LBB0_197
	s_lshl_b32 s2, s34, 2
	s_lshl_b32 s3, s34, 1
	s_and_b32 s2, s2, 4
	s_and_b32 s3, s3, 0x3fffc
	s_or_b32 s2, s2, s61
	s_add_i32 s3, s20, s3
	s_lshl_b32 s3, s3, 14
	s_lshl_b32 s2, s2, 11
	s_or_b32 s2, s2, s3
	v_or_b32_e32 v0, s2, v100
	v_or_b32_e32 v86, 0x1000, v0
	v_ashrrev_i32_e32 v87, 31, v86
	v_lshlrev_b64 v[86:87], 7, v[86:87]
	v_lshl_add_u64 v[88:89], v[140:141], 0, v[86:87]
	s_mov_b64 s[2:3], 0

; __device__ __forceinline__ unsigned cvt_pk_bf16(float lo, float hi) { unsigned r; asm volatile("v_cvt_pk_bf16_f32 %0, %1, %2" : "=v"(r) : "v"(lo), "v"(hi)); return r; }
;     __device__ __forceinline__ void operator()(const f32x4 (&acc)[2][2][4][2], const Unit& u, int wr, int wc, int fr, int fq) const {
;     ...
;                 for (int m = 0; m < 4; ++m) { float t = ((p0[ai][m][0] + p0[ai][m][1]) + (p0[ai][m][2] + p0[ai][m][3])) + ((p1[ai][m][0] + p1[ai][m][1]) + (p1[ai][m][2] + p1[ai][m][3]));
;                     t += __shfl_xor(t, 16); t += __shfl_xor(t, 32);
;                     rsv[ai][m] = 1.0f / sqrtf(t * (1.0f / D) + EPS); }
;         }
; #pragma unroll
;         for (int ai = 0; ai < 2; ++ai)
; #pragma unroll
;             for (int m = 0; m < 4; ++m) { const int row = row0 + ai * HALF + m * 16; const float rs = rsv[ai][m];
; #pragma unroll
;                 for (int bj = 0; bj < 2; ++bj) { const f32x4 v0 = acc[ai][bj][m][0] * rs, v1 = acc[ai][bj][m][1] * rs;
;                     u32x4 o; o.x = cvt_pk_bf16(v0[0], v0[1]); o.y = cvt_pk_bf16(v0[2], v0[3]); o.z = cvt_pk_bf16(v1[0], v1[1]); o.w = cvt_pk_bf16(v1[2], v1[3]);
;                     bf16_t* dst;
;                     if (u.pn < 4) { const int colg = u.pn * BM + bj * HALF + wc * 32 + 8 * fq; dst = P + (size_t)(colg >> 9) * ((size_t)T * 512) + (size_t)row * 512 + (colg & 511); }
;                     else if (u.pn < 8) { const int colc = (u.pn - 4) * BM + bj * HALF + wc * 32 + 8 * fq; dst = P + PJ_UC + (size_t)row * 1024 + colc; }
;                     else { const int which = (u.pn - 8) >> 1, hd = ((u.pn - 8) & 1) * 4 + 2 * bj + (wc >> 1), dim = 32 * (wc & 1) + 8 * fq, bb = row >> 11, ll = row & 2047;
;                         dst = P + PJ_QKV + ((size_t)(((which * 4 + bb) * 8 + hd) * SEQ + ll)) * 64 + dim; }
;                     *(u32x4*)dst = o; } }
.LBB0_202:
	s_waitcnt lgkmcnt(4)
	v_add_f32_e32 v0, v188, v189
	v_fmamk_f32 v0, v0, 0x3a000000, v223
	v_mul_f32_e32 v86, 0x4f800000, v0
	v_cmp_gt_f32_e32 vcc, s11, v0
	global_store_dwordx4 v[88:89], v[82:85], off sc1
	s_nop 0
	v_cndmask_b32_e32 v0, v0, v86, vcc
	v_sqrt_f32_e32 v86, v0
	v_and_b32_e32 v84, 0x7ff, v154
	v_lshlrev_b64 v[82:83], 11, v[154:155]
	v_add_u32_e32 v87, -1, v86
	v_fma_f32 v91, -v87, v86, v0
	v_add_u32_e32 v90, 1, v86
	v_cmp_ge_f32_e64 s[42:43], 0, v91
	s_nop 1
	v_cndmask_b32_e64 v87, v86, v87, s[42:43]
	v_fma_f32 v86, -v90, v86, v0
	v_cmp_lt_f32_e64 s[42:43], 0, v86
	s_nop 1
	v_cndmask_b32_e64 v86, v87, v90, s[42:43]
	v_mul_f32_e32 v87, 0x37800000, v86
	v_cndmask_b32_e32 v86, v86, v87, vcc
	v_cmp_class_f32_e32 vcc, v0, v224
	s_nop 1
	v_cndmask_b32_e32 v0, v86, v0, vcc
	v_div_scale_f32 v86, s[2:3], v0, v0, 1.0
	v_rcp_f32_e32 v87, v86
	s_mov_b64 s[2:3], -1
	v_fma_f32 v90, -v86, v87, 1.0
	v_fmac_f32_e32 v87, v90, v87
	v_div_scale_f32 v90, vcc, 1.0, v0, 1.0
	v_mul_f32_e32 v91, v90, v87
	v_fma_f32 v92, -v86, v91, v90
	v_fmac_f32_e32 v91, v92, v87
	v_fma_f32 v86, -v86, v91, v90
	v_div_fmas_f32 v86, v86, v87, v91
	v_div_fixup_f32 v86, v86, v0, 1.0
	v_pk_mul_f32 v[80:81], v[80:81], v[86:87] op_sel_hi:[1,0]
	v_pk_mul_f32 v[88:89], v[76:77], v[86:87] op_sel_hi:[1,0]
	v_pk_mul_f32 v[76:77], v[74:75], v[86:87] op_sel_hi:[1,0]
	s_and_b64 vcc, exec, s[40:41]
	v_pk_mul_f32 v[78:79], v[78:79], v[86:87] op_sel_hi:[1,0]
	s_nop 0
	v_cvt_pk_bf16_f32 v74, v78, v79
	v_cvt_pk_bf16_f32 v75, v80, v81
	v_cvt_pk_bf16_f32 v76, v76, v77
	v_cvt_pk_bf16_f32 v77, v88, v89
	s_cbranch_vccnz .LBB0_208
	s_cmp_lt_u32 s34, 8
	s_cbranch_scc1 .LBB0_205
	s_lshl_b32 s2, s34, 2
	s_lshl_b32 s3, s34, 1
	s_and_b32 s2, s2, 4
	s_and_b32 s3, s3, 0x3fffc
	s_or_b32 s2, s2, s61
	s_add_i32 s3, s20, s3
	s_lshl_b32 s3, s3, 14
	s_lshl_b32 s2, s2, 11
	s_or_b32 s2, s3, s2
	v_or_b32_e32 v78, s2, v84
	v_ashrrev_i32_e32 v79, 31, v78
	v_lshlrev_b64 v[78:79], 7, v[78:79]
	v_lshl_add_u64 v[80:81], v[140:141], 0, v[78:79]
	s_mov_b64 s[2:3], 0

; __device__ __forceinline__ unsigned cvt_pk_bf16(float lo, float hi) { unsigned r; asm volatile("v_cvt_pk_bf16_f32 %0, %1, %2" : "=v"(r) : "v"(lo), "v"(hi)); return r; }
;     __device__ __forceinline__ void operator()(const f32x4 (&acc)[2][2][4][2], const Unit& u, int wr, int wc, int fr, int fq) const {
;     ...
;             for (int m = 0; m < 4; ++m) { const int row = row0 + ai * HALF + m * 16; const float rs = rsv[ai][m];
; #pragma unroll
;                 for (int bj = 0; bj < 2; ++bj) { const f32x4 v0 = acc[ai][bj][m][0] * rs, v1 = acc[ai][bj][m][1] * rs;
;                     u32x4 o; o.x = cvt_pk_bf16(v0[0], v0[1]); o.y = cvt_pk_bf16(v0[2], v0[3]); o.z = cvt_pk_bf16(v1[0], v1[1]); o.w = cvt_pk_bf16(v1[2], v1[3]);
;                     bf16_t* dst;
;                     if (u.pn < 4) { const int colg = u.pn * BM + bj * HALF + wc * 32 + 8 * fq; dst = P + (size_t)(colg >> 9) * ((size_t)T * 512) + (size_t)row * 512 + (colg & 511); }
;                     else if (u.pn < 8) { const int colc = (u.pn - 4) * BM + bj * HALF + wc * 32 + 8 * fq; dst = P + PJ_UC + (size_t)row * 1024 + colc; }
;                     else { const int which = (u.pn - 8) >> 1, hd = ((u.pn - 8) & 1) * 4 + 2 * bj + (wc >> 1), dim = 32 * (wc & 1) + 8 * fq, bb = row >> 11, ll = row & 2047;
;                         dst = P + PJ_QKV + ((size_t)(((which * 4 + bb) * 8 + hd) * SEQ + ll)) * 64 + dim; }
;                     *(u32x4*)dst = o; } }
.LBB0_210:
	v_mov_b32_e32 v87, v86
	global_store_dwordx4 v[80:81], v[74:77], off sc1
	s_and_b64 vcc, exec, s[40:41]
	s_mov_b64 s[2:3], -1
	v_mov_b32_e32 v74, v86
	v_mov_b32_e32 v75, v86
	v_pk_mul_f32 v[72:73], v[72:73], v[74:75]
	v_pk_mul_f32 v[74:75], v[68:69], v[74:75]
	v_pk_mul_f32 v[68:69], v[66:67], v[86:87]
	v_pk_mul_f32 v[70:71], v[70:71], v[86:87]
	s_nop 0
	v_cvt_pk_bf16_f32 v66, v70, v71
	v_cvt_pk_bf16_f32 v67, v72, v73
	v_cvt_pk_bf16_f32 v68, v68, v69
	v_cvt_pk_bf16_f32 v69, v74, v75
	s_cbranch_vccnz .LBB0_216
	s_cmp_lt_u32 s34, 8
	s_cbranch_scc1 .LBB0_213
	s_lshl_b32 s2, s34, 2
	s_lshl_b32 s3, s34, 1
	s_and_b32 s2, s2, 4
	s_and_b32 s3, s3, 0x3fffc
	s_or_b32 s2, s2, s61
	s_add_i32 s20, s20, s3
	s_lshl_b32 s3, s20, 14
	s_lshl_b32 s2, s2, 11
	s_or_b32 s2, s2, s3
	v_or_b32_e32 v0, s2, v84
	v_or_b32_e32 v70, 0x1000, v0
	v_ashrrev_i32_e32 v71, 31, v70
	v_lshlrev_b64 v[70:71], 7, v[70:71]
	v_lshl_add_u64 v[72:73], v[140:141], 0, v[70:71]
	s_mov_b64 s[2:3], 0

; __device__ __forceinline__ unsigned cvt_pk_bf16(float lo, float hi) { unsigned r; asm volatile("v_cvt_pk_bf16_f32 %0, %1, %2" : "=v"(r) : "v"(lo), "v"(hi)); return r; }
;     __device__ __forceinline__ void operator()(const f32x4 (&acc)[2][2][4][2], const Unit& u, int wr, int wc, int fr, int fq) const {
;     ...
;                 for (int m = 0; m < 4; ++m) { float t = ((p0[ai][m][0] + p0[ai][m][1]) + (p0[ai][m][2] + p0[ai][m][3])) + ((p1[ai][m][0] + p1[ai][m][1]) + (p1[ai][m][2] + p1[ai][m][3]));
;                     t += __shfl_xor(t, 16); t += __shfl_xor(t, 32);
;                     rsv[ai][m] = 1.0f / sqrtf(t * (1.0f / D) + EPS); }
;         }
; #pragma unroll
;         for (int ai = 0; ai < 2; ++ai)
; #pragma unroll
;             for (int m = 0; m < 4; ++m) { const int row = row0 + ai * HALF + m * 16; const float rs = rsv[ai][m];
; #pragma unroll
;                 for (int bj = 0; bj < 2; ++bj) { const f32x4 v0 = acc[ai][bj][m][0] * rs, v1 = acc[ai][bj][m][1] * rs;
;                     u32x4 o; o.x = cvt_pk_bf16(v0[0], v0[1]); o.y = cvt_pk_bf16(v0[2], v0[3]); o.z = cvt_pk_bf16(v1[0], v1[1]); o.w = cvt_pk_bf16(v1[2], v1[3]);
;                     bf16_t* dst;
;                     if (u.pn < 4) { const int colg = u.pn * BM + bj * HALF + wc * 32 + 8 * fq; dst = P + (size_t)(colg >> 9) * ((size_t)T * 512) + (size_t)row * 512 + (colg & 511); }
;                     else if (u.pn < 8) { const int colc = (u.pn - 4) * BM + bj * HALF + wc * 32 + 8 * fq; dst = P + PJ_UC + (size_t)row * 1024 + colc; }
;                     else { const int which = (u.pn - 8) >> 1, hd = ((u.pn - 8) & 1) * 4 + 2 * bj + (wc >> 1), dim = 32 * (wc & 1) + 8 * fq, bb = row >> 11, ll = row & 2047;
;                         dst = P + PJ_QKV + ((size_t)(((which * 4 + bb) * 8 + hd) * SEQ + ll)) * 64 + dim; }
;                     *(u32x4*)dst = o; } }
.LBB0_218:
	s_waitcnt lgkmcnt(3)
	v_add_f32_e32 v0, v178, v183
	v_fmamk_f32 v0, v0, 0x3a000000, v223
	v_mul_f32_e32 v70, 0x4f800000, v0
	v_cmp_gt_f32_e32 vcc, s11, v0
	global_store_dwordx4 v[72:73], v[66:69], off sc1
	s_nop 0
	v_cndmask_b32_e32 v0, v0, v70, vcc
	v_sqrt_f32_e32 v70, v0
	v_and_b32_e32 v69, 0x7cf, v152
	v_lshlrev_b64 v[66:67], 11, v[152:153]
	v_add_u32_e32 v71, -1, v70
	v_fma_f32 v75, -v71, v70, v0
	v_add_u32_e32 v74, 1, v70
	v_cmp_ge_f32_e64 s[42:43], 0, v75
	s_nop 1
	v_cndmask_b32_e64 v71, v70, v71, s[42:43]
	v_fma_f32 v70, -v74, v70, v0
	v_cmp_lt_f32_e64 s[42:43], 0, v70
	s_nop 1
	v_cndmask_b32_e64 v70, v71, v74, s[42:43]
	v_mul_f32_e32 v71, 0x37800000, v70
	v_cndmask_b32_e32 v70, v70, v71, vcc
	v_cmp_class_f32_e32 vcc, v0, v224
	s_nop 1
	v_cndmask_b32_e32 v0, v70, v0, vcc
	v_div_scale_f32 v70, s[2:3], v0, v0, 1.0
	v_rcp_f32_e32 v71, v70
	s_mov_b64 s[2:3], -1
	v_fma_f32 v74, -v70, v71, 1.0
	v_fmac_f32_e32 v71, v74, v71
	v_div_scale_f32 v74, vcc, 1.0, v0, 1.0
	v_mul_f32_e32 v75, v74, v71
	v_fma_f32 v76, -v70, v75, v74
	v_fmac_f32_e32 v75, v76, v71
	v_fma_f32 v70, -v70, v75, v74
	v_div_fmas_f32 v70, v70, v71, v75
	v_div_fixup_f32 v70, v70, v0, 1.0
	v_lshrrev_b32_e32 v0, 11, v152
	v_add_u32_e32 v68, 0x3fff0, v0
	v_pk_mul_f32 v[64:65], v[64:65], v[70:71] op_sel_hi:[1,0]
	v_pk_mul_f32 v[72:73], v[60:61], v[70:71] op_sel_hi:[1,0]
	v_pk_mul_f32 v[60:61], v[58:59], v[70:71] op_sel_hi:[1,0]
	s_and_b64 vcc, exec, s[40:41]
	v_pk_mul_f32 v[62:63], v[62:63], v[70:71] op_sel_hi:[1,0]
	s_nop 0
	v_cvt_pk_bf16_f32 v58, v62, v63
	v_cvt_pk_bf16_f32 v59, v64, v65
	v_cvt_pk_bf16_f32 v60, v60, v61
	v_cvt_pk_bf16_f32 v61, v72, v73
	s_cbranch_vccnz .LBB0_224
	s_cmp_lt_u32 s34, 8
	s_cbranch_scc1 .LBB0_221
	s_lshl_b32 s2, s34, 2
	s_and_b32 s2, s2, 4
	s_lshl_b32 s3, s34, 1
	s_or_b32 s2, s2, s61
	s_and_b32 s3, s3, 0x3fffc
	v_add_lshl_u32 v0, v68, s3, 14
	s_lshl_b32 s2, s2, 11
	v_or3_b32 v62, v0, s2, v69
	v_ashrrev_i32_e32 v63, 31, v62
	v_lshlrev_b64 v[62:63], 7, v[62:63]
	v_lshl_add_u64 v[64:65], v[140:141], 0, v[62:63]
	s_mov_b64 s[2:3], 0

; __device__ __forceinline__ unsigned cvt_pk_bf16(float lo, float hi) { unsigned r; asm volatile("v_cvt_pk_bf16_f32 %0, %1, %2" : "=v"(r) : "v"(lo), "v"(hi)); return r; }
;     __device__ __forceinline__ void operator()(const f32x4 (&acc)[2][2][4][2], const Unit& u, int wr, int wc, int fr, int fq) const {
;     ...
;             for (int m = 0; m < 4; ++m) { const int row = row0 + ai * HALF + m * 16; const float rs = rsv[ai][m];
; #pragma unroll
;                 for (int bj = 0; bj < 2; ++bj) { const f32x4 v0 = acc[ai][bj][m][0] * rs, v1 = acc[ai][bj][m][1] * rs;
;                     u32x4 o; o.x = cvt_pk_bf16(v0[0], v0[1]); o.y = cvt_pk_bf16(v0[2], v0[3]); o.z = cvt_pk_bf16(v1[0], v1[1]); o.w = cvt_pk_bf16(v1[2], v1[3]);
;                     bf16_t* dst;
;                     if (u.pn < 4) { const int colg = u.pn * BM + bj * HALF + wc * 32 + 8 * fq; dst = P + (size_t)(colg >> 9) * ((size_t)T * 512) + (size_t)row * 512 + (colg & 511); }
;                     else if (u.pn < 8) { const int colc = (u.pn - 4) * BM + bj * HALF + wc * 32 + 8 * fq; dst = P + PJ_UC + (size_t)row * 1024 + colc; }
;                     else { const int which = (u.pn - 8) >> 1, hd = ((u.pn - 8) & 1) * 4 + 2 * bj + (wc >> 1), dim = 32 * (wc & 1) + 8 * fq, bb = row >> 11, ll = row & 2047;
;                         dst = P + PJ_QKV + ((size_t)(((which * 4 + bb) * 8 + hd) * SEQ + ll)) * 64 + dim; }
;                     *(u32x4*)dst = o; } }
.LBB0_226:
	v_mov_b32_e32 v71, v70
	global_store_dwordx4 v[64:65], v[58:61], off sc1
	s_and_b64 vcc, exec, s[40:41]
	s_mov_b64 s[2:3], -1
	v_mov_b32_e32 v58, v70
	v_mov_b32_e32 v59, v70
	v_pk_mul_f32 v[56:57], v[56:57], v[58:59]
	v_pk_mul_f32 v[58:59], v[52:53], v[58:59]
	v_pk_mul_f32 v[52:53], v[50:51], v[70:71]
	v_pk_mul_f32 v[54:55], v[54:55], v[70:71]
	s_nop 0
	v_cvt_pk_bf16_f32 v50, v54, v55
	v_cvt_pk_bf16_f32 v51, v56, v57
	v_cvt_pk_bf16_f32 v52, v52, v53
	v_cvt_pk_bf16_f32 v53, v58, v59
	s_cbranch_vccnz .LBB0_232
	s_cmp_lt_u32 s34, 8
	s_cbranch_scc1 .LBB0_229
	s_lshl_b32 s2, s34, 2
	s_and_b32 s2, s2, 4
	s_lshl_b32 s3, s34, 1
	s_or_b32 s2, s2, s61
	s_and_b32 s3, s3, 0x3fffc
	v_add_u32_e32 v0, s3, v68
	s_lshl_b32 s2, s2, 11
	v_lshl_or_b32 v0, v0, 14, s2
	s_movk_i32 s2, 0x1000
	v_or3_b32 v54, v0, v69, s2
	v_ashrrev_i32_e32 v55, 31, v54
	v_lshlrev_b64 v[54:55], 7, v[54:55]
	v_lshl_add_u64 v[56:57], v[140:141], 0, v[54:55]
	s_mov_b64 s[2:3], 0

; __device__ __forceinline__ unsigned cvt_pk_bf16(float lo, float hi) { unsigned r; asm volatile("v_cvt_pk_bf16_f32 %0, %1, %2" : "=v"(r) : "v"(lo), "v"(hi)); return r; }
;     __device__ __forceinline__ void operator()(const f32x4 (&acc)[2][2][4][2], const Unit& u, int wr, int wc, int fr, int fq) const {
;     ...
;                 for (int m = 0; m < 4; ++m) { float t = ((p0[ai][m][0] + p0[ai][m][1]) + (p0[ai][m][2] + p0[ai][m][3])) + ((p1[ai][m][0] + p1[ai][m][1]) + (p1[ai][m][2] + p1[ai][m][3]));
;                     t += __shfl_xor(t, 16); t += __shfl_xor(t, 32);
;                     rsv[ai][m] = 1.0f / sqrtf(t * (1.0f / D) + EPS); }
;         }
; #pragma unroll
;         for (int ai = 0; ai < 2; ++ai)
; #pragma unroll
;             for (int m = 0; m < 4; ++m) { const int row = row0 + ai * HALF + m * 16; const float rs = rsv[ai][m];
; #pragma unroll
;                 for (int bj = 0; bj < 2; ++bj) { const f32x4 v0 = acc[ai][bj][m][0] * rs, v1 = acc[ai][bj][m][1] * rs;
;                     u32x4 o; o.x = cvt_pk_bf16(v0[0], v0[1]); o.y = cvt_pk_bf16(v0[2], v0[3]); o.z = cvt_pk_bf16(v1[0], v1[1]); o.w = cvt_pk_bf16(v1[2], v1[3]);
;                     bf16_t* dst;
;                     if (u.pn < 4) { const int colg = u.pn * BM + bj * HALF + wc * 32 + 8 * fq; dst = P + (size_t)(colg >> 9) * ((size_t)T * 512) + (size_t)row * 512 + (colg & 511); }
;                     else if (u.pn < 8) { const int colc = (u.pn - 4) * BM + bj * HALF + wc * 32 + 8 * fq; dst = P + PJ_UC + (size_t)row * 1024 + colc; }
;                     else { const int which = (u.pn - 8) >> 1, hd = ((u.pn - 8) & 1) * 4 + 2 * bj + (wc >> 1), dim = 32 * (wc & 1) + 8 * fq, bb = row >> 11, ll = row & 2047;
;                         dst = P + PJ_QKV + ((size_t)(((which * 4 + bb) * 8 + hd) * SEQ + ll)) * 64 + dim; }
;                     *(u32x4*)dst = o; } }
.LBB0_234:
	s_waitcnt lgkmcnt(2)
	v_add_f32_e32 v0, v176, v177
	v_fmamk_f32 v0, v0, 0x3a000000, v223
	v_mul_f32_e32 v54, 0x4f800000, v0
	v_cmp_gt_f32_e32 vcc, s11, v0
	global_store_dwordx4 v[56:57], v[50:53], off sc1
	s_nop 0
	v_cndmask_b32_e32 v0, v0, v54, vcc
	v_sqrt_f32_e32 v54, v0
	v_and_b32_e32 v52, 0x7df, v150
	v_lshlrev_b64 v[50:51], 11, v[150:151]
	v_add_u32_e32 v55, -1, v54
	v_fma_f32 v59, -v55, v54, v0
	v_add_u32_e32 v58, 1, v54
	v_cmp_ge_f32_e64 s[42:43], 0, v59
	s_nop 1
	v_cndmask_b32_e64 v55, v54, v55, s[42:43]
	v_fma_f32 v54, -v58, v54, v0
	v_cmp_lt_f32_e64 s[42:43], 0, v54
	s_nop 1
	v_cndmask_b32_e64 v54, v55, v58, s[42:43]
	v_mul_f32_e32 v55, 0x37800000, v54
	v_cndmask_b32_e32 v54, v54, v55, vcc
	v_cmp_class_f32_e32 vcc, v0, v224
	s_nop 1
	v_cndmask_b32_e32 v0, v54, v0, vcc
	v_div_scale_f32 v54, s[2:3], v0, v0, 1.0
	v_rcp_f32_e32 v55, v54
	s_mov_b64 s[2:3], -1
	v_fma_f32 v58, -v54, v55, 1.0
	v_fmac_f32_e32 v55, v58, v55
	v_div_scale_f32 v58, vcc, 1.0, v0, 1.0
	v_mul_f32_e32 v59, v58, v55
	v_fma_f32 v60, -v54, v59, v58
	v_fmac_f32_e32 v59, v60, v55
	v_fma_f32 v54, -v54, v59, v58
	v_div_fmas_f32 v54, v54, v55, v59
	v_div_fixup_f32 v54, v54, v0, 1.0
	v_pk_mul_f32 v[48:49], v[48:49], v[54:55] op_sel_hi:[1,0]
	v_pk_mul_f32 v[56:57], v[44:45], v[54:55] op_sel_hi:[1,0]
	v_pk_mul_f32 v[44:45], v[42:43], v[54:55] op_sel_hi:[1,0]
	s_and_b64 vcc, exec, s[40:41]
	v_pk_mul_f32 v[46:47], v[46:47], v[54:55] op_sel_hi:[1,0]
	s_nop 0
	v_cvt_pk_bf16_f32 v42, v46, v47
	v_cvt_pk_bf16_f32 v43, v48, v49
	v_cvt_pk_bf16_f32 v44, v44, v45
	v_cvt_pk_bf16_f32 v45, v56, v57
	s_cbranch_vccnz .LBB0_240
	s_cmp_lt_u32 s34, 8
	s_cbranch_scc1 .LBB0_237
	s_lshl_b32 s2, s34, 2
	s_and_b32 s2, s2, 4
	s_lshl_b32 s3, s34, 1
	s_or_b32 s2, s2, s61
	s_and_b32 s3, s3, 0x3fffc
	v_add_lshl_u32 v0, v68, s3, 14
	s_lshl_b32 s2, s2, 11
	v_or3_b32 v46, v0, s2, v52
	v_ashrrev_i32_e32 v47, 31, v46
	v_lshlrev_b64 v[46:47], 7, v[46:47]
	v_lshl_add_u64 v[48:49], v[140:141], 0, v[46:47]
	s_mov_b64 s[2:3], 0

; __device__ __forceinline__ unsigned cvt_pk_bf16(float lo, float hi) { unsigned r; asm volatile("v_cvt_pk_bf16_f32 %0, %1, %2" : "=v"(r) : "v"(lo), "v"(hi)); return r; }
;     __device__ __forceinline__ void operator()(const f32x4 (&acc)[2][2][4][2], const Unit& u, int wr, int wc, int fr, int fq) const {
;     ...
;             for (int m = 0; m < 4; ++m) { const int row = row0 + ai * HALF + m * 16; const float rs = rsv[ai][m];
; #pragma unroll
;                 for (int bj = 0; bj < 2; ++bj) { const f32x4 v0 = acc[ai][bj][m][0] * rs, v1 = acc[ai][bj][m][1] * rs;
;                     u32x4 o; o.x = cvt_pk_bf16(v0[0], v0[1]); o.y = cvt_pk_bf16(v0[2], v0[3]); o.z = cvt_pk_bf16(v1[0], v1[1]); o.w = cvt_pk_bf16(v1[2], v1[3]);
;                     bf16_t* dst;
;                     if (u.pn < 4) { const int colg = u.pn * BM + bj * HALF + wc * 32 + 8 * fq; dst = P + (size_t)(colg >> 9) * ((size_t)T * 512) + (size_t)row * 512 + (colg & 511); }
;                     else if (u.pn < 8) { const int colc = (u.pn - 4) * BM + bj * HALF + wc * 32 + 8 * fq; dst = P + PJ_UC + (size_t)row * 1024 + colc; }
;                     else { const int which = (u.pn - 8) >> 1, hd = ((u.pn - 8) & 1) * 4 + 2 * bj + (wc >> 1), dim = 32 * (wc & 1) + 8 * fq, bb = row >> 11, ll = row & 2047;
;                         dst = P + PJ_QKV + ((size_t)(((which * 4 + bb) * 8 + hd) * SEQ + ll)) * 64 + dim; }
;                     *(u32x4*)dst = o; } }
.LBB0_242:
	v_mov_b32_e32 v55, v54
	global_store_dwordx4 v[48:49], v[42:45], off sc1
	s_and_b64 vcc, exec, s[40:41]
	s_mov_b64 s[2:3], -1
	v_mov_b32_e32 v42, v54
	v_mov_b32_e32 v43, v54
	v_pk_mul_f32 v[40:41], v[40:41], v[42:43]
	v_pk_mul_f32 v[42:43], v[36:37], v[42:43]
	v_pk_mul_f32 v[36:37], v[34:35], v[54:55]
	v_pk_mul_f32 v[38:39], v[38:39], v[54:55]
	s_nop 0
	v_cvt_pk_bf16_f32 v34, v38, v39
	v_cvt_pk_bf16_f32 v35, v40, v41
	v_cvt_pk_bf16_f32 v36, v36, v37
	v_cvt_pk_bf16_f32 v37, v42, v43
	s_cbranch_vccnz .LBB0_248
	s_cmp_lt_u32 s34, 8
	s_cbranch_scc1 .LBB0_245
	s_lshl_b32 s2, s34, 2
	s_and_b32 s2, s2, 4
	s_lshl_b32 s3, s34, 1
	s_or_b32 s2, s2, s61
	s_and_b32 s3, s3, 0x3fffc
	v_add_u32_e32 v0, s3, v68
	s_lshl_b32 s2, s2, 11
	v_lshl_or_b32 v0, v0, 14, s2
	s_movk_i32 s2, 0x1000
	v_or3_b32 v38, v0, v52, s2
	v_ashrrev_i32_e32 v39, 31, v38
	v_lshlrev_b64 v[38:39], 7, v[38:39]
	v_lshl_add_u64 v[40:41], v[140:141], 0, v[38:39]
	s_mov_b64 s[2:3], 0

; __device__ __forceinline__ unsigned cvt_pk_bf16(float lo, float hi) { unsigned r; asm volatile("v_cvt_pk_bf16_f32 %0, %1, %2" : "=v"(r) : "v"(lo), "v"(hi)); return r; }
;     __device__ __forceinline__ void operator()(const f32x4 (&acc)[2][2][4][2], const Unit& u, int wr, int wc, int fr, int fq) const {
;     ...
;                 for (int m = 0; m < 4; ++m) { float t = ((p0[ai][m][0] + p0[ai][m][1]) + (p0[ai][m][2] + p0[ai][m][3])) + ((p1[ai][m][0] + p1[ai][m][1]) + (p1[ai][m][2] + p1[ai][m][3]));
;                     t += __shfl_xor(t, 16); t += __shfl_xor(t, 32);
;                     rsv[ai][m] = 1.0f / sqrtf(t * (1.0f / D) + EPS); }
;         }
; #pragma unroll
;         for (int ai = 0; ai < 2; ++ai)
; #pragma unroll
;             for (int m = 0; m < 4; ++m) { const int row = row0 + ai * HALF + m * 16; const float rs = rsv[ai][m];
; #pragma unroll
;                 for (int bj = 0; bj < 2; ++bj) { const f32x4 v0 = acc[ai][bj][m][0] * rs, v1 = acc[ai][bj][m][1] * rs;
;                     u32x4 o; o.x = cvt_pk_bf16(v0[0], v0[1]); o.y = cvt_pk_bf16(v0[2], v0[3]); o.z = cvt_pk_bf16(v1[0], v1[1]); o.w = cvt_pk_bf16(v1[2], v1[3]);
;                     bf16_t* dst;
;                     if (u.pn < 4) { const int colg = u.pn * BM + bj * HALF + wc * 32 + 8 * fq; dst = P + (size_t)(colg >> 9) * ((size_t)T * 512) + (size_t)row * 512 + (colg & 511); }
;                     else if (u.pn < 8) { const int colc = (u.pn - 4) * BM + bj * HALF + wc * 32 + 8 * fq; dst = P + PJ_UC + (size_t)row * 1024 + colc; }
;                     else { const int which = (u.pn - 8) >> 1, hd = ((u.pn - 8) & 1) * 4 + 2 * bj + (wc >> 1), dim = 32 * (wc & 1) + 8 * fq, bb = row >> 11, ll = row & 2047;
;                         dst = P + PJ_QKV + ((size_t)(((which * 4 + bb) * 8 + hd) * SEQ + ll)) * 64 + dim; }
;                     *(u32x4*)dst = o; } }
.LBB0_250:
	s_waitcnt lgkmcnt(1)
	v_add_f32_e32 v0, v174, v175
	v_fmamk_f32 v0, v0, 0x3a000000, v223
	v_mul_f32_e32 v38, 0x4f800000, v0
	v_cmp_gt_f32_e32 vcc, s11, v0
	global_store_dwordx4 v[40:41], v[34:37], off sc1
	s_nop 0
	v_cndmask_b32_e32 v0, v0, v38, vcc
	v_sqrt_f32_e32 v38, v0
	v_and_b32_e32 v36, 0x7ef, v148
	v_lshlrev_b64 v[34:35], 11, v[148:149]
	v_add_u32_e32 v39, -1, v38
	v_fma_f32 v43, -v39, v38, v0
	v_add_u32_e32 v42, 1, v38
	v_cmp_ge_f32_e64 s[42:43], 0, v43
	s_nop 1
	v_cndmask_b32_e64 v39, v38, v39, s[42:43]
	v_fma_f32 v38, -v42, v38, v0
	v_cmp_lt_f32_e64 s[42:43], 0, v38
	s_nop 1
	v_cndmask_b32_e64 v38, v39, v42, s[42:43]
	v_mul_f32_e32 v39, 0x37800000, v38
	v_cndmask_b32_e32 v38, v38, v39, vcc
	v_cmp_class_f32_e32 vcc, v0, v224
	s_nop 1
	v_cndmask_b32_e32 v0, v38, v0, vcc
	v_div_scale_f32 v38, s[2:3], v0, v0, 1.0
	v_rcp_f32_e32 v39, v38
	s_mov_b64 s[2:3], -1
	v_fma_f32 v42, -v38, v39, 1.0
	v_fmac_f32_e32 v39, v42, v39
	v_div_scale_f32 v42, vcc, 1.0, v0, 1.0
	v_mul_f32_e32 v43, v42, v39
	v_fma_f32 v44, -v38, v43, v42
	v_fmac_f32_e32 v43, v44, v39
	v_fma_f32 v38, -v38, v43, v42
	v_div_fmas_f32 v38, v38, v39, v43
	v_div_fixup_f32 v38, v38, v0, 1.0
	v_pk_mul_f32 v[32:33], v[32:33], v[38:39] op_sel_hi:[1,0]
	v_pk_mul_f32 v[40:41], v[28:29], v[38:39] op_sel_hi:[1,0]
	v_pk_mul_f32 v[28:29], v[26:27], v[38:39] op_sel_hi:[1,0]
	s_and_b64 vcc, exec, s[40:41]
	v_pk_mul_f32 v[30:31], v[30:31], v[38:39] op_sel_hi:[1,0]
	s_nop 0
	v_cvt_pk_bf16_f32 v26, v30, v31
	v_cvt_pk_bf16_f32 v27, v32, v33
	v_cvt_pk_bf16_f32 v28, v28, v29
	v_cvt_pk_bf16_f32 v29, v40, v41
	s_cbranch_vccnz .LBB0_256
	s_cmp_lt_u32 s34, 8
	s_cbranch_scc1 .LBB0_253
	s_lshl_b32 s2, s34, 2
	s_and_b32 s2, s2, 4
	s_lshl_b32 s3, s34, 1
	s_or_b32 s2, s2, s61
	s_and_b32 s3, s3, 0x3fffc
	v_add_lshl_u32 v0, v68, s3, 14
	s_lshl_b32 s2, s2, 11
	v_or3_b32 v30, v0, s2, v36
	v_ashrrev_i32_e32 v31, 31, v30
	v_lshlrev_b64 v[30:31], 7, v[30:31]
	v_lshl_add_u64 v[32:33], v[140:141], 0, v[30:31]
	s_mov_b64 s[2:3], 0

; __device__ __forceinline__ unsigned cvt_pk_bf16(float lo, float hi) { unsigned r; asm volatile("v_cvt_pk_bf16_f32 %0, %1, %2" : "=v"(r) : "v"(lo), "v"(hi)); return r; }
;     __device__ __forceinline__ void operator()(const f32x4 (&acc)[2][2][4][2], const Unit& u, int wr, int wc, int fr, int fq) const {
;     ...
;             for (int m = 0; m < 4; ++m) { const int row = row0 + ai * HALF + m * 16; const float rs = rsv[ai][m];
; #pragma unroll
;                 for (int bj = 0; bj < 2; ++bj) { const f32x4 v0 = acc[ai][bj][m][0] * rs, v1 = acc[ai][bj][m][1] * rs;
;                     u32x4 o; o.x = cvt_pk_bf16(v0[0], v0[1]); o.y = cvt_pk_bf16(v0[2], v0[3]); o.z = cvt_pk_bf16(v1[0], v1[1]); o.w = cvt_pk_bf16(v1[2], v1[3]);
;                     bf16_t* dst;
;                     if (u.pn < 4) { const int colg = u.pn * BM + bj * HALF + wc * 32 + 8 * fq; dst = P + (size_t)(colg >> 9) * ((size_t)T * 512) + (size_t)row * 512 + (colg & 511); }
;                     else if (u.pn < 8) { const int colc = (u.pn - 4) * BM + bj * HALF + wc * 32 + 8 * fq; dst = P + PJ_UC + (size_t)row * 1024 + colc; }
;                     else { const int which = (u.pn - 8) >> 1, hd = ((u.pn - 8) & 1) * 4 + 2 * bj + (wc >> 1), dim = 32 * (wc & 1) + 8 * fq, bb = row >> 11, ll = row & 2047;
;                         dst = P + PJ_QKV + ((size_t)(((which * 4 + bb) * 8 + hd) * SEQ + ll)) * 64 + dim; }
;                     *(u32x4*)dst = o; } }
.LBB0_258:
	v_mov_b32_e32 v39, v38
	global_store_dwordx4 v[32:33], v[26:29], off sc1
	s_and_b64 vcc, exec, s[40:41]
	s_mov_b64 s[2:3], -1
	v_mov_b32_e32 v26, v38
	v_mov_b32_e32 v27, v38
	v_pk_mul_f32 v[24:25], v[24:25], v[26:27]
	v_pk_mul_f32 v[26:27], v[20:21], v[26:27]
	v_pk_mul_f32 v[20:21], v[18:19], v[38:39]
	v_pk_mul_f32 v[22:23], v[22:23], v[38:39]
	s_nop 0
	v_cvt_pk_bf16_f32 v18, v22, v23
	v_cvt_pk_bf16_f32 v19, v24, v25
	v_cvt_pk_bf16_f32 v20, v20, v21
	v_cvt_pk_bf16_f32 v21, v26, v27
	s_cbranch_vccnz .LBB0_264
	s_cmp_lt_u32 s34, 8
	s_cbranch_scc1 .LBB0_261
	s_lshl_b32 s2, s34, 2
	s_and_b32 s2, s2, 4
	s_lshl_b32 s3, s34, 1
	s_or_b32 s2, s2, s61
	s_and_b32 s3, s3, 0x3fffc
	v_add_u32_e32 v0, s3, v68
	s_lshl_b32 s2, s2, 11
	v_lshl_or_b32 v0, v0, 14, s2
	s_movk_i32 s2, 0x1000
	v_or3_b32 v22, v0, v36, s2
	v_ashrrev_i32_e32 v23, 31, v22
	v_lshlrev_b64 v[22:23], 7, v[22:23]
	v_lshl_add_u64 v[24:25], v[140:141], 0, v[22:23]
	s_mov_b64 s[2:3], 0

; __device__ __forceinline__ unsigned cvt_pk_bf16(float lo, float hi) { unsigned r; asm volatile("v_cvt_pk_bf16_f32 %0, %1, %2" : "=v"(r) : "v"(lo), "v"(hi)); return r; }
;     __device__ __forceinline__ void operator()(const f32x4 (&acc)[2][2][4][2], const Unit& u, int wr, int wc, int fr, int fq) const {
;     ...
;                 for (int m = 0; m < 4; ++m) { float t = ((p0[ai][m][0] + p0[ai][m][1]) + (p0[ai][m][2] + p0[ai][m][3])) + ((p1[ai][m][0] + p1[ai][m][1]) + (p1[ai][m][2] + p1[ai][m][3]));
;                     t += __shfl_xor(t, 16); t += __shfl_xor(t, 32);
;                     rsv[ai][m] = 1.0f / sqrtf(t * (1.0f / D) + EPS); }
;         }
; #pragma unroll
;         for (int ai = 0; ai < 2; ++ai)
; #pragma unroll
;             for (int m = 0; m < 4; ++m) { const int row = row0 + ai * HALF + m * 16; const float rs = rsv[ai][m];
; #pragma unroll
;                 for (int bj = 0; bj < 2; ++bj) { const f32x4 v0 = acc[ai][bj][m][0] * rs, v1 = acc[ai][bj][m][1] * rs;
;                     u32x4 o; o.x = cvt_pk_bf16(v0[0], v0[1]); o.y = cvt_pk_bf16(v0[2], v0[3]); o.z = cvt_pk_bf16(v1[0], v1[1]); o.w = cvt_pk_bf16(v1[2], v1[3]);
;                     bf16_t* dst;
;                     if (u.pn < 4) { const int colg = u.pn * BM + bj * HALF + wc * 32 + 8 * fq; dst = P + (size_t)(colg >> 9) * ((size_t)T * 512) + (size_t)row * 512 + (colg & 511); }
;                     else if (u.pn < 8) { const int colc = (u.pn - 4) * BM + bj * HALF + wc * 32 + 8 * fq; dst = P + PJ_UC + (size_t)row * 1024 + colc; }
;                     else { const int which = (u.pn - 8) >> 1, hd = ((u.pn - 8) & 1) * 4 + 2 * bj + (wc >> 1), dim = 32 * (wc & 1) + 8 * fq, bb = row >> 11, ll = row & 2047;
;                         dst = P + PJ_QKV + ((size_t)(((which * 4 + bb) * 8 + hd) * SEQ + ll)) * 64 + dim; }
;                     *(u32x4*)dst = o; } }
.LBB0_266:
	s_waitcnt lgkmcnt(0)
	v_add_f32_e32 v0, v172, v173
	v_fmamk_f32 v0, v0, 0x3a000000, v223
	v_mul_f32_e32 v22, 0x4f800000, v0
	v_cmp_gt_f32_e32 vcc, s11, v0
	global_store_dwordx4 v[24:25], v[18:21], off sc1
	s_nop 0
	v_cndmask_b32_e32 v0, v0, v22, vcc
	v_sqrt_f32_e32 v22, v0
	v_and_b32_e32 v20, 0x7ff, v146
	v_lshlrev_b64 v[18:19], 11, v[146:147]
	v_add_u32_e32 v23, -1, v22
	v_fma_f32 v27, -v23, v22, v0
	v_add_u32_e32 v26, 1, v22
	v_cmp_ge_f32_e64 s[42:43], 0, v27
	s_nop 1
	v_cndmask_b32_e64 v23, v22, v23, s[42:43]
	v_fma_f32 v22, -v26, v22, v0
	v_cmp_lt_f32_e64 s[42:43], 0, v22
	s_nop 1
	v_cndmask_b32_e64 v22, v23, v26, s[42:43]
	v_mul_f32_e32 v23, 0x37800000, v22
	v_cndmask_b32_e32 v22, v22, v23, vcc
	v_cmp_class_f32_e32 vcc, v0, v224
	s_nop 1
	v_cndmask_b32_e32 v0, v22, v0, vcc
	v_div_scale_f32 v22, s[2:3], v0, v0, 1.0
	v_rcp_f32_e32 v23, v22
	s_mov_b64 s[2:3], -1
	v_fma_f32 v26, -v22, v23, 1.0
	v_fmac_f32_e32 v23, v26, v23
	v_div_scale_f32 v26, vcc, 1.0, v0, 1.0
	v_mul_f32_e32 v27, v26, v23
	v_fma_f32 v28, -v22, v27, v26
	v_fmac_f32_e32 v27, v28, v23
	v_fma_f32 v22, -v22, v27, v26
	v_div_fmas_f32 v22, v22, v23, v27
	v_div_fixup_f32 v22, v22, v0, 1.0
	v_pk_mul_f32 v[16:17], v[16:17], v[22:23] op_sel_hi:[1,0]
	v_pk_mul_f32 v[24:25], v[12:13], v[22:23] op_sel_hi:[1,0]
	v_pk_mul_f32 v[12:13], v[10:11], v[22:23] op_sel_hi:[1,0]
	s_and_b64 vcc, exec, s[40:41]
	v_pk_mul_f32 v[14:15], v[14:15], v[22:23] op_sel_hi:[1,0]
	s_nop 0
	v_cvt_pk_bf16_f32 v10, v14, v15
	v_cvt_pk_bf16_f32 v11, v16, v17
	v_cvt_pk_bf16_f32 v12, v12, v13
	v_cvt_pk_bf16_f32 v13, v24, v25
	s_cbranch_vccnz .LBB0_272
	s_cmp_lt_u32 s34, 8
	s_cbranch_scc1 .LBB0_269
	s_lshl_b32 s2, s34, 2
	s_and_b32 s2, s2, 4
	s_lshl_b32 s3, s34, 1
	s_or_b32 s2, s2, s61
	s_and_b32 s3, s3, 0x3fffc
	v_add_lshl_u32 v0, v68, s3, 14
	s_lshl_b32 s2, s2, 11
	v_or3_b32 v14, v0, s2, v20
	v_ashrrev_i32_e32 v15, 31, v14
	v_lshlrev_b64 v[14:15], 7, v[14:15]
	v_lshl_add_u64 v[16:17], v[140:141], 0, v[14:15]
	s_mov_b64 s[2:3], 0

; __device__ __forceinline__ unsigned cvt_pk_bf16(float lo, float hi) { unsigned r; asm volatile("v_cvt_pk_bf16_f32 %0, %1, %2" : "=v"(r) : "v"(lo), "v"(hi)); return r; }
;     __device__ __forceinline__ void operator()(const f32x4 (&acc)[2][2][4][2], const Unit& u, int wr, int wc, int fr, int fq) const {
;     ...
;             for (int m = 0; m < 4; ++m) { const int row = row0 + ai * HALF + m * 16; const float rs = rsv[ai][m];
; #pragma unroll
;                 for (int bj = 0; bj < 2; ++bj) { const f32x4 v0 = acc[ai][bj][m][0] * rs, v1 = acc[ai][bj][m][1] * rs;
;                     u32x4 o; o.x = cvt_pk_bf16(v0[0], v0[1]); o.y = cvt_pk_bf16(v0[2], v0[3]); o.z = cvt_pk_bf16(v1[0], v1[1]); o.w = cvt_pk_bf16(v1[2], v1[3]);
;                     bf16_t* dst;
;                     if (u.pn < 4) { const int colg = u.pn * BM + bj * HALF + wc * 32 + 8 * fq; dst = P + (size_t)(colg >> 9) * ((size_t)T * 512) + (size_t)row * 512 + (colg & 511); }
;                     else if (u.pn < 8) { const int colc = (u.pn - 4) * BM + bj * HALF + wc * 32 + 8 * fq; dst = P + PJ_UC + (size_t)row * 1024 + colc; }
;                     else { const int which = (u.pn - 8) >> 1, hd = ((u.pn - 8) & 1) * 4 + 2 * bj + (wc >> 1), dim = 32 * (wc & 1) + 8 * fq, bb = row >> 11, ll = row & 2047;
;                         dst = P + PJ_QKV + ((size_t)(((which * 4 + bb) * 8 + hd) * SEQ + ll)) * 64 + dim; }
;                     *(u32x4*)dst = o; } }
.LBB0_274:
	v_mov_b32_e32 v23, v22
	global_store_dwordx4 v[16:17], v[10:13], off sc1
	v_pk_mul_f32 v[6:7], v[6:7], v[22:23]
	s_and_b64 vcc, exec, s[40:41]
	v_mov_b32_e32 v10, v22
	v_mov_b32_e32 v11, v22
	v_pk_mul_f32 v[8:9], v[8:9], v[10:11]
	v_pk_mul_f32 v[10:11], v[4:5], v[10:11]
	v_pk_mul_f32 v[4:5], v[2:3], v[22:23]
	s_mov_b64 s[2:3], -1
	v_cvt_pk_bf16_f32 v2, v6, v7
	v_cvt_pk_bf16_f32 v3, v8, v9
	v_cvt_pk_bf16_f32 v4, v4, v5
	v_cvt_pk_bf16_f32 v5, v10, v11
	s_cbranch_vccnz .LBB0_281
	s_cmp_lt_u32 s34, 8
	s_cbranch_scc1 .LBB0_277
	s_lshl_b32 s2, s34, 2
	s_and_b32 s2, s2, 4
	s_lshl_b32 s3, s34, 1
	s_or_b32 s2, s2, s61
	s_and_b32 s3, s3, 0x3fffc
	v_add_u32_e32 v0, s3, v68
	s_lshl_b32 s2, s2, 11
	v_lshl_or_b32 v0, v0, 14, s2
	s_movk_i32 s2, 0x1000
	v_or3_b32 v6, v0, v20, s2
	v_ashrrev_i32_e32 v7, 31, v6
	v_lshlrev_b64 v[6:7], 7, v[6:7]
	v_lshl_add_u64 v[6:7], v[140:141], 0, v[6:7]
	s_mov_b64 s[2:3], 0

;     __device__ __forceinline__ void operator()(const f32x4 (&acc)[2][2][4][2], const Unit& u, int wr, int wc, int fr, int fq) const {
;     ...
;                     if (u.pn < 4) { const int colg = u.pn * BM + bj * HALF + wc * 32 + 8 * fq; dst = P + (size_t)(colg >> 9) * ((size_t)T * 512) + (size_t)row * 512 + (colg & 511); }
;                     else if (u.pn < 8) { const int colc = (u.pn - 4) * BM + bj * HALF + wc * 32 + 8 * fq; dst = P + PJ_UC + (size_t)row * 1024 + colc; }
;                     else { const int which = (u.pn - 8) >> 1, hd = ((u.pn - 8) & 1) * 4 + 2 * bj + (wc >> 1), dim = 32 * (wc & 1) + 8 * fq, bb = row >> 11, ll = row & 2047;
;                         dst = P + PJ_QKV + ((size_t)(((which * 4 + bb) * 8 + hd) * SEQ + ll)) * 64 + dim; }
;                     *(u32x4*)dst = o; } }
.LBB0_280:
	s_andn2_b64 vcc, exec, s[38:39]
	s_mov_b64 s[2:3], -1
	global_store_dwordx4 v[6:7], v[2:5], off sc1
	s_cbranch_vccnz .LBB0_147
	s_branch .LBB0_283

;     __device__ __forceinline__ void operator()(const f32x4 (&acc)[2][2][4][2], const Unit& u, int wr, int wc, int fr, int fq) const {
;     ...
;                     if (u.pn < 4) { const int colg = u.pn * BM + bj * HALF + wc * 32 + 8 * fq; dst = P + (size_t)(colg >> 9) * ((size_t)T * 512) + (size_t)row * 512 + (colg & 511); }
;                     else if (u.pn < 8) { const int colc = (u.pn - 4) * BM + bj * HALF + wc * 32 + 8 * fq; dst = P + PJ_UC + (size_t)row * 1024 + colc; }
;                     else { const int which = (u.pn - 8) >> 1, hd = ((u.pn - 8) & 1) * 4 + 2 * bj + (wc >> 1), dim = 32 * (wc & 1) + 8 * fq, bb = row >> 11, ll = row & 2047;
;                         dst = P + PJ_QKV + ((size_t)(((which * 4 + bb) * 8 + hd) * SEQ + ll)) * 64 + dim; }
;                     *(u32x4*)dst = o; } }
.LBB0_282:
	s_ashr_i32 s2, s34, 1
	s_ashr_i32 s3, s2, 31
	s_lshl_b32 s12, s34, 8
	s_lshl_b64 s[2:3], s[2:3], 23
	s_add_u32 s2, s36, s2
	s_addc_u32 s3, s37, s3
	v_lshl_add_u64 v[6:7], s[2:3], 0, v[14:15]
	s_and_b32 s2, s12, 0x100
	v_or_b32_e32 v0, s2, v168
	v_lshlrev_b32_e32 v0, 1, v0
	v_lshl_add_u64 v[6:7], v[6:7], 0, v[0:1]
	s_mov_b64 s[2:3], 0x100
	v_lshl_add_u64 v[6:7], v[6:7], 0, s[2:3]
	s_andn2_b64 vcc, exec, s[38:39]
	s_mov_b64 s[2:3], -1
	global_store_dwordx4 v[6:7], v[2:5], off sc1
	s_cbranch_vccnz .LBB0_147

; __device__ __forceinline__ int tid_fresh() { int t = threadIdx.x; asm volatile("" : "+v"(t)); return t; }
; __device__ __forceinline__ int bid_fresh() { int t = blockIdx.x; asm volatile("" : "+s"(t)); return t; }
; __device__ __forceinline__ unsigned pk2(float lo, float hi) { const hf32x2 v = {lo, hi}; return __builtin_bit_cast(unsigned, __builtin_convertvector(v, hbf16x2)); }
; __device__ __forceinline__ void tconv_tile_w(const float* src, int N, int kb, int nb, bf16_t* dst, int ldd, float* tile, const float* kscale = nullptr) {
;     const int tid = tid_fresh();
;     f32x4 v[8];
; #pragma unroll
;     for (int p = 0; p < 8; ++p) { const int idx = tid + 512 * p, r = idx >> 6, c4 = idx & 63;
;         v[p] = __builtin_nontemporal_load((const f32x4*)(src + (size_t)(kb * 64 + r) * N + nb * 256 + c4 * 4)); }
;     if (kscale) {
; #pragma unroll
;         for (int p = 0; p < 8; ++p) v[p] = v[p] * kscale[kb * 64 + ((tid + 512 * p) >> 6)];
;     }
; #pragma unroll
;     for (int p = 0; p < 8; ++p) { const int idx = tid + 512 * p, r = idx >> 6, c4 = idx & 63;
;         float* t = tile + r * 257 + c4 * 4; t[0] = v[p][0]; t[1] = v[p][1]; t[2] = v[p][2]; t[3] = v[p][3]; }
;     __syncthreads();
; #pragma unroll
;     for (int q = 0; q < 4; ++q) { const int id = tid + 512 * q, n = id >> 3, k8 = id & 7;
;         const float* s = tile + (k8 * 8) * 257 + n;
;         u32x4 o; o.x = pk2(s[0], s[257]); o.y = pk2(s[2 * 257], s[3 * 257]); o.z = pk2(s[4 * 257], s[5 * 257]); o.w = pk2(s[6 * 257], s[7 * 257]);
;         *(u32x4*)(dst + (size_t)(nb * 256 + n) * ldd + kb * 64 + k8 * 8) = o; }
;     __syncthreads();
; }
; __global__ void __launch_bounds__(512, 2) hymba_fwd(Params p_unused) {
;     ...
;           { const int G = (int)gridDim.x, c = (int)bid_fresh(), nfull = 448 % G, nidle = (nfull == 0) ? 0 : G - nfull;
;             if (nidle > 0 && c >= nfull) { for (int r = c - nfull; r < 1024; r += nidle)
;                 tconv_tile_w(p->in[31] + (size_t)l * DFF * D, D, r / 8, r % 8, (bf16_t*)(ws + WS_WDN) + (size_t)l * D * DFF, DFF, (float*)shm); }
;             else if (nidle == 0) { for (int r = c; r < 1024; r += G) tconv_tile_w(p->in[31] + (size_t)l * DFF * D, D, r / 8, r % 8, (bf16_t*)(ws + WS_WDN) + (size_t)l * D * DFF, DFF, (float*)shm); } } }
.LBB0_294:
	s_ashr_i32 s8, s12, 31
	s_lshr_b32 s8, s8, 29
	s_add_i32 s8, s12, s8
	s_ashr_i32 s9, s8, 3
	s_lshl_b32 s18, s9, 11
	v_mov_b32_e32 v7, v222
	s_sub_i32 s20, s16, s18
	s_ashr_i32 s21, s20, 31
	v_add_u32_e32 v24, 0x800, v7
	s_lshl_b32 s8, s9, 6
	s_lshl_b64 s[20:21], s[20:21], 2
	v_ashrrev_i32_e32 v40, 6, v7
	v_ashrrev_i32_e32 v44, 6, v24
	s_add_u32 s20, s2, s20
	v_lshlrev_b32_e32 v0, 4, v7
	v_add_u32_e32 v4, s8, v40
	v_add_u32_e32 v24, s8, v44
	s_addc_u32 s21, s3, s21
	v_and_b32_e32 v0, 0x3f0, v0
	v_ashrrev_i32_e32 v5, 31, v4
	v_ashrrev_i32_e32 v25, 31, v24
	v_lshl_add_u64 v[2:3], s[20:21], 0, v[0:1]
	v_lshlrev_b64 v[4:5], 13, v[4:5]
	v_add_u32_e32 v6, 0x200, v7
	v_lshlrev_b64 v[24:25], 13, v[24:25]
	v_add_u32_e32 v28, 0xa00, v7
	v_lshl_add_u64 v[4:5], v[2:3], 0, v[4:5]
	v_ashrrev_i32_e32 v41, 6, v6
	v_lshl_add_u64 v[24:25], v[2:3], 0, v[24:25]
	v_ashrrev_i32_e32 v45, 6, v28
	global_load_dwordx4 v[8:11], v[4:5], off nt
	v_add_u32_e32 v28, s8, v45
	global_load_dwordx4 v[24:27], v[24:25], off nt
	v_add_u32_e32 v4, s8, v41
	v_ashrrev_i32_e32 v5, 31, v4
	v_ashrrev_i32_e32 v29, 31, v28
	v_lshlrev_b64 v[4:5], 13, v[4:5]
	v_lshlrev_b64 v[28:29], 13, v[28:29]
	v_lshl_add_u64 v[4:5], v[2:3], 0, v[4:5]
	v_lshl_add_u64 v[28:29], v[2:3], 0, v[28:29]
	global_load_dwordx4 v[12:15], v[4:5], off nt
	v_add_u32_e32 v32, 0xc00, v7
	global_load_dwordx4 v[28:31], v[28:29], off nt
	v_add_u32_e32 v5, 0x400, v7
	v_ashrrev_i32_e32 v42, 6, v5
	v_add_u32_e32 v4, 0x600, v7
	v_add_u32_e32 v16, s8, v42
	v_ashrrev_i32_e32 v43, 6, v4
	v_ashrrev_i32_e32 v17, 31, v16
	v_add_u32_e32 v20, s8, v43
	v_lshlrev_b64 v[16:17], 13, v[16:17]
	v_ashrrev_i32_e32 v21, 31, v20
	v_lshl_add_u64 v[16:17], v[2:3], 0, v[16:17]
	v_lshlrev_b64 v[20:21], 13, v[20:21]
	v_ashrrev_i32_e32 v46, 6, v32
	global_load_dwordx4 v[16:19], v[16:17], off nt
	v_lshl_add_u64 v[20:21], v[2:3], 0, v[20:21]
	v_add_u32_e32 v32, s8, v46
	global_load_dwordx4 v[20:23], v[20:21], off nt
	v_ashrrev_i32_e32 v33, 31, v32
	v_add_u32_e32 v36, 0xe00, v7
	v_lshlrev_b64 v[32:33], 13, v[32:33]
	v_ashrrev_i32_e32 v47, 6, v36
	v_lshl_add_u64 v[32:33], v[2:3], 0, v[32:33]
	v_add_u32_e32 v36, s8, v47
	global_load_dwordx4 v[32:35], v[32:33], off nt
	v_ashrrev_i32_e32 v37, 31, v36
	v_lshlrev_b64 v[36:37], 13, v[36:37]
	v_lshl_add_u64 v[2:3], v[2:3], 0, v[36:37]
	global_load_dwordx4 v[36:39], v[2:3], off nt
	v_add_u32_e32 v0, 0, v0
	v_mad_u64_u32 v[2:3], s[20:21], v40, s22, v[0:1]
	s_ashr_i32 s9, s8, 31
	s_lshl_b64 s[8:9], s[8:9], 1
	s_add_u32 s8, s13, s8
	s_addc_u32 s9, s14, s9
	s_add_i32 s12, s12, s66
	s_waitcnt vmcnt(7)
	ds_write2_b32 v2, v8, v9 offset1:1
	ds_write2_b32 v2, v10, v11 offset0:2 offset1:3
	v_mad_u64_u32 v[2:3], s[20:21], v41, s22, v[0:1]
	s_waitcnt vmcnt(5)
	ds_write2_b32 v2, v12, v13 offset1:1
	ds_write2_b32 v2, v14, v15 offset0:2 offset1:3
	v_mad_u64_u32 v[2:3], s[20:21], v42, s22, v[0:1]
	s_waitcnt vmcnt(3)
	ds_write2_b32 v2, v16, v17 offset1:1
	ds_write2_b32 v2, v18, v19 offset0:2 offset1:3
	v_mad_u64_u32 v[2:3], s[20:21], v43, s22, v[0:1]
	s_waitcnt vmcnt(2)
	ds_write2_b32 v2, v20, v21 offset1:1
	ds_write2_b32 v2, v22, v23 offset0:2 offset1:3
	v_mad_u64_u32 v[2:3], s[20:21], v44, s22, v[0:1]
	ds_write2_b32 v2, v24, v25 offset1:1
	ds_write2_b32 v2, v26, v27 offset0:2 offset1:3
	v_mad_u64_u32 v[2:3], s[20:21], v45, s22, v[0:1]
	ds_write2_b32 v2, v28, v29 offset1:1
	ds_write2_b32 v2, v30, v31 offset0:2 offset1:3
	v_mad_u64_u32 v[2:3], s[20:21], v46, s22, v[0:1]
	s_waitcnt vmcnt(1)
	ds_write2_b32 v2, v32, v33 offset1:1
	ds_write2_b32 v2, v34, v35 offset0:2 offset1:3
	v_mad_u64_u32 v[2:3], s[20:21], v47, s22, v[0:1]
	v_lshlrev_b32_e32 v0, 3, v7
	v_and_b32_e32 v0, 56, v0
	v_mad_u32_u24 v14, v0, s22, 0
	v_lshlrev_b32_e32 v0, 1, v0
	s_waitcnt vmcnt(0)
	ds_write2_b32 v2, v36, v37 offset1:1
	ds_write2_b32 v2, v38, v39 offset0:2 offset1:3
	v_lshl_add_u64 v[2:3], s[8:9], 0, v[0:1]
	v_ashrrev_i32_e32 v0, 3, v7
	v_lshl_add_u32 v7, v0, 2, v14
	s_waitcnt lgkmcnt(0)
	s_barrier
	ds_read_b32 v8, v7
	ds_read_b32 v9, v7 offset:1028
	v_subrev_u32_e32 v0, s18, v0
	v_add_u32_e32 v12, s16, v0
	v_ashrrev_i32_e32 v13, 31, v12
	v_lshlrev_b64 v[12:13], 14, v[12:13]
	s_waitcnt lgkmcnt(0)
	v_cvt_pk_bf16_f32 v8, v8, v9
	ds_read_b32 v9, v7 offset:2056
	ds_read_b32 v10, v7 offset:3084
	v_lshl_add_u64 v[12:13], v[2:3], 0, v[12:13]
	v_ashrrev_i32_e32 v0, 3, v6
	s_waitcnt lgkmcnt(0)
	v_cvt_pk_bf16_f32 v9, v9, v10
	ds_read_b32 v10, v7 offset:4112
	ds_read_b32 v11, v7 offset:5140
	s_waitcnt lgkmcnt(0)
	v_cvt_pk_bf16_f32 v10, v10, v11
	ds_read_b32 v11, v7 offset:6168
	ds_read_b32 v7, v7 offset:7196
	s_waitcnt lgkmcnt(0)
	v_cvt_pk_bf16_f32 v11, v11, v7
	global_store_dwordx4 v[12:13], v[8:11], off sc1
	s_nop 1
	v_lshl_add_u32 v9, v0, 2, v14
	ds_read_b32 v6, v9
	ds_read_b32 v7, v9 offset:1028
	v_subrev_u32_e32 v0, s18, v0
	s_waitcnt lgkmcnt(0)
	v_cvt_pk_bf16_f32 v6, v6, v7
	ds_read_b32 v7, v9 offset:2056
	ds_read_b32 v8, v9 offset:3084
	s_waitcnt lgkmcnt(0)
	v_cvt_pk_bf16_f32 v7, v7, v8
	ds_read_b32 v8, v9 offset:4112
	ds_read_b32 v10, v9 offset:5140
	s_waitcnt lgkmcnt(0)
	v_cvt_pk_bf16_f32 v8, v8, v10
	ds_read_b32 v10, v9 offset:6168
	ds_read_b32 v9, v9 offset:7196
	s_waitcnt lgkmcnt(0)
	v_cvt_pk_bf16_f32 v9, v10, v9
	v_add_u32_e32 v10, s16, v0
	v_ashrrev_i32_e32 v11, 31, v10
	v_lshlrev_b64 v[10:11], 14, v[10:11]
	v_lshl_add_u64 v[10:11], v[2:3], 0, v[10:11]
	v_ashrrev_i32_e32 v0, 3, v5
	global_store_dwordx4 v[10:11], v[6:9], off sc1
	v_lshl_add_u32 v5, v0, 2, v14
	ds_read_b32 v6, v5
	ds_read_b32 v7, v5 offset:1028
	v_subrev_u32_e32 v0, s18, v0
	v_add_u32_e32 v10, s16, v0
	v_ashrrev_i32_e32 v11, 31, v10
	v_lshlrev_b64 v[10:11], 14, v[10:11]
	s_waitcnt lgkmcnt(0)
	v_cvt_pk_bf16_f32 v6, v6, v7
	ds_read_b32 v7, v5 offset:2056
	ds_read_b32 v8, v5 offset:3084
	v_lshl_add_u64 v[10:11], v[2:3], 0, v[10:11]
	v_ashrrev_i32_e32 v0, 3, v4
	s_waitcnt lgkmcnt(0)
	v_cvt_pk_bf16_f32 v7, v7, v8
	ds_read_b32 v8, v5 offset:4112
	ds_read_b32 v9, v5 offset:5140
	s_waitcnt lgkmcnt(0)
	v_cvt_pk_bf16_f32 v8, v8, v9
	ds_read_b32 v9, v5 offset:6168
	ds_read_b32 v5, v5 offset:7196
	s_waitcnt lgkmcnt(0)
	v_cvt_pk_bf16_f32 v9, v9, v5
	global_store_dwordx4 v[10:11], v[6:9], off sc1
	s_nop 1
	v_lshl_add_u32 v7, v0, 2, v14
	ds_read_b32 v4, v7
	ds_read_b32 v5, v7 offset:1028
	v_subrev_u32_e32 v0, s18, v0
	s_waitcnt lgkmcnt(0)
	v_cvt_pk_bf16_f32 v4, v4, v5
	ds_read_b32 v5, v7 offset:2056
	ds_read_b32 v6, v7 offset:3084
	s_waitcnt lgkmcnt(0)
	v_cvt_pk_bf16_f32 v5, v5, v6
	ds_read_b32 v6, v7 offset:4112
	ds_read_b32 v8, v7 offset:5140
	s_waitcnt lgkmcnt(0)
	v_cvt_pk_bf16_f32 v6, v6, v8
	ds_read_b32 v8, v7 offset:6168
	ds_read_b32 v7, v7 offset:7196
	s_waitcnt lgkmcnt(0)
	v_cvt_pk_bf16_f32 v7, v8, v7
	v_add_u32_e32 v8, s16, v0
	v_ashrrev_i32_e32 v9, 31, v8
	v_lshlrev_b64 v[8:9], 14, v[8:9]
	s_add_i32 s16, s16, s17
	v_lshl_add_u64 v[2:3], v[2:3], 0, v[8:9]
	s_cmpk_gt_i32 s12, 0x3ff
	global_store_dwordx4 v[2:3], v[4:7], off sc1
	s_barrier
	s_cbranch_scc0 .LBB0_294

; __device__ __forceinline__ unsigned cvt_pk_bf16(float lo, float hi) { unsigned r; asm volatile("v_cvt_pk_bf16_f32 %0, %1, %2" : "=v"(r) : "v"(lo), "v"(hi)); return r; }
;     __device__ __forceinline__ void operator()(const f32x4 (&acc)[2][2][4][2], const Unit& u, int wr, int wc, int fr, int fq) const {
;     ...
; #pragma unroll
;         for (int ai = 0; ai < 2; ++ai)
; #pragma unroll
;             for (int m = 0; m < 4; ++m) { const int row = row0 + ai * HALF + m * 16; bf16_t* rowp = O + (size_t)row * ldc + col0;
;                 const float rs = rsv[ai][m];
; #pragma unroll
;                 for (int bj = 0; bj < 2; ++bj) { f32x4 v0 = acc[ai][bj][m][0] * rs, v1 = acc[ai][bj][m][1] * rs;
;                     if (ACT == 1) {
; #pragma unroll
;                         for (int e = 0; e < 4; ++e) { float a = fmaxf(v0[e], 0.f), b = fmaxf(v1[e], 0.f); v0[e] = a * a; v1[e] = b * b; } }
;                     u32x4 o; o.x = cvt_pk_bf16(v0[0], v0[1]); o.y = cvt_pk_bf16(v0[2], v0[3]); o.z = cvt_pk_bf16(v1[0], v1[1]); o.w = cvt_pk_bf16(v1[2], v1[3]);
;                     *(u32x4*)(rowp + bj * HALF) = o; } }
.LBB0_317:
	s_and_b64 vcc, exec, s[2:3]
	s_cbranch_vccz .LBB0_449
	v_or_b32_e32 v0, s58, v172
	v_add_u32_e32 v130, s16, v0
	v_ashrrev_i32_e32 v131, 31, v130
	v_or_b32_e32 v0, 0xfffff200, v174
	v_or_b32_e32 v132, 16, v130
	v_or_b32_e32 v150, 32, v130
	v_or_b32_e32 v152, 48, v130
	v_lshl_add_u32 v0, s46, 8, v0
	v_lshlrev_b64 v[130:131], 13, v[130:131]
	v_lshl_add_u64 v[130:131], s[34:35], 0, v[130:131]
	v_lshlrev_b64 v[154:155], 1, v[0:1]
	v_ashrrev_i32_e32 v133, 31, v132
	v_lshl_add_u64 v[130:131], v[130:131], 0, v[154:155]
	v_cvt_pk_bf16_f32 v126, v126, v127
	v_cvt_pk_bf16_f32 v127, v128, v129
	v_cvt_pk_bf16_f32 v128, v122, v123
	v_cvt_pk_bf16_f32 v129, v124, v125
	global_store_dwordx4 v[130:131], v[126:129], off sc1
	v_cvt_pk_bf16_f32 v114, v114, v115
	v_cvt_pk_bf16_f32 v115, v116, v117
	v_cvt_pk_bf16_f32 v116, v106, v107
	v_lshlrev_b64 v[106:107], 13, v[132:133]
	v_lshl_add_u64 v[106:107], s[34:35], 0, v[106:107]
	v_ashrrev_i32_e32 v151, 31, v150
	v_cvt_pk_bf16_f32 v117, v108, v109
	global_store_dwordx4 v[130:131], v[114:117], off offset:256 sc1
	v_ashrrev_i32_e32 v153, 31, v152
	s_mov_b64 s[2:3], 0x100000
	v_lshl_add_u64 v[114:115], v[106:107], 0, v[154:155]
	v_cvt_pk_bf16_f32 v106, v118, v119
	v_cvt_pk_bf16_f32 v107, v120, v121
	v_cvt_pk_bf16_f32 v108, v110, v111
	v_cvt_pk_bf16_f32 v109, v112, v113
	global_store_dwordx4 v[114:115], v[106:109], off sc1
	v_cvt_pk_bf16_f32 v98, v98, v99
	v_cvt_pk_bf16_f32 v99, v100, v101
	v_cvt_pk_bf16_f32 v100, v90, v91
	v_lshlrev_b64 v[90:91], 13, v[150:151]
	v_lshl_add_u64 v[90:91], s[34:35], 0, v[90:91]
	v_cvt_pk_bf16_f32 v101, v92, v93
	global_store_dwordx4 v[114:115], v[98:101], off offset:256 sc1
	s_nop 1
	v_lshl_add_u64 v[98:99], v[90:91], 0, v[154:155]
	v_cvt_pk_bf16_f32 v90, v102, v103
	v_cvt_pk_bf16_f32 v91, v104, v105
	v_cvt_pk_bf16_f32 v92, v94, v95
	v_cvt_pk_bf16_f32 v93, v96, v97
	global_store_dwordx4 v[98:99], v[90:93], off sc1
	v_cvt_pk_bf16_f32 v82, v82, v83
	v_cvt_pk_bf16_f32 v83, v84, v85
	v_cvt_pk_bf16_f32 v84, v74, v75
	v_lshlrev_b64 v[74:75], 13, v[152:153]
	v_lshl_add_u64 v[74:75], s[34:35], 0, v[74:75]
	v_cvt_pk_bf16_f32 v85, v76, v77
	global_store_dwordx4 v[98:99], v[82:85], off offset:256 sc1
	s_nop 1
	v_lshl_add_u64 v[82:83], v[74:75], 0, v[154:155]
	v_cvt_pk_bf16_f32 v74, v86, v87
	v_cvt_pk_bf16_f32 v75, v88, v89
	v_cvt_pk_bf16_f32 v76, v78, v79
	v_cvt_pk_bf16_f32 v77, v80, v81
	global_store_dwordx4 v[82:83], v[74:77], off sc1
	v_cvt_pk_bf16_f32 v70, v70, v71
	v_cvt_pk_bf16_f32 v71, v72, v73
	v_cvt_pk_bf16_f32 v72, v66, v67
	v_lshl_add_u64 v[66:67], v[130:131], 0, s[2:3]
	s_mov_b32 s2, 0x100000
	v_cvt_pk_bf16_f32 v73, v68, v69
	global_store_dwordx4 v[82:83], v[70:73], off offset:256 sc1
	v_cvt_pk_bf16_f32 v62, v62, v63
	v_cvt_pk_bf16_f32 v63, v64, v65
	v_cvt_pk_bf16_f32 v64, v58, v59
	v_add_co_u32_e32 v58, vcc, s2, v130
	v_cvt_pk_bf16_f32 v65, v60, v61
	s_mov_b64 s[2:3], 0x120000
	s_nop 0
	v_addc_co_u32_e32 v59, vcc, 0, v131, vcc
	global_store_dwordx4 v[58:59], v[62:65], off sc1
	v_cvt_pk_bf16_f32 v50, v50, v51
	v_cvt_pk_bf16_f32 v51, v52, v53
	v_cvt_pk_bf16_f32 v52, v42, v43
	v_cvt_pk_bf16_f32 v53, v44, v45
	global_store_dwordx4 v[66:67], v[50:53], off offset:256 sc1
	v_cvt_pk_bf16_f32 v42, v54, v55
	v_cvt_pk_bf16_f32 v43, v56, v57
	v_cvt_pk_bf16_f32 v44, v46, v47
	v_cvt_pk_bf16_f32 v45, v48, v49
	s_nop 1
	v_lshl_add_u64 v[50:51], v[130:131], 0, s[2:3]
	s_mov_b32 s2, 0x120000
	v_add_co_u32_e32 v46, vcc, s2, v130
	s_mov_b64 s[2:3], 0x140000
	s_nop 0
	v_addc_co_u32_e32 v47, vcc, 0, v131, vcc
	global_store_dwordx4 v[46:47], v[42:45], off sc1
	v_cvt_pk_bf16_f32 v34, v34, v35
	v_cvt_pk_bf16_f32 v35, v36, v37
	v_cvt_pk_bf16_f32 v36, v26, v27
	v_cvt_pk_bf16_f32 v37, v28, v29
	global_store_dwordx4 v[50:51], v[34:37], off offset:256 sc1
	v_cvt_pk_bf16_f32 v26, v38, v39
	v_cvt_pk_bf16_f32 v27, v40, v41
	v_cvt_pk_bf16_f32 v28, v30, v31
	v_cvt_pk_bf16_f32 v29, v32, v33
	s_nop 1
	v_lshl_add_u64 v[34:35], v[130:131], 0, s[2:3]
	s_mov_b32 s2, 0x140000
	v_add_co_u32_e32 v30, vcc, s2, v130
	s_mov_b64 s[2:3], 0x160000
	s_nop 0
	v_addc_co_u32_e32 v31, vcc, 0, v131, vcc
	global_store_dwordx4 v[30:31], v[26:29], off sc1
	v_cvt_pk_bf16_f32 v18, v18, v19
	v_cvt_pk_bf16_f32 v19, v20, v21
	v_cvt_pk_bf16_f32 v20, v10, v11
	v_cvt_pk_bf16_f32 v21, v12, v13
	global_store_dwordx4 v[34:35], v[18:21], off offset:256 sc1
	v_cvt_pk_bf16_f32 v10, v22, v23
	v_cvt_pk_bf16_f32 v11, v24, v25
	v_cvt_pk_bf16_f32 v12, v14, v15
	v_cvt_pk_bf16_f32 v13, v16, v17
	s_nop 1
	v_lshl_add_u64 v[18:19], v[130:131], 0, s[2:3]
	s_mov_b32 s2, 0x160000
	v_add_co_u32_e32 v14, vcc, s2, v130
	s_nop 1
	v_addc_co_u32_e32 v15, vcc, 0, v131, vcc
	global_store_dwordx4 v[14:15], v[10:13], off sc1
	v_cvt_pk_bf16_f32 v6, v6, v7
	v_cvt_pk_bf16_f32 v7, v8, v9
	v_cvt_pk_bf16_f32 v8, v2, v3
	v_cvt_pk_bf16_f32 v9, v4, v5
	global_store_dwordx4 v[18:19], v[6:9], off offset:256 sc1
	s_andn2_b64 vcc, exec, s[52:53]
	s_mov_b64 s[2:3], -1
	s_cbranch_vccnz .LBB0_307
	s_branch .LBB0_450

; __device__ __forceinline__ unsigned cvt_pk_bf16(float lo, float hi) { unsigned r; asm volatile("v_cvt_pk_bf16_f32 %0, %1, %2" : "=v"(r) : "v"(lo), "v"(hi)); return r; }
;     __device__ __forceinline__ void operator()(const f32x4 (&acc)[2][2][4][2], const Unit& u, int wr, int wc, int fr, int fq) const {
;     ...
;                     rsv[ai][m] = 1.0f / sqrtf(t * (1.0f / D) + EPS); }
;         }
; #pragma unroll
;         for (int ai = 0; ai < 2; ++ai)
; #pragma unroll
;             for (int m = 0; m < 4; ++m) { const int row = row0 + ai * HALF + m * 16; const float rs = rsv[ai][m];
; #pragma unroll
;                 for (int bj = 0; bj < 2; ++bj) { const f32x4 v0 = acc[ai][bj][m][0] * rs, v1 = acc[ai][bj][m][1] * rs;
;                     u32x4 o; o.x = cvt_pk_bf16(v0[0], v0[1]); o.y = cvt_pk_bf16(v0[2], v0[3]); o.z = cvt_pk_bf16(v1[0], v1[1]); o.w = cvt_pk_bf16(v1[2], v1[3]);
;                     bf16_t* dst;
;                     if (u.pn < 4) { const int colg = u.pn * BM + bj * HALF + wc * 32 + 8 * fq; dst = P + (size_t)(colg >> 9) * ((size_t)T * 512) + (size_t)row * 512 + (colg & 511); }
;                     else if (u.pn < 8) { const int colc = (u.pn - 4) * BM + bj * HALF + wc * 32 + 8 * fq; dst = P + PJ_UC + (size_t)row * 1024 + colc; }
;                     else { const int which = (u.pn - 8) >> 1, hd = ((u.pn - 8) & 1) * 4 + 2 * bj + (wc >> 1), dim = 32 * (wc & 1) + 8 * fq, bb = row >> 11, ll = row & 2047;
;                         dst = P + PJ_QKV + ((size_t)(((which * 4 + bb) * 8 + hd) * SEQ + ll)) * 64 + dim; }
;                     *(u32x4*)dst = o; } }
.LBB0_328:
	v_mov_b32_e32 v167, v166
	global_store_dwordx4 v[170:171], v[130:133], off sc1
	v_cndmask_b32_e64 v0, 0, 1, s[2:3]
	v_pk_mul_f32 v[170:171], v[114:115], v[166:167]
	v_mov_b32_e32 v130, v166
	v_mov_b32_e32 v131, v166
	v_pk_mul_f32 v[132:133], v[116:117], v[130:131]
	v_cmp_ne_u32_e64 s[38:39], 1, v0
	s_andn2_b64 vcc, exec, s[2:3]
	s_mov_b64 s[2:3], -1
	v_pk_mul_f32 v[180:181], v[108:109], v[130:131]
	v_pk_mul_f32 v[166:167], v[106:107], v[166:167]
	v_cvt_pk_bf16_f32 v130, v170, v171
	v_cvt_pk_bf16_f32 v131, v132, v133
	s_nop 0
	v_cvt_pk_bf16_f32 v132, v166, v167
	v_cvt_pk_bf16_f32 v133, v180, v181
	s_cbranch_vccnz .LBB0_334
	s_cmp_lt_u32 s46, 8
	s_cbranch_scc1 .LBB0_331
	s_lshl_b32 s2, s46, 2
	s_lshl_b32 s3, s46, 1
	s_and_b32 s2, s2, 4
	s_and_b32 s3, s3, 0x3fffc
	s_or_b32 s2, s2, s61
	s_add_i32 s3, s17, s3
	s_lshl_b32 s3, s3, 14
	s_lshl_b32 s2, s2, 11
	s_or_b32 s2, s2, s3
	v_or_b32_e32 v0, s2, v200
	v_or_b32_e32 v166, 0x1000, v0
	v_ashrrev_i32_e32 v167, 31, v166
	v_lshlrev_b64 v[166:167], 7, v[166:167]
	v_lshl_add_u64 v[170:171], v[144:145], 0, v[166:167]
	s_mov_b64 s[2:3], 0

; __device__ __forceinline__ unsigned cvt_pk_bf16(float lo, float hi) { unsigned r; asm volatile("v_cvt_pk_bf16_f32 %0, %1, %2" : "=v"(r) : "v"(lo), "v"(hi)); return r; }
;     __device__ __forceinline__ void operator()(const f32x4 (&acc)[2][2][4][2], const Unit& u, int wr, int wc, int fr, int fq) const {
;     ...
;                 for (int m = 0; m < 4; ++m) { float t = ((p0[ai][m][0] + p0[ai][m][1]) + (p0[ai][m][2] + p0[ai][m][3])) + ((p1[ai][m][0] + p1[ai][m][1]) + (p1[ai][m][2] + p1[ai][m][3]));
;                     t += __shfl_xor(t, 16); t += __shfl_xor(t, 32);
;                     rsv[ai][m] = 1.0f / sqrtf(t * (1.0f / D) + EPS); }
;         }
; #pragma unroll
;         for (int ai = 0; ai < 2; ++ai)
; #pragma unroll
;             for (int m = 0; m < 4; ++m) { const int row = row0 + ai * HALF + m * 16; const float rs = rsv[ai][m];
; #pragma unroll
;                 for (int bj = 0; bj < 2; ++bj) { const f32x4 v0 = acc[ai][bj][m][0] * rs, v1 = acc[ai][bj][m][1] * rs;
;                     u32x4 o; o.x = cvt_pk_bf16(v0[0], v0[1]); o.y = cvt_pk_bf16(v0[2], v0[3]); o.z = cvt_pk_bf16(v1[0], v1[1]); o.w = cvt_pk_bf16(v1[2], v1[3]);
;                     bf16_t* dst;
;                     if (u.pn < 4) { const int colg = u.pn * BM + bj * HALF + wc * 32 + 8 * fq; dst = P + (size_t)(colg >> 9) * ((size_t)T * 512) + (size_t)row * 512 + (colg & 511); }
;                     else if (u.pn < 8) { const int colc = (u.pn - 4) * BM + bj * HALF + wc * 32 + 8 * fq; dst = P + PJ_UC + (size_t)row * 1024 + colc; }
;                     else { const int which = (u.pn - 8) >> 1, hd = ((u.pn - 8) & 1) * 4 + 2 * bj + (wc >> 1), dim = 32 * (wc & 1) + 8 * fq, bb = row >> 11, ll = row & 2047;
;                         dst = P + PJ_QKV + ((size_t)(((which * 4 + bb) * 8 + hd) * SEQ + ll)) * 64 + dim; }
;                     *(u32x4*)dst = o; } }
.LBB0_336:
	s_waitcnt lgkmcnt(6)
	v_add_f32_e32 v0, v198, v199
	v_fmamk_f32 v0, v0, 0x3a000000, v223
	v_mul_f32_e32 v164, 0x4f800000, v0
	v_cmp_gt_f32_e32 vcc, s11, v0
	global_store_dwordx4 v[170:171], v[130:133], off sc1
	v_and_b32_e32 v170, 0x7df, v162
	v_cndmask_b32_e32 v0, v0, v164, vcc
	v_sqrt_f32_e32 v164, v0
	s_nop 0
	v_add_u32_e32 v165, -1, v164
	v_fma_f32 v167, -v165, v164, v0
	v_add_u32_e32 v166, 1, v164
	v_cmp_ge_f32_e64 s[40:41], 0, v167
	s_nop 1
	v_cndmask_b32_e64 v165, v164, v165, s[40:41]
	v_fma_f32 v164, -v166, v164, v0
	v_cmp_lt_f32_e64 s[40:41], 0, v164
	s_nop 1
	v_cndmask_b32_e64 v164, v165, v166, s[40:41]
	v_mul_f32_e32 v165, 0x37800000, v164
	v_cndmask_b32_e32 v164, v164, v165, vcc
	v_cmp_class_f32_e32 vcc, v0, v224
	s_nop 1
	v_cndmask_b32_e32 v0, v164, v0, vcc
	v_div_scale_f32 v164, s[2:3], v0, v0, 1.0
	v_rcp_f32_e32 v165, v164
	s_mov_b64 s[2:3], -1
	v_fma_f32 v166, -v164, v165, 1.0
	v_fmac_f32_e32 v165, v166, v165
	v_div_scale_f32 v166, vcc, 1.0, v0, 1.0
	v_mul_f32_e32 v167, v166, v165
	v_fma_f32 v168, -v164, v167, v166
	v_fmac_f32_e32 v167, v168, v165
	v_fma_f32 v164, -v164, v167, v166
	v_div_fmas_f32 v164, v164, v165, v167
	v_div_fixup_f32 v166, v164, v0, 1.0
	v_lshlrev_b64 v[164:165], 11, v[162:163]
	v_pk_mul_f32 v[132:133], v[120:121], v[166:167] op_sel_hi:[1,0]
	v_pk_mul_f32 v[130:131], v[118:119], v[166:167] op_sel_hi:[1,0]
	v_pk_mul_f32 v[168:169], v[112:113], v[166:167] op_sel_hi:[1,0]
	s_and_b64 vcc, exec, s[38:39]
	v_pk_mul_f32 v[180:181], v[110:111], v[166:167] op_sel_hi:[1,0]
	v_cvt_pk_bf16_f32 v130, v130, v131
	v_cvt_pk_bf16_f32 v131, v132, v133
	s_nop 0
	v_cvt_pk_bf16_f32 v132, v180, v181
	v_cvt_pk_bf16_f32 v133, v168, v169
	s_cbranch_vccnz .LBB0_342
	s_cmp_lt_u32 s46, 8
	s_cbranch_scc1 .LBB0_339
	s_lshl_b32 s2, s46, 2
	s_lshl_b32 s3, s46, 1
	s_and_b32 s2, s2, 4
	s_and_b32 s3, s3, 0x3fffc
	s_or_b32 s2, s2, s61
	s_add_i32 s3, s17, s3
	s_lshl_b32 s3, s3, 14
	s_lshl_b32 s2, s2, 11
	s_or_b32 s2, s3, s2
	v_or_b32_e32 v168, s2, v170
	v_ashrrev_i32_e32 v169, 31, v168
	v_lshlrev_b64 v[168:169], 7, v[168:169]
	v_lshl_add_u64 v[168:169], v[144:145], 0, v[168:169]
	s_mov_b64 s[2:3], 0

; __device__ __forceinline__ unsigned cvt_pk_bf16(float lo, float hi) { unsigned r; asm volatile("v_cvt_pk_bf16_f32 %0, %1, %2" : "=v"(r) : "v"(lo), "v"(hi)); return r; }
;     __device__ __forceinline__ void operator()(const f32x4 (&acc)[2][2][4][2], const Unit& u, int wr, int wc, int fr, int fq) const {
;     ...
;             for (int m = 0; m < 4; ++m) { const int row = row0 + ai * HALF + m * 16; const float rs = rsv[ai][m];
; #pragma unroll
;                 for (int bj = 0; bj < 2; ++bj) { const f32x4 v0 = acc[ai][bj][m][0] * rs, v1 = acc[ai][bj][m][1] * rs;
;                     u32x4 o; o.x = cvt_pk_bf16(v0[0], v0[1]); o.y = cvt_pk_bf16(v0[2], v0[3]); o.z = cvt_pk_bf16(v1[0], v1[1]); o.w = cvt_pk_bf16(v1[2], v1[3]);
;                     bf16_t* dst;
;                     if (u.pn < 4) { const int colg = u.pn * BM + bj * HALF + wc * 32 + 8 * fq; dst = P + (size_t)(colg >> 9) * ((size_t)T * 512) + (size_t)row * 512 + (colg & 511); }
;                     else if (u.pn < 8) { const int colc = (u.pn - 4) * BM + bj * HALF + wc * 32 + 8 * fq; dst = P + PJ_UC + (size_t)row * 1024 + colc; }
;                     else { const int which = (u.pn - 8) >> 1, hd = ((u.pn - 8) & 1) * 4 + 2 * bj + (wc >> 1), dim = 32 * (wc & 1) + 8 * fq, bb = row >> 11, ll = row & 2047;
;                         dst = P + PJ_QKV + ((size_t)(((which * 4 + bb) * 8 + hd) * SEQ + ll)) * 64 + dim; }
;                     *(u32x4*)dst = o; } }
.LBB0_344:
	v_mov_b32_e32 v167, v166
	global_store_dwordx4 v[168:169], v[130:133], off sc1
	v_pk_mul_f32 v[168:169], v[98:99], v[166:167]
	s_and_b64 vcc, exec, s[38:39]
	v_mov_b32_e32 v130, v166
	v_mov_b32_e32 v131, v166
	v_pk_mul_f32 v[132:133], v[100:101], v[130:131]
	v_pk_mul_f32 v[166:167], v[90:91], v[166:167]
	s_mov_b64 s[2:3], -1
	v_pk_mul_f32 v[180:181], v[92:93], v[130:131]
	v_cvt_pk_bf16_f32 v130, v168, v169
	v_cvt_pk_bf16_f32 v131, v132, v133
	v_cvt_pk_bf16_f32 v132, v166, v167
	s_nop 0
	v_cvt_pk_bf16_f32 v133, v180, v181
	s_cbranch_vccnz .LBB0_350
	s_cmp_lt_u32 s46, 8
	s_cbranch_scc1 .LBB0_347
	s_lshl_b32 s2, s46, 2
	s_lshl_b32 s3, s46, 1
	s_and_b32 s2, s2, 4
	s_and_b32 s3, s3, 0x3fffc
	s_or_b32 s2, s2, s61
	s_add_i32 s3, s17, s3
	s_lshl_b32 s3, s3, 14
	s_lshl_b32 s2, s2, 11
	s_or_b32 s2, s2, s3
	v_or_b32_e32 v0, s2, v170
	v_or_b32_e32 v166, 0x1000, v0
	v_ashrrev_i32_e32 v167, 31, v166
	v_lshlrev_b64 v[166:167], 7, v[166:167]
	v_lshl_add_u64 v[166:167], v[144:145], 0, v[166:167]
	s_mov_b64 s[2:3], 0

; __device__ __forceinline__ unsigned cvt_pk_bf16(float lo, float hi) { unsigned r; asm volatile("v_cvt_pk_bf16_f32 %0, %1, %2" : "=v"(r) : "v"(lo), "v"(hi)); return r; }
;     __device__ __forceinline__ void operator()(const f32x4 (&acc)[2][2][4][2], const Unit& u, int wr, int wc, int fr, int fq) const {
;     ...
;                 for (int m = 0; m < 4; ++m) { float t = ((p0[ai][m][0] + p0[ai][m][1]) + (p0[ai][m][2] + p0[ai][m][3])) + ((p1[ai][m][0] + p1[ai][m][1]) + (p1[ai][m][2] + p1[ai][m][3]));
;                     t += __shfl_xor(t, 16); t += __shfl_xor(t, 32);
;                     rsv[ai][m] = 1.0f / sqrtf(t * (1.0f / D) + EPS); }
;         }
; #pragma unroll
;         for (int ai = 0; ai < 2; ++ai)
; #pragma unroll
;             for (int m = 0; m < 4; ++m) { const int row = row0 + ai * HALF + m * 16; const float rs = rsv[ai][m];
; #pragma unroll
;                 for (int bj = 0; bj < 2; ++bj) { const f32x4 v0 = acc[ai][bj][m][0] * rs, v1 = acc[ai][bj][m][1] * rs;
;                     u32x4 o; o.x = cvt_pk_bf16(v0[0], v0[1]); o.y = cvt_pk_bf16(v0[2], v0[3]); o.z = cvt_pk_bf16(v1[0], v1[1]); o.w = cvt_pk_bf16(v1[2], v1[3]);
;                     bf16_t* dst;
;                     if (u.pn < 4) { const int colg = u.pn * BM + bj * HALF + wc * 32 + 8 * fq; dst = P + (size_t)(colg >> 9) * ((size_t)T * 512) + (size_t)row * 512 + (colg & 511); }
;                     else if (u.pn < 8) { const int colc = (u.pn - 4) * BM + bj * HALF + wc * 32 + 8 * fq; dst = P + PJ_UC + (size_t)row * 1024 + colc; }
;                     else { const int which = (u.pn - 8) >> 1, hd = ((u.pn - 8) & 1) * 4 + 2 * bj + (wc >> 1), dim = 32 * (wc & 1) + 8 * fq, bb = row >> 11, ll = row & 2047;
;                         dst = P + PJ_QKV + ((size_t)(((which * 4 + bb) * 8 + hd) * SEQ + ll)) * 64 + dim; }
;                     *(u32x4*)dst = o; } }
.LBB0_352:
	s_waitcnt lgkmcnt(5)
	v_add_f32_e32 v0, v196, v197
	v_fmamk_f32 v0, v0, 0x3a000000, v223
	v_mul_f32_e32 v162, 0x4f800000, v0
	v_cmp_gt_f32_e32 vcc, s11, v0
	global_store_dwordx4 v[166:167], v[130:133], off sc1
	s_nop 0
	v_cndmask_b32_e32 v0, v0, v162, vcc
	v_sqrt_f32_e32 v162, v0
	s_nop 0
	v_add_u32_e32 v163, -1, v162
	v_fma_f32 v165, -v163, v162, v0
	v_add_u32_e32 v164, 1, v162
	v_cmp_ge_f32_e64 s[40:41], 0, v165
	s_nop 1
	v_cndmask_b32_e64 v163, v162, v163, s[40:41]
	v_fma_f32 v162, -v164, v162, v0
	v_cmp_lt_f32_e64 s[40:41], 0, v162
	s_nop 1
	v_cndmask_b32_e64 v162, v163, v164, s[40:41]
	v_mul_f32_e32 v163, 0x37800000, v162
	v_cndmask_b32_e32 v162, v162, v163, vcc
	v_cmp_class_f32_e32 vcc, v0, v224
	s_nop 1
	v_cndmask_b32_e32 v0, v162, v0, vcc
	v_div_scale_f32 v162, s[2:3], v0, v0, 1.0
	v_rcp_f32_e32 v163, v162
	s_mov_b64 s[2:3], -1
	v_fma_f32 v164, -v162, v163, 1.0
	v_fmac_f32_e32 v163, v164, v163
	v_div_scale_f32 v164, vcc, 1.0, v0, 1.0
	v_mul_f32_e32 v165, v164, v163
	v_fma_f32 v168, -v162, v165, v164
	v_fmac_f32_e32 v165, v168, v163
	v_fma_f32 v162, -v162, v165, v164
	v_div_fmas_f32 v162, v162, v163, v165
	v_div_fixup_f32 v164, v162, v0, 1.0
	v_and_b32_e32 v168, 0x7ef, v160
	v_lshlrev_b64 v[162:163], 11, v[160:161]
	v_pk_mul_f32 v[132:133], v[104:105], v[164:165] op_sel_hi:[1,0]
	v_pk_mul_f32 v[130:131], v[102:103], v[164:165] op_sel_hi:[1,0]
	v_pk_mul_f32 v[166:167], v[96:97], v[164:165] op_sel_hi:[1,0]
	s_and_b64 vcc, exec, s[38:39]
	v_pk_mul_f32 v[170:171], v[94:95], v[164:165] op_sel_hi:[1,0]
	v_cvt_pk_bf16_f32 v130, v130, v131
	v_cvt_pk_bf16_f32 v131, v132, v133
	s_nop 0
	v_cvt_pk_bf16_f32 v132, v170, v171
	v_cvt_pk_bf16_f32 v133, v166, v167
	s_cbranch_vccnz .LBB0_358
	s_cmp_lt_u32 s46, 8
	s_cbranch_scc1 .LBB0_355
	s_lshl_b32 s2, s46, 2
	s_lshl_b32 s3, s46, 1
	s_and_b32 s2, s2, 4
	s_and_b32 s3, s3, 0x3fffc
	s_or_b32 s2, s2, s61
	s_add_i32 s3, s17, s3
	s_lshl_b32 s3, s3, 14
	s_lshl_b32 s2, s2, 11
	s_or_b32 s2, s3, s2
	v_or_b32_e32 v166, s2, v168
	v_ashrrev_i32_e32 v167, 31, v166
	v_lshlrev_b64 v[166:167], 7, v[166:167]
	v_lshl_add_u64 v[166:167], v[144:145], 0, v[166:167]
	s_mov_b64 s[2:3], 0

; __device__ __forceinline__ unsigned cvt_pk_bf16(float lo, float hi) { unsigned r; asm volatile("v_cvt_pk_bf16_f32 %0, %1, %2" : "=v"(r) : "v"(lo), "v"(hi)); return r; }
;     __device__ __forceinline__ void operator()(const f32x4 (&acc)[2][2][4][2], const Unit& u, int wr, int wc, int fr, int fq) const {
;     ...
;             for (int m = 0; m < 4; ++m) { const int row = row0 + ai * HALF + m * 16; const float rs = rsv[ai][m];
; #pragma unroll
;                 for (int bj = 0; bj < 2; ++bj) { const f32x4 v0 = acc[ai][bj][m][0] * rs, v1 = acc[ai][bj][m][1] * rs;
;                     u32x4 o; o.x = cvt_pk_bf16(v0[0], v0[1]); o.y = cvt_pk_bf16(v0[2], v0[3]); o.z = cvt_pk_bf16(v1[0], v1[1]); o.w = cvt_pk_bf16(v1[2], v1[3]);
;                     bf16_t* dst;
;                     if (u.pn < 4) { const int colg = u.pn * BM + bj * HALF + wc * 32 + 8 * fq; dst = P + (size_t)(colg >> 9) * ((size_t)T * 512) + (size_t)row * 512 + (colg & 511); }
;                     else if (u.pn < 8) { const int colc = (u.pn - 4) * BM + bj * HALF + wc * 32 + 8 * fq; dst = P + PJ_UC + (size_t)row * 1024 + colc; }
;                     else { const int which = (u.pn - 8) >> 1, hd = ((u.pn - 8) & 1) * 4 + 2 * bj + (wc >> 1), dim = 32 * (wc & 1) + 8 * fq, bb = row >> 11, ll = row & 2047;
;                         dst = P + PJ_QKV + ((size_t)(((which * 4 + bb) * 8 + hd) * SEQ + ll)) * 64 + dim; }
;                     *(u32x4*)dst = o; } }
.LBB0_360:
	v_mov_b32_e32 v165, v164
	global_store_dwordx4 v[166:167], v[130:133], off sc1
	v_pk_mul_f32 v[166:167], v[82:83], v[164:165]
	s_and_b64 vcc, exec, s[38:39]
	v_mov_b32_e32 v130, v164
	v_mov_b32_e32 v131, v164
	v_pk_mul_f32 v[132:133], v[84:85], v[130:131]
	v_pk_mul_f32 v[164:165], v[74:75], v[164:165]
	s_mov_b64 s[2:3], -1
	v_pk_mul_f32 v[170:171], v[76:77], v[130:131]
	v_cvt_pk_bf16_f32 v130, v166, v167
	v_cvt_pk_bf16_f32 v131, v132, v133
	v_cvt_pk_bf16_f32 v132, v164, v165
	s_nop 0
	v_cvt_pk_bf16_f32 v133, v170, v171
	s_cbranch_vccnz .LBB0_366
	s_cmp_lt_u32 s46, 8
	s_cbranch_scc1 .LBB0_363
	s_lshl_b32 s2, s46, 2
	s_lshl_b32 s3, s46, 1
	s_and_b32 s2, s2, 4
	s_and_b32 s3, s3, 0x3fffc
	s_or_b32 s2, s2, s61
	s_add_i32 s3, s17, s3
	s_lshl_b32 s3, s3, 14
	s_lshl_b32 s2, s2, 11
	s_or_b32 s2, s2, s3
	v_or_b32_e32 v0, s2, v168
	v_or_b32_e32 v164, 0x1000, v0
	v_ashrrev_i32_e32 v165, 31, v164
	v_lshlrev_b64 v[164:165], 7, v[164:165]
	v_lshl_add_u64 v[164:165], v[144:145], 0, v[164:165]
	s_mov_b64 s[2:3], 0

; __device__ __forceinline__ unsigned cvt_pk_bf16(float lo, float hi) { unsigned r; asm volatile("v_cvt_pk_bf16_f32 %0, %1, %2" : "=v"(r) : "v"(lo), "v"(hi)); return r; }
;     __device__ __forceinline__ void operator()(const f32x4 (&acc)[2][2][4][2], const Unit& u, int wr, int wc, int fr, int fq) const {
;     ...
;                 for (int m = 0; m < 4; ++m) { float t = ((p0[ai][m][0] + p0[ai][m][1]) + (p0[ai][m][2] + p0[ai][m][3])) + ((p1[ai][m][0] + p1[ai][m][1]) + (p1[ai][m][2] + p1[ai][m][3]));
;                     t += __shfl_xor(t, 16); t += __shfl_xor(t, 32);
;                     rsv[ai][m] = 1.0f / sqrtf(t * (1.0f / D) + EPS); }
;         }
; #pragma unroll
;         for (int ai = 0; ai < 2; ++ai)
; #pragma unroll
;             for (int m = 0; m < 4; ++m) { const int row = row0 + ai * HALF + m * 16; const float rs = rsv[ai][m];
; #pragma unroll
;                 for (int bj = 0; bj < 2; ++bj) { const f32x4 v0 = acc[ai][bj][m][0] * rs, v1 = acc[ai][bj][m][1] * rs;
;                     u32x4 o; o.x = cvt_pk_bf16(v0[0], v0[1]); o.y = cvt_pk_bf16(v0[2], v0[3]); o.z = cvt_pk_bf16(v1[0], v1[1]); o.w = cvt_pk_bf16(v1[2], v1[3]);
;                     bf16_t* dst;
;                     if (u.pn < 4) { const int colg = u.pn * BM + bj * HALF + wc * 32 + 8 * fq; dst = P + (size_t)(colg >> 9) * ((size_t)T * 512) + (size_t)row * 512 + (colg & 511); }
;                     else if (u.pn < 8) { const int colc = (u.pn - 4) * BM + bj * HALF + wc * 32 + 8 * fq; dst = P + PJ_UC + (size_t)row * 1024 + colc; }
;                     else { const int which = (u.pn - 8) >> 1, hd = ((u.pn - 8) & 1) * 4 + 2 * bj + (wc >> 1), dim = 32 * (wc & 1) + 8 * fq, bb = row >> 11, ll = row & 2047;
;                         dst = P + PJ_QKV + ((size_t)(((which * 4 + bb) * 8 + hd) * SEQ + ll)) * 64 + dim; }
;                     *(u32x4*)dst = o; } }
.LBB0_368:
	s_waitcnt lgkmcnt(4)
	v_add_f32_e32 v0, v194, v195
	v_fmamk_f32 v0, v0, 0x3a000000, v223
	v_mul_f32_e32 v160, 0x4f800000, v0
	v_cmp_gt_f32_e32 vcc, s11, v0
	global_store_dwordx4 v[164:165], v[130:133], off sc1
	s_nop 0
	v_cndmask_b32_e32 v0, v0, v160, vcc
	v_sqrt_f32_e32 v160, v0
	s_nop 0
	v_add_u32_e32 v161, -1, v160
	v_fma_f32 v163, -v161, v160, v0
	v_add_u32_e32 v162, 1, v160
	v_cmp_ge_f32_e64 s[40:41], 0, v163
	s_nop 1
	v_cndmask_b32_e64 v161, v160, v161, s[40:41]
	v_fma_f32 v160, -v162, v160, v0
	v_cmp_lt_f32_e64 s[40:41], 0, v160
	s_nop 1
	v_cndmask_b32_e64 v160, v161, v162, s[40:41]
	v_mul_f32_e32 v161, 0x37800000, v160
	v_cndmask_b32_e32 v160, v160, v161, vcc
	v_cmp_class_f32_e32 vcc, v0, v224
	s_nop 1
	v_cndmask_b32_e32 v0, v160, v0, vcc
	v_div_scale_f32 v160, s[2:3], v0, v0, 1.0
	v_rcp_f32_e32 v161, v160
	s_mov_b64 s[2:3], -1
	v_fma_f32 v162, -v160, v161, 1.0
	v_fmac_f32_e32 v161, v162, v161
	v_div_scale_f32 v162, vcc, 1.0, v0, 1.0
	v_mul_f32_e32 v163, v162, v161
	v_fma_f32 v166, -v160, v163, v162
	v_fmac_f32_e32 v163, v166, v161
	v_fma_f32 v160, -v160, v163, v162
	v_div_fmas_f32 v160, v160, v161, v163
	v_div_fixup_f32 v162, v160, v0, 1.0
	v_and_b32_e32 v166, 0x7ff, v158
	v_lshlrev_b64 v[160:161], 11, v[158:159]
	v_pk_mul_f32 v[132:133], v[88:89], v[162:163] op_sel_hi:[1,0]
	v_pk_mul_f32 v[130:131], v[86:87], v[162:163] op_sel_hi:[1,0]
	v_pk_mul_f32 v[164:165], v[80:81], v[162:163] op_sel_hi:[1,0]
	s_and_b64 vcc, exec, s[38:39]
	v_pk_mul_f32 v[168:169], v[78:79], v[162:163] op_sel_hi:[1,0]
	v_cvt_pk_bf16_f32 v130, v130, v131
	v_cvt_pk_bf16_f32 v131, v132, v133
	s_nop 0
	v_cvt_pk_bf16_f32 v132, v168, v169
	v_cvt_pk_bf16_f32 v133, v164, v165
	s_cbranch_vccnz .LBB0_374
	s_cmp_lt_u32 s46, 8
	s_cbranch_scc1 .LBB0_371
	s_lshl_b32 s2, s46, 2
	s_lshl_b32 s3, s46, 1
	s_and_b32 s2, s2, 4
	s_and_b32 s3, s3, 0x3fffc
	s_or_b32 s2, s2, s61
	s_add_i32 s3, s17, s3
	s_lshl_b32 s3, s3, 14
	s_lshl_b32 s2, s2, 11
	s_or_b32 s2, s3, s2
	v_or_b32_e32 v164, s2, v166
	v_ashrrev_i32_e32 v165, 31, v164
	v_lshlrev_b64 v[164:165], 7, v[164:165]
	v_lshl_add_u64 v[164:165], v[144:145], 0, v[164:165]
	s_mov_b64 s[2:3], 0

; __device__ __forceinline__ unsigned cvt_pk_bf16(float lo, float hi) { unsigned r; asm volatile("v_cvt_pk_bf16_f32 %0, %1, %2" : "=v"(r) : "v"(lo), "v"(hi)); return r; }
;     __device__ __forceinline__ void operator()(const f32x4 (&acc)[2][2][4][2], const Unit& u, int wr, int wc, int fr, int fq) const {
;     ...
;             for (int m = 0; m < 4; ++m) { const int row = row0 + ai * HALF + m * 16; const float rs = rsv[ai][m];
; #pragma unroll
;                 for (int bj = 0; bj < 2; ++bj) { const f32x4 v0 = acc[ai][bj][m][0] * rs, v1 = acc[ai][bj][m][1] * rs;
;                     u32x4 o; o.x = cvt_pk_bf16(v0[0], v0[1]); o.y = cvt_pk_bf16(v0[2], v0[3]); o.z = cvt_pk_bf16(v1[0], v1[1]); o.w = cvt_pk_bf16(v1[2], v1[3]);
;                     bf16_t* dst;
;                     if (u.pn < 4) { const int colg = u.pn * BM + bj * HALF + wc * 32 + 8 * fq; dst = P + (size_t)(colg >> 9) * ((size_t)T * 512) + (size_t)row * 512 + (colg & 511); }
;                     else if (u.pn < 8) { const int colc = (u.pn - 4) * BM + bj * HALF + wc * 32 + 8 * fq; dst = P + PJ_UC + (size_t)row * 1024 + colc; }
;                     else { const int which = (u.pn - 8) >> 1, hd = ((u.pn - 8) & 1) * 4 + 2 * bj + (wc >> 1), dim = 32 * (wc & 1) + 8 * fq, bb = row >> 11, ll = row & 2047;
;                         dst = P + PJ_QKV + ((size_t)(((which * 4 + bb) * 8 + hd) * SEQ + ll)) * 64 + dim; }
;                     *(u32x4*)dst = o; } }
.LBB0_376:
	v_mov_b32_e32 v163, v162
	global_store_dwordx4 v[164:165], v[130:133], off sc1
	v_pk_mul_f32 v[164:165], v[70:71], v[162:163]
	s_and_b64 vcc, exec, s[38:39]
	v_mov_b32_e32 v130, v162
	v_mov_b32_e32 v131, v162
	v_pk_mul_f32 v[132:133], v[72:73], v[130:131]
	v_pk_mul_f32 v[162:163], v[66:67], v[162:163]
	s_mov_b64 s[2:3], -1
	v_pk_mul_f32 v[168:169], v[68:69], v[130:131]
	v_cvt_pk_bf16_f32 v130, v164, v165
	v_cvt_pk_bf16_f32 v131, v132, v133
	v_cvt_pk_bf16_f32 v132, v162, v163
	s_nop 0
	v_cvt_pk_bf16_f32 v133, v168, v169
	s_cbranch_vccnz .LBB0_382
	s_cmp_lt_u32 s46, 8
	s_cbranch_scc1 .LBB0_379
	s_lshl_b32 s2, s46, 2
	s_lshl_b32 s3, s46, 1
	s_and_b32 s2, s2, 4
	s_and_b32 s3, s3, 0x3fffc
	s_or_b32 s2, s2, s61
	s_add_i32 s17, s17, s3
	s_lshl_b32 s3, s17, 14
	s_lshl_b32 s2, s2, 11
	s_or_b32 s2, s2, s3
	v_or_b32_e32 v0, s2, v166
	v_or_b32_e32 v162, 0x1000, v0
	v_ashrrev_i32_e32 v163, 31, v162
	v_lshlrev_b64 v[162:163], 7, v[162:163]
	v_lshl_add_u64 v[162:163], v[144:145], 0, v[162:163]
	s_mov_b64 s[2:3], 0

; __device__ __forceinline__ unsigned cvt_pk_bf16(float lo, float hi) { unsigned r; asm volatile("v_cvt_pk_bf16_f32 %0, %1, %2" : "=v"(r) : "v"(lo), "v"(hi)); return r; }
;     __device__ __forceinline__ void operator()(const f32x4 (&acc)[2][2][4][2], const Unit& u, int wr, int wc, int fr, int fq) const {
;     ...
;                 for (int m = 0; m < 4; ++m) { float t = ((p0[ai][m][0] + p0[ai][m][1]) + (p0[ai][m][2] + p0[ai][m][3])) + ((p1[ai][m][0] + p1[ai][m][1]) + (p1[ai][m][2] + p1[ai][m][3]));
;                     t += __shfl_xor(t, 16); t += __shfl_xor(t, 32);
;                     rsv[ai][m] = 1.0f / sqrtf(t * (1.0f / D) + EPS); }
;         }
; #pragma unroll
;         for (int ai = 0; ai < 2; ++ai)
; #pragma unroll
;             for (int m = 0; m < 4; ++m) { const int row = row0 + ai * HALF + m * 16; const float rs = rsv[ai][m];
; #pragma unroll
;                 for (int bj = 0; bj < 2; ++bj) { const f32x4 v0 = acc[ai][bj][m][0] * rs, v1 = acc[ai][bj][m][1] * rs;
;                     u32x4 o; o.x = cvt_pk_bf16(v0[0], v0[1]); o.y = cvt_pk_bf16(v0[2], v0[3]); o.z = cvt_pk_bf16(v1[0], v1[1]); o.w = cvt_pk_bf16(v1[2], v1[3]);
;                     bf16_t* dst;
;                     if (u.pn < 4) { const int colg = u.pn * BM + bj * HALF + wc * 32 + 8 * fq; dst = P + (size_t)(colg >> 9) * ((size_t)T * 512) + (size_t)row * 512 + (colg & 511); }
;                     else if (u.pn < 8) { const int colc = (u.pn - 4) * BM + bj * HALF + wc * 32 + 8 * fq; dst = P + PJ_UC + (size_t)row * 1024 + colc; }
;                     else { const int which = (u.pn - 8) >> 1, hd = ((u.pn - 8) & 1) * 4 + 2 * bj + (wc >> 1), dim = 32 * (wc & 1) + 8 * fq, bb = row >> 11, ll = row & 2047;
;                         dst = P + PJ_QKV + ((size_t)(((which * 4 + bb) * 8 + hd) * SEQ + ll)) * 64 + dim; }
;                     *(u32x4*)dst = o; } }
.LBB0_384:
	s_waitcnt lgkmcnt(3)
	v_add_f32_e32 v0, v192, v193
	v_fmamk_f32 v0, v0, 0x3a000000, v223
	v_mul_f32_e32 v158, 0x4f800000, v0
	v_cmp_gt_f32_e32 vcc, s11, v0
	global_store_dwordx4 v[162:163], v[130:133], off sc1
	v_and_b32_e32 v165, 0x7cf, v156
	v_cndmask_b32_e32 v0, v0, v158, vcc
	v_sqrt_f32_e32 v158, v0
	s_nop 0
	v_add_u32_e32 v159, -1, v158
	v_fma_f32 v161, -v159, v158, v0
	v_add_u32_e32 v160, 1, v158
	v_cmp_ge_f32_e64 s[40:41], 0, v161
	s_nop 1
	v_cndmask_b32_e64 v159, v158, v159, s[40:41]
	v_fma_f32 v158, -v160, v158, v0
	v_cmp_lt_f32_e64 s[40:41], 0, v158
	s_nop 1
	v_cndmask_b32_e64 v158, v159, v160, s[40:41]
	v_mul_f32_e32 v159, 0x37800000, v158
	v_cndmask_b32_e32 v158, v158, v159, vcc
	v_cmp_class_f32_e32 vcc, v0, v224
	s_nop 1
	v_cndmask_b32_e32 v0, v158, v0, vcc
	v_div_scale_f32 v158, s[2:3], v0, v0, 1.0
	v_rcp_f32_e32 v159, v158
	s_mov_b64 s[2:3], -1
	v_fma_f32 v160, -v158, v159, 1.0
	v_fmac_f32_e32 v159, v160, v159
	v_div_scale_f32 v160, vcc, 1.0, v0, 1.0
	v_mul_f32_e32 v161, v160, v159
	v_fma_f32 v164, -v158, v161, v160
	v_fmac_f32_e32 v161, v164, v159
	v_fma_f32 v158, -v158, v161, v160
	v_div_fmas_f32 v158, v158, v159, v161
	v_div_fixup_f32 v160, v158, v0, 1.0
	v_lshrrev_b32_e32 v0, 11, v156
	v_add_u32_e32 v164, 0x3fff0, v0
	v_lshlrev_b64 v[158:159], 11, v[156:157]
	v_pk_mul_f32 v[132:133], v[64:65], v[160:161] op_sel_hi:[1,0]
	v_pk_mul_f32 v[130:131], v[62:63], v[160:161] op_sel_hi:[1,0]
	v_pk_mul_f32 v[162:163], v[60:61], v[160:161] op_sel_hi:[1,0]
	s_and_b64 vcc, exec, s[38:39]
	v_pk_mul_f32 v[166:167], v[58:59], v[160:161] op_sel_hi:[1,0]
	v_cvt_pk_bf16_f32 v130, v130, v131
	v_cvt_pk_bf16_f32 v131, v132, v133
	s_nop 0
	v_cvt_pk_bf16_f32 v132, v166, v167
	v_cvt_pk_bf16_f32 v133, v162, v163
	s_cbranch_vccnz .LBB0_390
	s_cmp_lt_u32 s46, 8
	s_cbranch_scc1 .LBB0_387
	s_lshl_b32 s2, s46, 2
	s_and_b32 s2, s2, 4
	s_lshl_b32 s3, s46, 1
	s_or_b32 s2, s2, s61
	s_and_b32 s3, s3, 0x3fffc
	v_add_lshl_u32 v0, v164, s3, 14
	s_lshl_b32 s2, s2, 11
	v_or3_b32 v162, v0, s2, v165
	v_ashrrev_i32_e32 v163, 31, v162
	v_lshlrev_b64 v[162:163], 7, v[162:163]
	v_lshl_add_u64 v[162:163], v[144:145], 0, v[162:163]
	s_mov_b64 s[2:3], 0

; __device__ __forceinline__ unsigned cvt_pk_bf16(float lo, float hi) { unsigned r; asm volatile("v_cvt_pk_bf16_f32 %0, %1, %2" : "=v"(r) : "v"(lo), "v"(hi)); return r; }
;     __device__ __forceinline__ void operator()(const f32x4 (&acc)[2][2][4][2], const Unit& u, int wr, int wc, int fr, int fq) const {
;     ...
;             for (int m = 0; m < 4; ++m) { const int row = row0 + ai * HALF + m * 16; const float rs = rsv[ai][m];
; #pragma unroll
;                 for (int bj = 0; bj < 2; ++bj) { const f32x4 v0 = acc[ai][bj][m][0] * rs, v1 = acc[ai][bj][m][1] * rs;
;                     u32x4 o; o.x = cvt_pk_bf16(v0[0], v0[1]); o.y = cvt_pk_bf16(v0[2], v0[3]); o.z = cvt_pk_bf16(v1[0], v1[1]); o.w = cvt_pk_bf16(v1[2], v1[3]);
;                     bf16_t* dst;
;                     if (u.pn < 4) { const int colg = u.pn * BM + bj * HALF + wc * 32 + 8 * fq; dst = P + (size_t)(colg >> 9) * ((size_t)T * 512) + (size_t)row * 512 + (colg & 511); }
;                     else if (u.pn < 8) { const int colc = (u.pn - 4) * BM + bj * HALF + wc * 32 + 8 * fq; dst = P + PJ_UC + (size_t)row * 1024 + colc; }
;                     else { const int which = (u.pn - 8) >> 1, hd = ((u.pn - 8) & 1) * 4 + 2 * bj + (wc >> 1), dim = 32 * (wc & 1) + 8 * fq, bb = row >> 11, ll = row & 2047;
;                         dst = P + PJ_QKV + ((size_t)(((which * 4 + bb) * 8 + hd) * SEQ + ll)) * 64 + dim; }
;                     *(u32x4*)dst = o; } }
.LBB0_392:
	v_mov_b32_e32 v161, v160
	global_store_dwordx4 v[162:163], v[130:133], off sc1
	v_pk_mul_f32 v[162:163], v[50:51], v[160:161]
	s_and_b64 vcc, exec, s[38:39]
	v_mov_b32_e32 v130, v160
	v_mov_b32_e32 v131, v160
	v_pk_mul_f32 v[132:133], v[52:53], v[130:131]
	v_pk_mul_f32 v[160:161], v[42:43], v[160:161]
	s_mov_b64 s[2:3], -1
	v_pk_mul_f32 v[166:167], v[44:45], v[130:131]
	v_cvt_pk_bf16_f32 v130, v162, v163
	v_cvt_pk_bf16_f32 v131, v132, v133
	v_cvt_pk_bf16_f32 v132, v160, v161
	s_nop 0
	v_cvt_pk_bf16_f32 v133, v166, v167
	s_cbranch_vccnz .LBB0_398
	s_cmp_lt_u32 s46, 8
	s_cbranch_scc1 .LBB0_395
	s_lshl_b32 s2, s46, 2
	s_and_b32 s2, s2, 4
	s_lshl_b32 s3, s46, 1
	s_or_b32 s2, s2, s61
	s_and_b32 s3, s3, 0x3fffc
	v_add_u32_e32 v0, s3, v164
	s_lshl_b32 s2, s2, 11
	v_lshl_or_b32 v0, v0, 14, s2
	s_movk_i32 s2, 0x1000
	v_or3_b32 v160, v0, v165, s2
	v_ashrrev_i32_e32 v161, 31, v160
	v_lshlrev_b64 v[160:161], 7, v[160:161]
	v_lshl_add_u64 v[160:161], v[144:145], 0, v[160:161]
	s_mov_b64 s[2:3], 0

; __device__ __forceinline__ unsigned cvt_pk_bf16(float lo, float hi) { unsigned r; asm volatile("v_cvt_pk_bf16_f32 %0, %1, %2" : "=v"(r) : "v"(lo), "v"(hi)); return r; }
;     __device__ __forceinline__ void operator()(const f32x4 (&acc)[2][2][4][2], const Unit& u, int wr, int wc, int fr, int fq) const {
;     ...
;                 for (int m = 0; m < 4; ++m) { float t = ((p0[ai][m][0] + p0[ai][m][1]) + (p0[ai][m][2] + p0[ai][m][3])) + ((p1[ai][m][0] + p1[ai][m][1]) + (p1[ai][m][2] + p1[ai][m][3]));
;                     t += __shfl_xor(t, 16); t += __shfl_xor(t, 32);
;                     rsv[ai][m] = 1.0f / sqrtf(t * (1.0f / D) + EPS); }
;         }
; #pragma unroll
;         for (int ai = 0; ai < 2; ++ai)
; #pragma unroll
;             for (int m = 0; m < 4; ++m) { const int row = row0 + ai * HALF + m * 16; const float rs = rsv[ai][m];
; #pragma unroll
;                 for (int bj = 0; bj < 2; ++bj) { const f32x4 v0 = acc[ai][bj][m][0] * rs, v1 = acc[ai][bj][m][1] * rs;
;                     u32x4 o; o.x = cvt_pk_bf16(v0[0], v0[1]); o.y = cvt_pk_bf16(v0[2], v0[3]); o.z = cvt_pk_bf16(v1[0], v1[1]); o.w = cvt_pk_bf16(v1[2], v1[3]);
;                     bf16_t* dst;
;                     if (u.pn < 4) { const int colg = u.pn * BM + bj * HALF + wc * 32 + 8 * fq; dst = P + (size_t)(colg >> 9) * ((size_t)T * 512) + (size_t)row * 512 + (colg & 511); }
;                     else if (u.pn < 8) { const int colc = (u.pn - 4) * BM + bj * HALF + wc * 32 + 8 * fq; dst = P + PJ_UC + (size_t)row * 1024 + colc; }
;                     else { const int which = (u.pn - 8) >> 1, hd = ((u.pn - 8) & 1) * 4 + 2 * bj + (wc >> 1), dim = 32 * (wc & 1) + 8 * fq, bb = row >> 11, ll = row & 2047;
;                         dst = P + PJ_QKV + ((size_t)(((which * 4 + bb) * 8 + hd) * SEQ + ll)) * 64 + dim; }
;                     *(u32x4*)dst = o; } }
.LBB0_400:
	s_waitcnt lgkmcnt(2)
	v_add_f32_e32 v0, v190, v191
	v_fmamk_f32 v0, v0, 0x3a000000, v223
	v_mul_f32_e32 v156, 0x4f800000, v0
	v_cmp_gt_f32_e32 vcc, s11, v0
	global_store_dwordx4 v[160:161], v[130:133], off sc1
	s_nop 0
	v_cndmask_b32_e32 v0, v0, v156, vcc
	v_sqrt_f32_e32 v156, v0
	s_nop 0
	v_add_u32_e32 v157, -1, v156
	v_fma_f32 v159, -v157, v156, v0
	v_add_u32_e32 v158, 1, v156
	v_cmp_ge_f32_e64 s[40:41], 0, v159
	s_nop 1
	v_cndmask_b32_e64 v157, v156, v157, s[40:41]
	v_fma_f32 v156, -v158, v156, v0
	v_cmp_lt_f32_e64 s[40:41], 0, v156
	s_nop 1
	v_cndmask_b32_e64 v156, v157, v158, s[40:41]
	v_mul_f32_e32 v157, 0x37800000, v156
	v_cndmask_b32_e32 v156, v156, v157, vcc
	v_cmp_class_f32_e32 vcc, v0, v224
	s_nop 1
	v_cndmask_b32_e32 v0, v156, v0, vcc
	v_div_scale_f32 v156, s[2:3], v0, v0, 1.0
	v_rcp_f32_e32 v157, v156
	s_mov_b64 s[2:3], -1
	v_fma_f32 v158, -v156, v157, 1.0
	v_fmac_f32_e32 v157, v158, v157
	v_div_scale_f32 v158, vcc, 1.0, v0, 1.0
	v_mul_f32_e32 v159, v158, v157
	v_fma_f32 v162, -v156, v159, v158
	v_fmac_f32_e32 v159, v162, v157
	v_fma_f32 v156, -v156, v159, v158
	v_div_fmas_f32 v156, v156, v157, v159
	v_div_fixup_f32 v158, v156, v0, 1.0
	v_and_b32_e32 v162, 0x7df, v154
	v_lshlrev_b64 v[156:157], 11, v[154:155]
	v_pk_mul_f32 v[132:133], v[56:57], v[158:159] op_sel_hi:[1,0]
	v_pk_mul_f32 v[130:131], v[54:55], v[158:159] op_sel_hi:[1,0]
	v_pk_mul_f32 v[160:161], v[48:49], v[158:159] op_sel_hi:[1,0]
	s_and_b64 vcc, exec, s[38:39]
	v_pk_mul_f32 v[166:167], v[46:47], v[158:159] op_sel_hi:[1,0]
	v_cvt_pk_bf16_f32 v130, v130, v131
	v_cvt_pk_bf16_f32 v131, v132, v133
	s_nop 0
	v_cvt_pk_bf16_f32 v132, v166, v167
	v_cvt_pk_bf16_f32 v133, v160, v161
	s_cbranch_vccnz .LBB0_406
	s_cmp_lt_u32 s46, 8
	s_cbranch_scc1 .LBB0_403
	s_lshl_b32 s2, s46, 2
	s_and_b32 s2, s2, 4
	s_lshl_b32 s3, s46, 1
	s_or_b32 s2, s2, s61
	s_and_b32 s3, s3, 0x3fffc
	v_add_lshl_u32 v0, v164, s3, 14
	s_lshl_b32 s2, s2, 11
	v_or3_b32 v160, v0, s2, v162
	v_ashrrev_i32_e32 v161, 31, v160
	v_lshlrev_b64 v[160:161], 7, v[160:161]
	v_lshl_add_u64 v[160:161], v[144:145], 0, v[160:161]
	s_mov_b64 s[2:3], 0

; __device__ __forceinline__ unsigned cvt_pk_bf16(float lo, float hi) { unsigned r; asm volatile("v_cvt_pk_bf16_f32 %0, %1, %2" : "=v"(r) : "v"(lo), "v"(hi)); return r; }
;     __device__ __forceinline__ void operator()(const f32x4 (&acc)[2][2][4][2], const Unit& u, int wr, int wc, int fr, int fq) const {
;     ...
;             for (int m = 0; m < 4; ++m) { const int row = row0 + ai * HALF + m * 16; const float rs = rsv[ai][m];
; #pragma unroll
;                 for (int bj = 0; bj < 2; ++bj) { const f32x4 v0 = acc[ai][bj][m][0] * rs, v1 = acc[ai][bj][m][1] * rs;
;                     u32x4 o; o.x = cvt_pk_bf16(v0[0], v0[1]); o.y = cvt_pk_bf16(v0[2], v0[3]); o.z = cvt_pk_bf16(v1[0], v1[1]); o.w = cvt_pk_bf16(v1[2], v1[3]);
;                     bf16_t* dst;
;                     if (u.pn < 4) { const int colg = u.pn * BM + bj * HALF + wc * 32 + 8 * fq; dst = P + (size_t)(colg >> 9) * ((size_t)T * 512) + (size_t)row * 512 + (colg & 511); }
;                     else if (u.pn < 8) { const int colc = (u.pn - 4) * BM + bj * HALF + wc * 32 + 8 * fq; dst = P + PJ_UC + (size_t)row * 1024 + colc; }
;                     else { const int which = (u.pn - 8) >> 1, hd = ((u.pn - 8) & 1) * 4 + 2 * bj + (wc >> 1), dim = 32 * (wc & 1) + 8 * fq, bb = row >> 11, ll = row & 2047;
;                         dst = P + PJ_QKV + ((size_t)(((which * 4 + bb) * 8 + hd) * SEQ + ll)) * 64 + dim; }
;                     *(u32x4*)dst = o; } }
.LBB0_408:
	v_mov_b32_e32 v159, v158
	global_store_dwordx4 v[160:161], v[130:133], off sc1
	v_pk_mul_f32 v[160:161], v[34:35], v[158:159]
	s_and_b64 vcc, exec, s[38:39]
	v_mov_b32_e32 v130, v158
	v_mov_b32_e32 v131, v158
	v_pk_mul_f32 v[132:133], v[36:37], v[130:131]
	v_pk_mul_f32 v[158:159], v[26:27], v[158:159]
	s_mov_b64 s[2:3], -1
	v_pk_mul_f32 v[166:167], v[28:29], v[130:131]
	v_cvt_pk_bf16_f32 v130, v160, v161
	v_cvt_pk_bf16_f32 v131, v132, v133
	v_cvt_pk_bf16_f32 v132, v158, v159
	s_nop 0
	v_cvt_pk_bf16_f32 v133, v166, v167
	s_cbranch_vccnz .LBB0_414
	s_cmp_lt_u32 s46, 8
	s_cbranch_scc1 .LBB0_411
	s_lshl_b32 s2, s46, 2
	s_and_b32 s2, s2, 4
	s_lshl_b32 s3, s46, 1
	s_or_b32 s2, s2, s61
	s_and_b32 s3, s3, 0x3fffc
	v_add_u32_e32 v0, s3, v164
	s_lshl_b32 s2, s2, 11
	v_lshl_or_b32 v0, v0, 14, s2
	s_movk_i32 s2, 0x1000
	v_or3_b32 v158, v0, v162, s2
	v_ashrrev_i32_e32 v159, 31, v158
	v_lshlrev_b64 v[158:159], 7, v[158:159]
	v_lshl_add_u64 v[158:159], v[144:145], 0, v[158:159]
	s_mov_b64 s[2:3], 0

; __device__ __forceinline__ unsigned cvt_pk_bf16(float lo, float hi) { unsigned r; asm volatile("v_cvt_pk_bf16_f32 %0, %1, %2" : "=v"(r) : "v"(lo), "v"(hi)); return r; }
;     __device__ __forceinline__ void operator()(const f32x4 (&acc)[2][2][4][2], const Unit& u, int wr, int wc, int fr, int fq) const {
;     ...
;                 for (int m = 0; m < 4; ++m) { float t = ((p0[ai][m][0] + p0[ai][m][1]) + (p0[ai][m][2] + p0[ai][m][3])) + ((p1[ai][m][0] + p1[ai][m][1]) + (p1[ai][m][2] + p1[ai][m][3]));
;                     t += __shfl_xor(t, 16); t += __shfl_xor(t, 32);
;                     rsv[ai][m] = 1.0f / sqrtf(t * (1.0f / D) + EPS); }
;         }
; #pragma unroll
;         for (int ai = 0; ai < 2; ++ai)
; #pragma unroll
;             for (int m = 0; m < 4; ++m) { const int row = row0 + ai * HALF + m * 16; const float rs = rsv[ai][m];
; #pragma unroll
;                 for (int bj = 0; bj < 2; ++bj) { const f32x4 v0 = acc[ai][bj][m][0] * rs, v1 = acc[ai][bj][m][1] * rs;
;                     u32x4 o; o.x = cvt_pk_bf16(v0[0], v0[1]); o.y = cvt_pk_bf16(v0[2], v0[3]); o.z = cvt_pk_bf16(v1[0], v1[1]); o.w = cvt_pk_bf16(v1[2], v1[3]);
;                     bf16_t* dst;
;                     if (u.pn < 4) { const int colg = u.pn * BM + bj * HALF + wc * 32 + 8 * fq; dst = P + (size_t)(colg >> 9) * ((size_t)T * 512) + (size_t)row * 512 + (colg & 511); }
;                     else if (u.pn < 8) { const int colc = (u.pn - 4) * BM + bj * HALF + wc * 32 + 8 * fq; dst = P + PJ_UC + (size_t)row * 1024 + colc; }
;                     else { const int which = (u.pn - 8) >> 1, hd = ((u.pn - 8) & 1) * 4 + 2 * bj + (wc >> 1), dim = 32 * (wc & 1) + 8 * fq, bb = row >> 11, ll = row & 2047;
;                         dst = P + PJ_QKV + ((size_t)(((which * 4 + bb) * 8 + hd) * SEQ + ll)) * 64 + dim; }
;                     *(u32x4*)dst = o; } }
.LBB0_416:
	s_waitcnt lgkmcnt(1)
	v_add_f32_e32 v0, v188, v189
	v_fmamk_f32 v0, v0, 0x3a000000, v223
	v_mul_f32_e32 v154, 0x4f800000, v0
	v_cmp_gt_f32_e32 vcc, s11, v0
	global_store_dwordx4 v[158:159], v[130:133], off sc1
	s_nop 0
	v_cndmask_b32_e32 v0, v0, v154, vcc
	v_sqrt_f32_e32 v154, v0
	s_nop 0
	v_add_u32_e32 v155, -1, v154
	v_fma_f32 v157, -v155, v154, v0
	v_add_u32_e32 v156, 1, v154
	v_cmp_ge_f32_e64 s[40:41], 0, v157
	s_nop 1
	v_cndmask_b32_e64 v155, v154, v155, s[40:41]
	v_fma_f32 v154, -v156, v154, v0
	v_cmp_lt_f32_e64 s[40:41], 0, v154
	s_nop 1
	v_cndmask_b32_e64 v154, v155, v156, s[40:41]
	v_mul_f32_e32 v155, 0x37800000, v154
	v_cndmask_b32_e32 v154, v154, v155, vcc
	v_cmp_class_f32_e32 vcc, v0, v224
	s_nop 1
	v_cndmask_b32_e32 v0, v154, v0, vcc
	v_div_scale_f32 v154, s[2:3], v0, v0, 1.0
	v_rcp_f32_e32 v155, v154
	s_mov_b64 s[2:3], -1
	v_fma_f32 v156, -v154, v155, 1.0
	v_fmac_f32_e32 v155, v156, v155
	v_div_scale_f32 v156, vcc, 1.0, v0, 1.0
	v_mul_f32_e32 v157, v156, v155
	v_fma_f32 v160, -v154, v157, v156
	v_fmac_f32_e32 v157, v160, v155
	v_fma_f32 v154, -v154, v157, v156
	v_div_fmas_f32 v154, v154, v155, v157
	v_div_fixup_f32 v156, v154, v0, 1.0
	v_and_b32_e32 v160, 0x7ef, v152
	v_lshlrev_b64 v[154:155], 11, v[152:153]
	v_pk_mul_f32 v[132:133], v[40:41], v[156:157] op_sel_hi:[1,0]
	v_pk_mul_f32 v[130:131], v[38:39], v[156:157] op_sel_hi:[1,0]
	v_pk_mul_f32 v[158:159], v[32:33], v[156:157] op_sel_hi:[1,0]
	s_and_b64 vcc, exec, s[38:39]
	v_pk_mul_f32 v[162:163], v[30:31], v[156:157] op_sel_hi:[1,0]
	v_cvt_pk_bf16_f32 v130, v130, v131
	v_cvt_pk_bf16_f32 v131, v132, v133
	s_nop 0
	v_cvt_pk_bf16_f32 v132, v162, v163
	v_cvt_pk_bf16_f32 v133, v158, v159
	s_cbranch_vccnz .LBB0_422
	s_cmp_lt_u32 s46, 8
	s_cbranch_scc1 .LBB0_419
	s_lshl_b32 s2, s46, 2
	s_and_b32 s2, s2, 4
	s_lshl_b32 s3, s46, 1
	s_or_b32 s2, s2, s61
	s_and_b32 s3, s3, 0x3fffc
	v_add_lshl_u32 v0, v164, s3, 14
	s_lshl_b32 s2, s2, 11
	v_or3_b32 v158, v0, s2, v160
	v_ashrrev_i32_e32 v159, 31, v158
	v_lshlrev_b64 v[158:159], 7, v[158:159]
	v_lshl_add_u64 v[158:159], v[144:145], 0, v[158:159]
	s_mov_b64 s[2:3], 0

; __device__ __forceinline__ unsigned cvt_pk_bf16(float lo, float hi) { unsigned r; asm volatile("v_cvt_pk_bf16_f32 %0, %1, %2" : "=v"(r) : "v"(lo), "v"(hi)); return r; }
;     __device__ __forceinline__ void operator()(const f32x4 (&acc)[2][2][4][2], const Unit& u, int wr, int wc, int fr, int fq) const {
;     ...
;             for (int m = 0; m < 4; ++m) { const int row = row0 + ai * HALF + m * 16; const float rs = rsv[ai][m];
; #pragma unroll
;                 for (int bj = 0; bj < 2; ++bj) { const f32x4 v0 = acc[ai][bj][m][0] * rs, v1 = acc[ai][bj][m][1] * rs;
;                     u32x4 o; o.x = cvt_pk_bf16(v0[0], v0[1]); o.y = cvt_pk_bf16(v0[2], v0[3]); o.z = cvt_pk_bf16(v1[0], v1[1]); o.w = cvt_pk_bf16(v1[2], v1[3]);
;                     bf16_t* dst;
;                     if (u.pn < 4) { const int colg = u.pn * BM + bj * HALF + wc * 32 + 8 * fq; dst = P + (size_t)(colg >> 9) * ((size_t)T * 512) + (size_t)row * 512 + (colg & 511); }
;                     else if (u.pn < 8) { const int colc = (u.pn - 4) * BM + bj * HALF + wc * 32 + 8 * fq; dst = P + PJ_UC + (size_t)row * 1024 + colc; }
;                     else { const int which = (u.pn - 8) >> 1, hd = ((u.pn - 8) & 1) * 4 + 2 * bj + (wc >> 1), dim = 32 * (wc & 1) + 8 * fq, bb = row >> 11, ll = row & 2047;
;                         dst = P + PJ_QKV + ((size_t)(((which * 4 + bb) * 8 + hd) * SEQ + ll)) * 64 + dim; }
;                     *(u32x4*)dst = o; } }
.LBB0_424:
	v_mov_b32_e32 v157, v156
	global_store_dwordx4 v[158:159], v[130:133], off sc1
	v_pk_mul_f32 v[158:159], v[18:19], v[156:157]
	s_and_b64 vcc, exec, s[38:39]
	v_mov_b32_e32 v130, v156
	v_mov_b32_e32 v131, v156
	v_pk_mul_f32 v[132:133], v[20:21], v[130:131]
	v_pk_mul_f32 v[156:157], v[10:11], v[156:157]
	s_mov_b64 s[2:3], -1
	v_pk_mul_f32 v[162:163], v[12:13], v[130:131]
	v_cvt_pk_bf16_f32 v130, v158, v159
	v_cvt_pk_bf16_f32 v131, v132, v133
	v_cvt_pk_bf16_f32 v132, v156, v157
	s_nop 0
	v_cvt_pk_bf16_f32 v133, v162, v163
	s_cbranch_vccnz .LBB0_430
	s_cmp_lt_u32 s46, 8
	s_cbranch_scc1 .LBB0_427
	s_lshl_b32 s2, s46, 2
	s_and_b32 s2, s2, 4
	s_lshl_b32 s3, s46, 1
	s_or_b32 s2, s2, s61
	s_and_b32 s3, s3, 0x3fffc
	v_add_u32_e32 v0, s3, v164
	s_lshl_b32 s2, s2, 11
	v_lshl_or_b32 v0, v0, 14, s2
	s_movk_i32 s2, 0x1000
	v_or3_b32 v156, v0, v160, s2
	v_ashrrev_i32_e32 v157, 31, v156
	v_lshlrev_b64 v[156:157], 7, v[156:157]
	v_lshl_add_u64 v[156:157], v[144:145], 0, v[156:157]
	s_mov_b64 s[2:3], 0

; __device__ __forceinline__ unsigned cvt_pk_bf16(float lo, float hi) { unsigned r; asm volatile("v_cvt_pk_bf16_f32 %0, %1, %2" : "=v"(r) : "v"(lo), "v"(hi)); return r; }
;     __device__ __forceinline__ void operator()(const f32x4 (&acc)[2][2][4][2], const Unit& u, int wr, int wc, int fr, int fq) const {
;     ...
;                 for (int m = 0; m < 4; ++m) { float t = ((p0[ai][m][0] + p0[ai][m][1]) + (p0[ai][m][2] + p0[ai][m][3])) + ((p1[ai][m][0] + p1[ai][m][1]) + (p1[ai][m][2] + p1[ai][m][3]));
;                     t += __shfl_xor(t, 16); t += __shfl_xor(t, 32);
;                     rsv[ai][m] = 1.0f / sqrtf(t * (1.0f / D) + EPS); }
;         }
; #pragma unroll
;         for (int ai = 0; ai < 2; ++ai)
; #pragma unroll
;             for (int m = 0; m < 4; ++m) { const int row = row0 + ai * HALF + m * 16; const float rs = rsv[ai][m];
; #pragma unroll
;                 for (int bj = 0; bj < 2; ++bj) { const f32x4 v0 = acc[ai][bj][m][0] * rs, v1 = acc[ai][bj][m][1] * rs;
;                     u32x4 o; o.x = cvt_pk_bf16(v0[0], v0[1]); o.y = cvt_pk_bf16(v0[2], v0[3]); o.z = cvt_pk_bf16(v1[0], v1[1]); o.w = cvt_pk_bf16(v1[2], v1[3]);
;                     bf16_t* dst;
;                     if (u.pn < 4) { const int colg = u.pn * BM + bj * HALF + wc * 32 + 8 * fq; dst = P + (size_t)(colg >> 9) * ((size_t)T * 512) + (size_t)row * 512 + (colg & 511); }
;                     else if (u.pn < 8) { const int colc = (u.pn - 4) * BM + bj * HALF + wc * 32 + 8 * fq; dst = P + PJ_UC + (size_t)row * 1024 + colc; }
;                     else { const int which = (u.pn - 8) >> 1, hd = ((u.pn - 8) & 1) * 4 + 2 * bj + (wc >> 1), dim = 32 * (wc & 1) + 8 * fq, bb = row >> 11, ll = row & 2047;
;                         dst = P + PJ_QKV + ((size_t)(((which * 4 + bb) * 8 + hd) * SEQ + ll)) * 64 + dim; }
;                     *(u32x4*)dst = o; } }
.LBB0_432:
	s_waitcnt lgkmcnt(0)
	v_add_f32_e32 v0, v178, v183
	v_fmamk_f32 v0, v0, 0x3a000000, v223
	v_mul_f32_e32 v152, 0x4f800000, v0
	v_cmp_gt_f32_e32 vcc, s11, v0
	global_store_dwordx4 v[156:157], v[130:133], off sc1
	s_nop 0
	v_cndmask_b32_e32 v0, v0, v152, vcc
	v_sqrt_f32_e32 v152, v0
	s_nop 0
	v_add_u32_e32 v153, -1, v152
	v_fma_f32 v155, -v153, v152, v0
	v_add_u32_e32 v154, 1, v152
	v_cmp_ge_f32_e64 s[40:41], 0, v155
	s_nop 1
	v_cndmask_b32_e64 v153, v152, v153, s[40:41]
	v_fma_f32 v152, -v154, v152, v0
	v_cmp_lt_f32_e64 s[40:41], 0, v152
	s_nop 1
	v_cndmask_b32_e64 v152, v153, v154, s[40:41]
	v_mul_f32_e32 v153, 0x37800000, v152
	v_cndmask_b32_e32 v152, v152, v153, vcc
	v_cmp_class_f32_e32 vcc, v0, v224
	s_nop 1
	v_cndmask_b32_e32 v0, v152, v0, vcc
	v_div_scale_f32 v152, s[2:3], v0, v0, 1.0
	v_rcp_f32_e32 v153, v152
	s_mov_b64 s[2:3], -1
	v_fma_f32 v154, -v152, v153, 1.0
	v_fmac_f32_e32 v153, v154, v153
	v_div_scale_f32 v154, vcc, 1.0, v0, 1.0
	v_mul_f32_e32 v155, v154, v153
	v_fma_f32 v158, -v152, v155, v154
	v_fmac_f32_e32 v155, v158, v153
	v_fma_f32 v152, -v152, v155, v154
	v_div_fmas_f32 v152, v152, v153, v155
	v_div_fixup_f32 v154, v152, v0, 1.0
	v_and_b32_e32 v158, 0x7ff, v150
	v_lshlrev_b64 v[152:153], 11, v[150:151]
	v_pk_mul_f32 v[132:133], v[24:25], v[154:155] op_sel_hi:[1,0]
	v_pk_mul_f32 v[130:131], v[22:23], v[154:155] op_sel_hi:[1,0]
	v_pk_mul_f32 v[156:157], v[16:17], v[154:155] op_sel_hi:[1,0]
	s_and_b64 vcc, exec, s[38:39]
	v_pk_mul_f32 v[160:161], v[14:15], v[154:155] op_sel_hi:[1,0]
	v_cvt_pk_bf16_f32 v130, v130, v131
	v_cvt_pk_bf16_f32 v131, v132, v133
	s_nop 0
	v_cvt_pk_bf16_f32 v132, v160, v161
	v_cvt_pk_bf16_f32 v133, v156, v157
	s_cbranch_vccnz .LBB0_438
	s_cmp_lt_u32 s46, 8
	s_cbranch_scc1 .LBB0_435
	s_lshl_b32 s2, s46, 2
	s_and_b32 s2, s2, 4
	s_lshl_b32 s3, s46, 1
	s_or_b32 s2, s2, s61
	s_and_b32 s3, s3, 0x3fffc
	v_add_lshl_u32 v0, v164, s3, 14
	s_lshl_b32 s2, s2, 11
	v_or3_b32 v156, v0, s2, v158
	v_ashrrev_i32_e32 v157, 31, v156
	v_lshlrev_b64 v[156:157], 7, v[156:157]
	v_lshl_add_u64 v[156:157], v[144:145], 0, v[156:157]
	s_mov_b64 s[2:3], 0

; __device__ __forceinline__ unsigned cvt_pk_bf16(float lo, float hi) { unsigned r; asm volatile("v_cvt_pk_bf16_f32 %0, %1, %2" : "=v"(r) : "v"(lo), "v"(hi)); return r; }
;     __device__ __forceinline__ void operator()(const f32x4 (&acc)[2][2][4][2], const Unit& u, int wr, int wc, int fr, int fq) const {
;     ...
;             for (int m = 0; m < 4; ++m) { const int row = row0 + ai * HALF + m * 16; const float rs = rsv[ai][m];
; #pragma unroll
;                 for (int bj = 0; bj < 2; ++bj) { const f32x4 v0 = acc[ai][bj][m][0] * rs, v1 = acc[ai][bj][m][1] * rs;
;                     u32x4 o; o.x = cvt_pk_bf16(v0[0], v0[1]); o.y = cvt_pk_bf16(v0[2], v0[3]); o.z = cvt_pk_bf16(v1[0], v1[1]); o.w = cvt_pk_bf16(v1[2], v1[3]);
;                     bf16_t* dst;
;                     if (u.pn < 4) { const int colg = u.pn * BM + bj * HALF + wc * 32 + 8 * fq; dst = P + (size_t)(colg >> 9) * ((size_t)T * 512) + (size_t)row * 512 + (colg & 511); }
;                     else if (u.pn < 8) { const int colc = (u.pn - 4) * BM + bj * HALF + wc * 32 + 8 * fq; dst = P + PJ_UC + (size_t)row * 1024 + colc; }
;                     else { const int which = (u.pn - 8) >> 1, hd = ((u.pn - 8) & 1) * 4 + 2 * bj + (wc >> 1), dim = 32 * (wc & 1) + 8 * fq, bb = row >> 11, ll = row & 2047;
;                         dst = P + PJ_QKV + ((size_t)(((which * 4 + bb) * 8 + hd) * SEQ + ll)) * 64 + dim; }
;                     *(u32x4*)dst = o; } }
.LBB0_440:
	v_mov_b32_e32 v155, v154
	global_store_dwordx4 v[156:157], v[130:133], off sc1
	v_pk_mul_f32 v[156:157], v[6:7], v[154:155]
	s_and_b64 vcc, exec, s[38:39]
	v_mov_b32_e32 v130, v154
	v_mov_b32_e32 v131, v154
	v_pk_mul_f32 v[132:133], v[8:9], v[130:131]
	v_pk_mul_f32 v[154:155], v[2:3], v[154:155]
	s_mov_b64 s[2:3], -1
	v_pk_mul_f32 v[160:161], v[4:5], v[130:131]
	v_cvt_pk_bf16_f32 v130, v156, v157
	v_cvt_pk_bf16_f32 v131, v132, v133
	v_cvt_pk_bf16_f32 v132, v154, v155
	s_nop 0
	v_cvt_pk_bf16_f32 v133, v160, v161
	s_cbranch_vccnz .LBB0_446
	s_cmp_lt_u32 s46, 8
	s_cbranch_scc1 .LBB0_443
	s_lshl_b32 s2, s46, 2
	s_and_b32 s2, s2, 4
	s_lshl_b32 s3, s46, 1
	s_or_b32 s2, s2, s61
	s_and_b32 s3, s3, 0x3fffc
	v_add_u32_e32 v0, s3, v164
	s_lshl_b32 s2, s2, 11
	v_lshl_or_b32 v0, v0, 14, s2
	s_movk_i32 s2, 0x1000
	v_or3_b32 v154, v0, v158, s2
	v_ashrrev_i32_e32 v155, 31, v154
	v_lshlrev_b64 v[154:155], 7, v[154:155]
	v_lshl_add_u64 v[154:155], v[144:145], 0, v[154:155]
	s_mov_b64 s[2:3], 0

;     __device__ __forceinline__ void operator()(const f32x4 (&acc)[2][2][4][2], const Unit& u, int wr, int wc, int fr, int fq) const {
;     ...
;                     if (u.pn < 4) { const int colg = u.pn * BM + bj * HALF + wc * 32 + 8 * fq; dst = P + (size_t)(colg >> 9) * ((size_t)T * 512) + (size_t)row * 512 + (colg & 511); }
;                     else if (u.pn < 8) { const int colc = (u.pn - 4) * BM + bj * HALF + wc * 32 + 8 * fq; dst = P + PJ_UC + (size_t)row * 1024 + colc; }
;                     else { const int which = (u.pn - 8) >> 1, hd = ((u.pn - 8) & 1) * 4 + 2 * bj + (wc >> 1), dim = 32 * (wc & 1) + 8 * fq, bb = row >> 11, ll = row & 2047;
;                         dst = P + PJ_QKV + ((size_t)(((which * 4 + bb) * 8 + hd) * SEQ + ll)) * 64 + dim; }
;                     *(u32x4*)dst = o; } }
.LBB0_448:
	global_store_dwordx4 v[154:155], v[130:133], off sc1

; __device__ __forceinline__ unsigned xb_ld(unsigned* p)              { return __hip_atomic_load(p, __ATOMIC_RELAXED, __HIP_MEMORY_SCOPE_AGENT); }
; __device__ __forceinline__ unsigned xb_add(unsigned* p, unsigned v) { return __hip_atomic_fetch_add(p, v, __ATOMIC_RELAXED, __HIP_MEMORY_SCOPE_AGENT); }
; #define XB_SPIN(cond, bar) do { unsigned _sp = 0; while (cond) { __builtin_amdgcn_s_sleep(1); \
;     if ((++_sp & 255u) == 0u) { if (xb_ld(&(bar)[XB_TMO])) break; if (_sp > XB_SPIN_CAP) { atomicAdd(&(bar)[XB_TMO], 1u); break; } } } } while (0)
; __device__ __forceinline__ void xcd_barrier(const XcdBarrier& b) {
;     ...
;         const unsigned old = xb_add(&bar[XB_XSUB(b.x)], 1u);
;         const unsigned gen = old / nloc;
;         if (old + 1u == (gen + 1u) * nloc) {
;             __builtin_amdgcn_fence(__ATOMIC_RELEASE, "agent");
;             asm volatile("s_waitcnt vmcnt(0)" ::: "memory");
;             const unsigned og = xb_add(&bar[XB_TOP], 1u);
;             const unsigned tg = og / nx;
;             if (og + 1u == (tg + 1u) * nx) xb_add(&bar[XB_TOPGEN], 1u);
;             else XB_SPIN(xb_ld(&bar[XB_TOPGEN]) == tg, bar);
;             __builtin_amdgcn_fence(__ATOMIC_ACQUIRE, "agent");
;             xb_add(&bar[XB_XGEN(b.x)], 1u);
.LBB0_485:
	s_andn2_saveexec_b64 s[2:3], s[2:3]
	s_cbranch_execz .LBB0_505
	s_mov_b64 s[2:3], exec
	s_nop 0
	s_waitcnt lgkmcnt(0)
	s_waitcnt vmcnt(0)
	v_mbcnt_lo_u32_b32 v0, s2, 0
	v_mbcnt_hi_u32_b32 v0, s3, v0
	v_cmp_eq_u32_e32 vcc, 0, v0
	s_and_saveexec_b64 s[12:13], vcc
	s_cbranch_execz .LBB0_488
	s_bcnt1_i32_b64 s2, s[2:3]
	v_mov_b32_e32 v3, s2
	v_readlane_b32 s2, v254, 45
	v_readlane_b32 s3, v254, 46
	s_nop 4
	global_atomic_add v3, v1, v3, s[2:3] sc0

; __device__ __forceinline__ unsigned cvt_pk_bf16(float lo, float hi) { unsigned r; asm volatile("v_cvt_pk_bf16_f32 %0, %1, %2" : "=v"(r) : "v"(lo), "v"(hi)); return r; }
;     __device__ __forceinline__ void operator()(const f32x4 (&acc)[2][2][4][2], const Unit& u, int wr, int wc, int fr, int fq) const {
;         const int row0 = u.pm * BM + wr * 64 + fr, col0 = (u.pn & 1) * BM + wc * 32 + 8 * fq;
;         bf16_t* base = Q + (size_t)(u.pn >> 1) * ((size_t)T * 512);
; #pragma unroll
;         for (int ai = 0; ai < 2; ++ai)
; #pragma unroll
;             for (int m = 0; m < 4; ++m) { bf16_t* rowp = base + (size_t)(row0 + ai * HALF + m * 16) * 512 + col0;
; #pragma unroll
;                 for (int bj = 0; bj < 2; ++bj) { const f32x4 v0 = acc[ai][bj][m][0], v1 = acc[ai][bj][m][1];
;                     u32x4 o; o.x = cvt_pk_bf16(v0[0], v0[1]); o.y = cvt_pk_bf16(v0[2], v0[3]); o.z = cvt_pk_bf16(v1[0], v1[1]); o.w = cvt_pk_bf16(v1[2], v1[3]);
;                     *(u32x4*)(rowp + bj * HALF) = o; } }
;     }
.LBB0_1122:
	s_lshl_b32 s2, s50, 8
	s_and_b32 s2, s2, 0x100
	v_or_b32_e32 v0, s2, v146
	s_lshl_b32 s2, s50, 22
	s_and_b32 s2, s2, 0x1800000
	v_lshl_add_u32 v148, s51, 8, v144
	s_add_u32 s2, s37, s2
	s_addc_u32 s3, s46, 0
	v_lshlrev_b32_e32 v0, 1, v0
	v_ashrrev_i32_e32 v149, 31, v148
	v_lshl_add_u64 v[150:151], s[2:3], 0, v[0:1]
	v_lshlrev_b64 v[142:143], 10, v[148:149]
	v_lshl_add_u64 v[142:143], v[150:151], 0, v[142:143]
	v_cvt_pk_bf16_f32 v126, v126, v127
	v_cvt_pk_bf16_f32 v127, v128, v129
	v_cvt_pk_bf16_f32 v128, v122, v123
	v_cvt_pk_bf16_f32 v129, v124, v125
	global_store_dwordx4 v[142:143], v[126:129], off sc1
	v_cvt_pk_bf16_f32 v114, v114, v115
	v_cvt_pk_bf16_f32 v115, v116, v117
	v_cvt_pk_bf16_f32 v116, v106, v107
	v_or_b32_e32 v106, 16, v148
	v_ashrrev_i32_e32 v107, 31, v106
	v_lshlrev_b64 v[106:107], 10, v[106:107]
	v_cvt_pk_bf16_f32 v117, v108, v109
	global_store_dwordx4 v[142:143], v[114:117], off offset:256 sc1
	s_mov_b64 s[2:3], 0x20000
	s_nop 0
	v_lshl_add_u64 v[114:115], v[150:151], 0, v[106:107]
	v_cvt_pk_bf16_f32 v106, v118, v119
	v_cvt_pk_bf16_f32 v107, v120, v121
	v_cvt_pk_bf16_f32 v108, v110, v111
	v_cvt_pk_bf16_f32 v109, v112, v113
	global_store_dwordx4 v[114:115], v[106:109], off sc1
	v_cvt_pk_bf16_f32 v98, v98, v99
	v_cvt_pk_bf16_f32 v99, v100, v101
	v_cvt_pk_bf16_f32 v100, v90, v91
	v_or_b32_e32 v90, 32, v148
	v_ashrrev_i32_e32 v91, 31, v90
	v_lshlrev_b64 v[90:91], 10, v[90:91]
	v_cvt_pk_bf16_f32 v101, v92, v93
	global_store_dwordx4 v[114:115], v[98:101], off offset:256 sc1
	s_nop 1
	v_lshl_add_u64 v[98:99], v[150:151], 0, v[90:91]
	v_cvt_pk_bf16_f32 v90, v102, v103
	v_cvt_pk_bf16_f32 v91, v104, v105
	v_cvt_pk_bf16_f32 v92, v94, v95
	v_cvt_pk_bf16_f32 v93, v96, v97
	global_store_dwordx4 v[98:99], v[90:93], off sc1
	v_cvt_pk_bf16_f32 v82, v82, v83
	v_cvt_pk_bf16_f32 v83, v84, v85
	v_cvt_pk_bf16_f32 v84, v74, v75
	v_or_b32_e32 v74, 48, v148
	v_ashrrev_i32_e32 v75, 31, v74
	v_lshlrev_b64 v[74:75], 10, v[74:75]
	v_cvt_pk_bf16_f32 v85, v76, v77
	global_store_dwordx4 v[98:99], v[82:85], off offset:256 sc1
	s_nop 1
	v_lshl_add_u64 v[82:83], v[150:151], 0, v[74:75]
	v_cvt_pk_bf16_f32 v74, v86, v87
	v_cvt_pk_bf16_f32 v75, v88, v89
	v_cvt_pk_bf16_f32 v76, v78, v79
	v_cvt_pk_bf16_f32 v77, v80, v81
	global_store_dwordx4 v[82:83], v[74:77], off sc1
	v_cvt_pk_bf16_f32 v70, v70, v71
	v_cvt_pk_bf16_f32 v71, v72, v73
	v_cvt_pk_bf16_f32 v72, v66, v67
	v_lshl_add_u64 v[66:67], v[142:143], 0, s[2:3]
	s_mov_b32 s2, 0x20000
	v_cvt_pk_bf16_f32 v73, v68, v69
	global_store_dwordx4 v[82:83], v[70:73], off offset:256 sc1
	v_cvt_pk_bf16_f32 v62, v62, v63
	v_cvt_pk_bf16_f32 v63, v64, v65
	v_cvt_pk_bf16_f32 v64, v58, v59
	v_add_co_u32_e32 v58, vcc, s2, v142
	v_cvt_pk_bf16_f32 v65, v60, v61
	s_mov_b64 s[2:3], 0x24000
	s_nop 0
	v_addc_co_u32_e32 v59, vcc, 0, v143, vcc
	global_store_dwordx4 v[58:59], v[62:65], off sc1
	v_cvt_pk_bf16_f32 v50, v50, v51
	v_cvt_pk_bf16_f32 v51, v52, v53
	v_cvt_pk_bf16_f32 v52, v42, v43
	v_cvt_pk_bf16_f32 v53, v44, v45
	global_store_dwordx4 v[66:67], v[50:53], off offset:256 sc1
	v_cvt_pk_bf16_f32 v42, v54, v55
	v_cvt_pk_bf16_f32 v43, v56, v57
	v_cvt_pk_bf16_f32 v44, v46, v47
	v_cvt_pk_bf16_f32 v45, v48, v49
	s_nop 1
	v_lshl_add_u64 v[50:51], v[142:143], 0, s[2:3]
	s_mov_b32 s2, 0x24000
	v_add_co_u32_e32 v46, vcc, s2, v142
	s_mov_b64 s[2:3], 0x28000
	s_nop 0
	v_addc_co_u32_e32 v47, vcc, 0, v143, vcc
	global_store_dwordx4 v[46:47], v[42:45], off sc1
	v_cvt_pk_bf16_f32 v34, v34, v35
	v_cvt_pk_bf16_f32 v35, v36, v37
	v_cvt_pk_bf16_f32 v36, v26, v27
	v_cvt_pk_bf16_f32 v37, v28, v29
	global_store_dwordx4 v[50:51], v[34:37], off offset:256 sc1
	v_cvt_pk_bf16_f32 v26, v38, v39
	v_cvt_pk_bf16_f32 v27, v40, v41
	v_cvt_pk_bf16_f32 v28, v30, v31
	v_cvt_pk_bf16_f32 v29, v32, v33
	s_nop 1
	v_lshl_add_u64 v[34:35], v[142:143], 0, s[2:3]
	s_mov_b32 s2, 0x28000
	v_add_co_u32_e32 v30, vcc, s2, v142
	s_mov_b64 s[2:3], 0x2c000
	s_nop 0
	v_addc_co_u32_e32 v31, vcc, 0, v143, vcc
	global_store_dwordx4 v[30:31], v[26:29], off sc1
	v_cvt_pk_bf16_f32 v18, v18, v19
	v_cvt_pk_bf16_f32 v19, v20, v21
	v_cvt_pk_bf16_f32 v20, v10, v11
	v_cvt_pk_bf16_f32 v21, v12, v13
	global_store_dwordx4 v[34:35], v[18:21], off offset:256 sc1
	v_cvt_pk_bf16_f32 v10, v22, v23
	v_cvt_pk_bf16_f32 v11, v24, v25
	v_cvt_pk_bf16_f32 v12, v14, v15
	v_cvt_pk_bf16_f32 v13, v16, v17
	s_nop 1
	v_lshl_add_u64 v[18:19], v[142:143], 0, s[2:3]
	s_mov_b32 s2, 0x2c000
	v_add_co_u32_e32 v14, vcc, s2, v142
	s_mov_b64 s[2:3], -1
	s_nop 0
	v_addc_co_u32_e32 v15, vcc, 0, v143, vcc
	s_andn2_b64 vcc, exec, s[42:43]
	global_store_dwordx4 v[14:15], v[10:13], off sc1
	v_cvt_pk_bf16_f32 v6, v6, v7
	v_cvt_pk_bf16_f32 v7, v8, v9
	v_cvt_pk_bf16_f32 v8, v2, v3
	v_cvt_pk_bf16_f32 v9, v4, v5
	global_store_dwordx4 v[18:19], v[6:9], off offset:256 sc1
	s_cbranch_vccnz .LBB0_1117
	s_andn2_b64 vcc, exec, s[34:35]
	s_cbranch_vccnz .LBB0_1116
	s_barrier
	s_branch .LBB0_1116

; __device__ __forceinline__ unsigned cvt_pk_bf16(float lo, float hi) { unsigned r; asm volatile("v_cvt_pk_bf16_f32 %0, %1, %2" : "=v"(r) : "v"(lo), "v"(hi)); return r; }
;     __device__ __forceinline__ void operator()(const f32x4 (&acc)[2][2][4][2], const Unit& u, int wr, int wc, int fr, int fq) const {
;     ...
; #pragma unroll
;         for (int ai = 0; ai < 2; ++ai)
; #pragma unroll
;             for (int m = 0; m < 4; ++m) { const int row = row0 + ai * HALF + m * 16; bf16_t* rowp = O + (size_t)row * ldc + col0;
;                 const float rs = rsv[ai][m];
; #pragma unroll
;                 for (int bj = 0; bj < 2; ++bj) { f32x4 v0 = acc[ai][bj][m][0] * rs, v1 = acc[ai][bj][m][1] * rs;
;                     if (ACT == 1) {
; #pragma unroll
;                         for (int e = 0; e < 4; ++e) { float a = fmaxf(v0[e], 0.f), b = fmaxf(v1[e], 0.f); v0[e] = a * a; v1[e] = b * b; } }
;                     u32x4 o; o.x = cvt_pk_bf16(v0[0], v0[1]); o.y = cvt_pk_bf16(v0[2], v0[3]); o.z = cvt_pk_bf16(v1[0], v1[1]); o.w = cvt_pk_bf16(v1[2], v1[3]);
;                     *(u32x4*)(rowp + bj * HALF) = o; } }
.LBB0_1347:
	v_max_f32_e32 v122, v122, v122
	v_lshl_add_u32 v140, s48, 8, v142
	v_max_f32_e32 v122, 0, v122
	v_max_f32_e32 v123, v123, v123
	v_max_f32_e32 v124, v124, v124
	v_ashrrev_i32_e32 v141, 31, v140
	v_lshl_or_b32 v152, s56, 8, v144
	v_mul_f32_e32 v154, v122, v122
	v_max_f32_e32 v122, v127, v127
	v_max_f32_e32 v123, 0, v123
	v_max_f32_e32 v124, 0, v124
	v_or_b32_e32 v146, 16, v140
	v_or_b32_e32 v148, 32, v140
	v_or_b32_e32 v150, 48, v140
	v_ashrrev_i32_e32 v153, 31, v152
	v_lshlrev_b64 v[140:141], 14, v[140:141]
	v_max_f32_e32 v126, v126, v126
	v_max_f32_e32 v122, 0, v122
	v_mul_f32_e32 v127, v123, v123
	v_max_f32_e32 v123, v128, v128
	v_mul_f32_e32 v128, v124, v124
	v_max_f32_e32 v124, v129, v129
	v_max_f32_e32 v125, v125, v125
	v_lshl_add_u64 v[140:141], s[12:13], 0, v[140:141]
	v_lshlrev_b64 v[152:153], 1, v[152:153]
	v_max_f32_e32 v126, 0, v126
	v_mul_f32_e32 v122, v122, v122
	v_max_f32_e32 v123, 0, v123
	v_max_f32_e32 v124, 0, v124
	v_max_f32_e32 v125, 0, v125
	v_max_f32_e32 v114, v114, v114
	v_max_f32_e32 v115, v115, v115
	v_max_f32_e32 v116, v116, v116
	v_lshl_add_u64 v[140:141], v[140:141], 0, v[152:153]
	v_mul_f32_e32 v126, v126, v126
	v_mul_f32_e32 v123, v123, v123
	v_mul_f32_e32 v124, v124, v124
	v_mul_f32_e32 v125, v125, v125
	v_cvt_pk_bf16_f32 v122, v126, v122
	v_max_f32_e32 v114, 0, v114
	v_max_f32_e32 v115, 0, v115
	v_max_f32_e32 v116, 0, v116
	v_cvt_pk_bf16_f32 v123, v123, v124
	v_cvt_pk_bf16_f32 v124, v154, v127
	v_cvt_pk_bf16_f32 v125, v128, v125
	global_store_dwordx4 v[140:141], v[122:125], off sc1
	v_max_f32_e32 v118, v118, v118
	v_max_f32_e32 v117, v117, v117
	v_mul_f32_e32 v122, v114, v114
	v_max_f32_e32 v114, v119, v119
	v_mul_f32_e32 v119, v115, v115
	v_max_f32_e32 v115, v120, v120
	v_mul_f32_e32 v120, v116, v116
	v_max_f32_e32 v116, v121, v121
	v_max_f32_e32 v114, 0, v114
	v_max_f32_e32 v115, 0, v115
	v_max_f32_e32 v116, 0, v116
	v_max_f32_e32 v118, 0, v118
	v_mul_f32_e32 v114, v114, v114
	v_mul_f32_e32 v115, v115, v115
	v_max_f32_e32 v117, 0, v117
	v_mul_f32_e32 v116, v116, v116
	v_max_f32_e32 v106, v106, v106
	v_mul_f32_e32 v118, v118, v118
	v_mul_f32_e32 v117, v117, v117
	v_cvt_pk_bf16_f32 v114, v118, v114
	v_cvt_pk_bf16_f32 v115, v115, v116
	v_cvt_pk_bf16_f32 v116, v122, v119
	v_max_f32_e32 v106, 0, v106
	v_max_f32_e32 v107, v107, v107
	v_max_f32_e32 v108, v108, v108
	v_ashrrev_i32_e32 v147, 31, v146
	v_cvt_pk_bf16_f32 v117, v120, v117
	global_store_dwordx4 v[140:141], v[114:117], off offset:256 sc1
	v_max_f32_e32 v107, 0, v107
	v_max_f32_e32 v108, 0, v108
	v_mul_f32_e32 v116, v106, v106
	v_max_f32_e32 v106, v111, v111
	v_lshlrev_b64 v[114:115], 14, v[146:147]
	v_max_f32_e32 v110, v110, v110
	v_max_f32_e32 v106, 0, v106
	v_mul_f32_e32 v111, v107, v107
	v_max_f32_e32 v107, v112, v112
	v_mul_f32_e32 v112, v108, v108
	v_max_f32_e32 v108, v113, v113
	v_max_f32_e32 v109, v109, v109
	v_lshl_add_u64 v[114:115], s[12:13], 0, v[114:115]
	v_max_f32_e32 v110, 0, v110
	v_mul_f32_e32 v106, v106, v106
	v_max_f32_e32 v107, 0, v107
	v_max_f32_e32 v108, 0, v108
	v_max_f32_e32 v109, 0, v109
	v_max_f32_e32 v98, v98, v98
	v_max_f32_e32 v99, v99, v99
	v_max_f32_e32 v100, v100, v100
	v_lshl_add_u64 v[114:115], v[114:115], 0, v[152:153]
	v_mul_f32_e32 v110, v110, v110
	v_mul_f32_e32 v107, v107, v107
	v_mul_f32_e32 v108, v108, v108
	v_mul_f32_e32 v109, v109, v109
	v_cvt_pk_bf16_f32 v106, v110, v106
	v_max_f32_e32 v98, 0, v98
	v_max_f32_e32 v99, 0, v99
	v_max_f32_e32 v100, 0, v100
	v_cvt_pk_bf16_f32 v107, v107, v108
	v_cvt_pk_bf16_f32 v108, v116, v111
	v_cvt_pk_bf16_f32 v109, v112, v109
	global_store_dwordx4 v[114:115], v[106:109], off sc1
	v_max_f32_e32 v102, v102, v102
	v_max_f32_e32 v101, v101, v101
	v_mul_f32_e32 v106, v98, v98
	v_max_f32_e32 v98, v103, v103
	v_mul_f32_e32 v103, v99, v99
	v_max_f32_e32 v99, v104, v104
	v_mul_f32_e32 v104, v100, v100
	v_max_f32_e32 v100, v105, v105
	v_max_f32_e32 v98, 0, v98
	v_max_f32_e32 v99, 0, v99
	v_max_f32_e32 v100, 0, v100
	v_max_f32_e32 v102, 0, v102
	v_mul_f32_e32 v98, v98, v98
	v_mul_f32_e32 v99, v99, v99
	v_max_f32_e32 v101, 0, v101
	v_mul_f32_e32 v100, v100, v100
	v_max_f32_e32 v90, v90, v90
	v_mul_f32_e32 v102, v102, v102
	v_mul_f32_e32 v101, v101, v101
	v_cvt_pk_bf16_f32 v98, v102, v98
	v_cvt_pk_bf16_f32 v99, v99, v100
	v_cvt_pk_bf16_f32 v100, v106, v103
	v_max_f32_e32 v90, 0, v90
	v_max_f32_e32 v91, v91, v91
	v_max_f32_e32 v92, v92, v92
	v_ashrrev_i32_e32 v149, 31, v148
	v_cvt_pk_bf16_f32 v101, v104, v101
	global_store_dwordx4 v[114:115], v[98:101], off offset:256 sc1
	v_max_f32_e32 v91, 0, v91
	v_max_f32_e32 v92, 0, v92
	v_mul_f32_e32 v100, v90, v90
	v_max_f32_e32 v90, v95, v95
	v_lshlrev_b64 v[98:99], 14, v[148:149]
	v_max_f32_e32 v94, v94, v94
	v_max_f32_e32 v90, 0, v90
	v_mul_f32_e32 v95, v91, v91
	v_max_f32_e32 v91, v96, v96
	v_mul_f32_e32 v96, v92, v92
	v_max_f32_e32 v92, v97, v97
	v_max_f32_e32 v93, v93, v93
	v_lshl_add_u64 v[98:99], s[12:13], 0, v[98:99]
	v_max_f32_e32 v94, 0, v94
	v_mul_f32_e32 v90, v90, v90
	v_max_f32_e32 v91, 0, v91
	v_max_f32_e32 v92, 0, v92
	v_max_f32_e32 v93, 0, v93
	v_max_f32_e32 v82, v82, v82
	v_max_f32_e32 v83, v83, v83
	v_max_f32_e32 v84, v84, v84
	v_lshl_add_u64 v[98:99], v[98:99], 0, v[152:153]
	v_mul_f32_e32 v94, v94, v94
	v_mul_f32_e32 v91, v91, v91
	v_mul_f32_e32 v92, v92, v92
	v_mul_f32_e32 v93, v93, v93
	v_cvt_pk_bf16_f32 v90, v94, v90
	v_max_f32_e32 v82, 0, v82
	v_max_f32_e32 v83, 0, v83
	v_max_f32_e32 v84, 0, v84
	v_cvt_pk_bf16_f32 v91, v91, v92
	v_cvt_pk_bf16_f32 v92, v100, v95
	v_cvt_pk_bf16_f32 v93, v96, v93
	global_store_dwordx4 v[98:99], v[90:93], off sc1
	v_max_f32_e32 v86, v86, v86
	v_max_f32_e32 v85, v85, v85
; __device__ __forceinline__ unsigned cvt_pk_bf16(float lo, float hi) { unsigned r; asm volatile("v_cvt_pk_bf16_f32 %0, %1, %2" : "=v"(r) : "v"(lo), "v"(hi)); return r; }
;     __device__ __forceinline__ void operator()(const f32x4 (&acc)[2][2][4][2], const Unit& u, int wr, int wc, int fr, int fq) const {
;     ...
; #pragma unroll
;         for (int ai = 0; ai < 2; ++ai)
; #pragma unroll
;             for (int m = 0; m < 4; ++m) { const int row = row0 + ai * HALF + m * 16; bf16_t* rowp = O + (size_t)row * ldc + col0;
;                 const float rs = rsv[ai][m];
; #pragma unroll
;                 for (int bj = 0; bj < 2; ++bj) { f32x4 v0 = acc[ai][bj][m][0] * rs, v1 = acc[ai][bj][m][1] * rs;
;                     if (ACT == 1) {
; #pragma unroll
;                         for (int e = 0; e < 4; ++e) { float a = fmaxf(v0[e], 0.f), b = fmaxf(v1[e], 0.f); v0[e] = a * a; v1[e] = b * b; } }
;                     u32x4 o; o.x = cvt_pk_bf16(v0[0], v0[1]); o.y = cvt_pk_bf16(v0[2], v0[3]); o.z = cvt_pk_bf16(v1[0], v1[1]); o.w = cvt_pk_bf16(v1[2], v1[3]);
;                     *(u32x4*)(rowp + bj * HALF) = o; } }
	v_mul_f32_e32 v90, v82, v82
	v_max_f32_e32 v82, v87, v87
	v_mul_f32_e32 v87, v83, v83
	v_max_f32_e32 v83, v88, v88
	v_mul_f32_e32 v88, v84, v84
	v_max_f32_e32 v84, v89, v89
	v_max_f32_e32 v82, 0, v82
	v_max_f32_e32 v83, 0, v83
	v_max_f32_e32 v84, 0, v84
	v_max_f32_e32 v86, 0, v86
	v_mul_f32_e32 v82, v82, v82
	v_mul_f32_e32 v83, v83, v83
	v_max_f32_e32 v85, 0, v85
	v_mul_f32_e32 v84, v84, v84
	v_max_f32_e32 v74, v74, v74
	v_mul_f32_e32 v86, v86, v86
	v_mul_f32_e32 v85, v85, v85
	v_cvt_pk_bf16_f32 v82, v86, v82
	v_cvt_pk_bf16_f32 v83, v83, v84
	v_cvt_pk_bf16_f32 v84, v90, v87
	v_max_f32_e32 v74, 0, v74
	v_max_f32_e32 v75, v75, v75
	v_max_f32_e32 v76, v76, v76
	v_ashrrev_i32_e32 v151, 31, v150
	v_cvt_pk_bf16_f32 v85, v88, v85
	global_store_dwordx4 v[98:99], v[82:85], off offset:256 sc1
	v_max_f32_e32 v75, 0, v75
	v_max_f32_e32 v76, 0, v76
	v_mul_f32_e32 v84, v74, v74
	v_max_f32_e32 v74, v79, v79
	v_lshlrev_b64 v[82:83], 14, v[150:151]
	v_max_f32_e32 v78, v78, v78
	v_max_f32_e32 v74, 0, v74
	v_mul_f32_e32 v79, v75, v75
	v_max_f32_e32 v75, v80, v80
	v_mul_f32_e32 v80, v76, v76
	v_max_f32_e32 v76, v81, v81
	v_max_f32_e32 v77, v77, v77
	v_lshl_add_u64 v[82:83], s[12:13], 0, v[82:83]
	v_max_f32_e32 v78, 0, v78
	v_mul_f32_e32 v74, v74, v74
	v_max_f32_e32 v75, 0, v75
	v_max_f32_e32 v76, 0, v76
	v_max_f32_e32 v77, 0, v77
	v_max_f32_e32 v66, v66, v66
	v_max_f32_e32 v67, v67, v67
	v_max_f32_e32 v68, v68, v68
	v_lshl_add_u64 v[82:83], v[82:83], 0, v[152:153]
	v_mul_f32_e32 v78, v78, v78
	v_mul_f32_e32 v75, v75, v75
	v_mul_f32_e32 v76, v76, v76
	v_mul_f32_e32 v77, v77, v77
	v_cvt_pk_bf16_f32 v74, v78, v74
	v_max_f32_e32 v66, 0, v66
	v_max_f32_e32 v67, 0, v67
	v_max_f32_e32 v68, 0, v68
	v_cvt_pk_bf16_f32 v75, v75, v76
	v_cvt_pk_bf16_f32 v76, v84, v79
	v_cvt_pk_bf16_f32 v77, v80, v77
	global_store_dwordx4 v[82:83], v[74:77], off sc1
	v_max_f32_e32 v70, v70, v70
	v_max_f32_e32 v69, v69, v69
	v_mul_f32_e32 v74, v66, v66
	v_max_f32_e32 v66, v71, v71
	v_mul_f32_e32 v71, v67, v67
	v_max_f32_e32 v67, v72, v72
	v_mul_f32_e32 v72, v68, v68
	v_max_f32_e32 v68, v73, v73
	v_max_f32_e32 v66, 0, v66
	v_max_f32_e32 v67, 0, v67
	v_max_f32_e32 v68, 0, v68
	v_max_f32_e32 v70, 0, v70
	v_mul_f32_e32 v66, v66, v66
	v_mul_f32_e32 v67, v67, v67
	v_max_f32_e32 v69, 0, v69
	v_mul_f32_e32 v68, v68, v68
	v_max_f32_e32 v58, v58, v58
	v_mul_f32_e32 v70, v70, v70
	v_mul_f32_e32 v69, v69, v69
	v_cvt_pk_bf16_f32 v66, v70, v66
	v_cvt_pk_bf16_f32 v67, v67, v68
	v_cvt_pk_bf16_f32 v68, v74, v71
	v_max_f32_e32 v58, 0, v58
	v_max_f32_e32 v59, v59, v59
	v_max_f32_e32 v60, v60, v60
	v_cvt_pk_bf16_f32 v69, v72, v69
	global_store_dwordx4 v[82:83], v[66:69], off offset:256 sc1
	v_max_f32_e32 v62, v62, v62
	v_max_f32_e32 v59, 0, v59
	v_mul_f32_e32 v68, v58, v58
	v_max_f32_e32 v58, v63, v63
	v_max_f32_e32 v60, 0, v60
	s_mov_b64 s[2:3], 0x200000
	v_max_f32_e32 v62, 0, v62
	v_max_f32_e32 v58, 0, v58
	v_mul_f32_e32 v63, v59, v59
	v_max_f32_e32 v59, v64, v64
	v_mul_f32_e32 v64, v60, v60
	v_max_f32_e32 v60, v65, v65
	v_lshl_add_u64 v[66:67], v[140:141], 0, s[2:3]
	v_mul_f32_e32 v62, v62, v62
	v_mul_f32_e32 v58, v58, v58
	v_max_f32_e32 v59, 0, v59
	v_max_f32_e32 v60, 0, v60
	v_max_f32_e32 v61, v61, v61
	s_mov_b32 s2, 0x200000
	v_mul_f32_e32 v59, v59, v59
	v_max_f32_e32 v61, 0, v61
	v_mul_f32_e32 v60, v60, v60
	v_cvt_pk_bf16_f32 v58, v62, v58
	v_add_co_u32_e32 v62, vcc, s2, v140
	v_max_f32_e32 v50, v50, v50
	v_max_f32_e32 v51, v51, v51
	v_max_f32_e32 v52, v52, v52
	v_mul_f32_e32 v61, v61, v61
	v_cvt_pk_bf16_f32 v59, v59, v60
	v_cvt_pk_bf16_f32 v60, v68, v63
	v_addc_co_u32_e32 v63, vcc, 0, v141, vcc
	v_max_f32_e32 v50, 0, v50
	v_max_f32_e32 v51, 0, v51
	v_max_f32_e32 v52, 0, v52
	v_cvt_pk_bf16_f32 v61, v64, v61
	global_store_dwordx4 v[62:63], v[58:61], off sc1
	v_max_f32_e32 v54, v54, v54
	v_max_f32_e32 v53, v53, v53
	v_mul_f32_e32 v58, v50, v50
	v_max_f32_e32 v50, v55, v55
	v_mul_f32_e32 v55, v51, v51
	v_max_f32_e32 v51, v56, v56
	v_mul_f32_e32 v56, v52, v52
	v_max_f32_e32 v52, v57, v57
	v_max_f32_e32 v50, 0, v50
	v_max_f32_e32 v51, 0, v51
	v_max_f32_e32 v52, 0, v52
	v_max_f32_e32 v54, 0, v54
	v_mul_f32_e32 v50, v50, v50
	v_mul_f32_e32 v51, v51, v51
	v_max_f32_e32 v53, 0, v53
	v_mul_f32_e32 v52, v52, v52
	v_max_f32_e32 v42, v42, v42
	v_mul_f32_e32 v54, v54, v54
	v_mul_f32_e32 v53, v53, v53
	v_cvt_pk_bf16_f32 v50, v54, v50
	v_cvt_pk_bf16_f32 v51, v51, v52
	v_cvt_pk_bf16_f32 v52, v58, v55
	v_max_f32_e32 v42, 0, v42
	v_max_f32_e32 v43, v43, v43
	v_max_f32_e32 v44, v44, v44
	v_cvt_pk_bf16_f32 v53, v56, v53
	global_store_dwordx4 v[66:67], v[50:53], off offset:256 sc1
	v_max_f32_e32 v46, v46, v46
	v_max_f32_e32 v43, 0, v43
	v_mul_f32_e32 v52, v42, v42
	v_max_f32_e32 v42, v47, v47
	v_max_f32_e32 v44, 0, v44
	s_mov_b64 s[2:3], 0x240000
	v_max_f32_e32 v46, 0, v46
	v_max_f32_e32 v42, 0, v42
	v_mul_f32_e32 v47, v43, v43
	v_max_f32_e32 v43, v48, v48
	v_mul_f32_e32 v48, v44, v44
	v_max_f32_e32 v44, v49, v49
	v_lshl_add_u64 v[50:51], v[140:141], 0, s[2:3]
	v_mul_f32_e32 v46, v46, v46
	v_mul_f32_e32 v42, v42, v42
	v_max_f32_e32 v43, 0, v43
	v_max_f32_e32 v44, 0, v44
	v_max_f32_e32 v45, v45, v45
	s_mov_b32 s2, 0x240000
	v_mul_f32_e32 v43, v43, v43
; __device__ __forceinline__ unsigned cvt_pk_bf16(float lo, float hi) { unsigned r; asm volatile("v_cvt_pk_bf16_f32 %0, %1, %2" : "=v"(r) : "v"(lo), "v"(hi)); return r; }
;     __device__ __forceinline__ void operator()(const f32x4 (&acc)[2][2][4][2], const Unit& u, int wr, int wc, int fr, int fq) const {
;     ...
; #pragma unroll
;         for (int ai = 0; ai < 2; ++ai)
; #pragma unroll
;             for (int m = 0; m < 4; ++m) { const int row = row0 + ai * HALF + m * 16; bf16_t* rowp = O + (size_t)row * ldc + col0;
;                 const float rs = rsv[ai][m];
; #pragma unroll
;                 for (int bj = 0; bj < 2; ++bj) { f32x4 v0 = acc[ai][bj][m][0] * rs, v1 = acc[ai][bj][m][1] * rs;
;                     if (ACT == 1) {
; #pragma unroll
;                         for (int e = 0; e < 4; ++e) { float a = fmaxf(v0[e], 0.f), b = fmaxf(v1[e], 0.f); v0[e] = a * a; v1[e] = b * b; } }
;                     u32x4 o; o.x = cvt_pk_bf16(v0[0], v0[1]); o.y = cvt_pk_bf16(v0[2], v0[3]); o.z = cvt_pk_bf16(v1[0], v1[1]); o.w = cvt_pk_bf16(v1[2], v1[3]);
;                     *(u32x4*)(rowp + bj * HALF) = o; } }
	v_max_f32_e32 v45, 0, v45
	v_mul_f32_e32 v44, v44, v44
	v_cvt_pk_bf16_f32 v42, v46, v42
	v_add_co_u32_e32 v46, vcc, s2, v140
	v_max_f32_e32 v34, v34, v34
	v_max_f32_e32 v35, v35, v35
	v_max_f32_e32 v36, v36, v36
	v_mul_f32_e32 v45, v45, v45
	v_cvt_pk_bf16_f32 v43, v43, v44
	v_cvt_pk_bf16_f32 v44, v52, v47
	v_addc_co_u32_e32 v47, vcc, 0, v141, vcc
	v_max_f32_e32 v34, 0, v34
	v_max_f32_e32 v35, 0, v35
	v_max_f32_e32 v36, 0, v36
	v_cvt_pk_bf16_f32 v45, v48, v45
	global_store_dwordx4 v[46:47], v[42:45], off sc1
	v_max_f32_e32 v38, v38, v38
	v_max_f32_e32 v37, v37, v37
	v_mul_f32_e32 v42, v34, v34
	v_max_f32_e32 v34, v39, v39
	v_mul_f32_e32 v39, v35, v35
	v_max_f32_e32 v35, v40, v40
	v_mul_f32_e32 v40, v36, v36
	v_max_f32_e32 v36, v41, v41
	v_max_f32_e32 v34, 0, v34
	v_max_f32_e32 v35, 0, v35
	v_max_f32_e32 v36, 0, v36
	v_max_f32_e32 v38, 0, v38
	v_mul_f32_e32 v34, v34, v34
	v_mul_f32_e32 v35, v35, v35
	v_max_f32_e32 v37, 0, v37
	v_mul_f32_e32 v36, v36, v36
	v_max_f32_e32 v26, v26, v26
	v_mul_f32_e32 v38, v38, v38
	v_mul_f32_e32 v37, v37, v37
	v_cvt_pk_bf16_f32 v34, v38, v34
	v_cvt_pk_bf16_f32 v35, v35, v36
	v_cvt_pk_bf16_f32 v36, v42, v39
	v_max_f32_e32 v26, 0, v26
	v_max_f32_e32 v27, v27, v27
	v_max_f32_e32 v28, v28, v28
	v_cvt_pk_bf16_f32 v37, v40, v37
	global_store_dwordx4 v[50:51], v[34:37], off offset:256 sc1
	v_max_f32_e32 v30, v30, v30
	v_max_f32_e32 v27, 0, v27
	v_mul_f32_e32 v36, v26, v26
	v_max_f32_e32 v26, v31, v31
	v_max_f32_e32 v28, 0, v28
	s_mov_b64 s[2:3], 0x280000
	v_max_f32_e32 v30, 0, v30
	v_max_f32_e32 v26, 0, v26
	v_mul_f32_e32 v31, v27, v27
	v_max_f32_e32 v27, v32, v32
	v_mul_f32_e32 v32, v28, v28
	v_max_f32_e32 v28, v33, v33
	v_lshl_add_u64 v[34:35], v[140:141], 0, s[2:3]
	v_mul_f32_e32 v30, v30, v30
	v_mul_f32_e32 v26, v26, v26
	v_max_f32_e32 v27, 0, v27
	v_max_f32_e32 v28, 0, v28
	v_max_f32_e32 v29, v29, v29
	s_mov_b32 s2, 0x280000
	v_mul_f32_e32 v27, v27, v27
	v_max_f32_e32 v29, 0, v29
	v_mul_f32_e32 v28, v28, v28
	v_cvt_pk_bf16_f32 v26, v30, v26
	v_add_co_u32_e32 v30, vcc, s2, v140
	v_max_f32_e32 v18, v18, v18
	v_max_f32_e32 v19, v19, v19
	v_max_f32_e32 v20, v20, v20
	v_mul_f32_e32 v29, v29, v29
	v_cvt_pk_bf16_f32 v27, v27, v28
	v_cvt_pk_bf16_f32 v28, v36, v31
	v_addc_co_u32_e32 v31, vcc, 0, v141, vcc
	v_max_f32_e32 v18, 0, v18
	v_max_f32_e32 v19, 0, v19
	v_max_f32_e32 v20, 0, v20
	v_cvt_pk_bf16_f32 v29, v32, v29
	global_store_dwordx4 v[30:31], v[26:29], off sc1
	v_max_f32_e32 v22, v22, v22
	v_max_f32_e32 v21, v21, v21
	v_mul_f32_e32 v26, v18, v18
	v_max_f32_e32 v18, v23, v23
	v_mul_f32_e32 v23, v19, v19
	v_max_f32_e32 v19, v24, v24
	v_mul_f32_e32 v24, v20, v20
	v_max_f32_e32 v20, v25, v25
	v_max_f32_e32 v18, 0, v18
	v_max_f32_e32 v19, 0, v19
	v_max_f32_e32 v20, 0, v20
	v_max_f32_e32 v22, 0, v22
	v_mul_f32_e32 v18, v18, v18
	v_mul_f32_e32 v19, v19, v19
	v_max_f32_e32 v21, 0, v21
	v_mul_f32_e32 v20, v20, v20
	v_max_f32_e32 v10, v10, v10
	v_mul_f32_e32 v22, v22, v22
	v_mul_f32_e32 v21, v21, v21
	v_cvt_pk_bf16_f32 v18, v22, v18
	v_cvt_pk_bf16_f32 v19, v19, v20
	v_cvt_pk_bf16_f32 v20, v26, v23
	v_max_f32_e32 v10, 0, v10
	v_max_f32_e32 v11, v11, v11
	v_max_f32_e32 v12, v12, v12
	v_cvt_pk_bf16_f32 v21, v24, v21
	global_store_dwordx4 v[34:35], v[18:21], off offset:256 sc1
	v_max_f32_e32 v14, v14, v14
	v_max_f32_e32 v11, 0, v11
	v_mul_f32_e32 v20, v10, v10
	v_max_f32_e32 v10, v15, v15
	v_max_f32_e32 v12, 0, v12
	s_mov_b64 s[2:3], 0x2c0000
	v_max_f32_e32 v14, 0, v14
	v_max_f32_e32 v10, 0, v10
	v_mul_f32_e32 v15, v11, v11
	v_max_f32_e32 v11, v16, v16
	v_mul_f32_e32 v16, v12, v12
	v_max_f32_e32 v12, v17, v17
	v_lshl_add_u64 v[18:19], v[140:141], 0, s[2:3]
	v_mul_f32_e32 v14, v14, v14
	v_mul_f32_e32 v10, v10, v10
	v_max_f32_e32 v11, 0, v11
	v_max_f32_e32 v12, 0, v12
	v_max_f32_e32 v13, v13, v13
	s_mov_b32 s2, 0x2c0000
	v_mul_f32_e32 v11, v11, v11
	v_max_f32_e32 v13, 0, v13
	v_mul_f32_e32 v12, v12, v12
	v_cvt_pk_bf16_f32 v10, v14, v10
	v_add_co_u32_e32 v14, vcc, s2, v140
	v_max_f32_e32 v2, v2, v2
	v_max_f32_e32 v3, v3, v3
	v_max_f32_e32 v4, v4, v4
	v_mul_f32_e32 v13, v13, v13
	v_cvt_pk_bf16_f32 v11, v11, v12
	v_cvt_pk_bf16_f32 v12, v20, v15
	v_addc_co_u32_e32 v15, vcc, 0, v141, vcc
	v_max_f32_e32 v2, 0, v2
	v_max_f32_e32 v3, 0, v3
	v_max_f32_e32 v4, 0, v4
	v_cvt_pk_bf16_f32 v13, v16, v13
	global_store_dwordx4 v[14:15], v[10:13], off sc1
	v_max_f32_e32 v5, v5, v5
	v_max_f32_e32 v6, v6, v6
	v_mul_f32_e32 v10, v2, v2
	v_max_f32_e32 v2, v7, v7
	v_mul_f32_e32 v7, v3, v3
	v_max_f32_e32 v3, v8, v8
	v_mul_f32_e32 v8, v4, v4
	v_max_f32_e32 v4, v9, v9
	v_max_f32_e32 v2, 0, v2
	v_max_f32_e32 v3, 0, v3
	v_max_f32_e32 v4, 0, v4
	v_max_f32_e32 v5, 0, v5
	v_max_f32_e32 v6, 0, v6
	v_mul_f32_e32 v2, v2, v2
	v_mul_f32_e32 v3, v3, v3
	v_mul_f32_e32 v4, v4, v4
	v_mul_f32_e32 v5, v5, v5
	s_andn2_b64 vcc, exec, s[38:39]
	s_mov_b64 s[2:3], -1
	v_mul_f32_e32 v6, v6, v6
	v_cvt_pk_bf16_f32 v2, v6, v2
	v_cvt_pk_bf16_f32 v3, v3, v4
	v_cvt_pk_bf16_f32 v4, v10, v7
	v_cvt_pk_bf16_f32 v5, v8, v5
	global_store_dwordx4 v[18:19], v[2:5], off offset:256 sc1
	s_cbranch_vccnz .LBB0_1336
	s_andn2_b64 vcc, exec, s[8:9]
	s_cbranch_vccnz .LBB0_1335
	s_barrier
	s_branch .LBB0_1335
